# adds: gain vectors preloaded once per norm phase (loop-invariant loads hoisted, in-loop vmcnt(0) chain removed), pool-GEMM L3 epilogue loads hoisted, counted lgkmcnt in MLA QK chains
# speedup vs baseline: 1.0352x; 1.0013x over previous
; DI float bflo(unsigned w) { return __uint_as_float(w << 16); }
; DI float bfhi(unsigned w) { return __uint_as_float(w & 0xffff0000u); }
; DI int opaque_tid() { int t = threadIdx.x; asm volatile("" : "+v"(t)); return t; }
; template <bool BF> DI void norm_phase(const Params& p, const void* x, const float* gain) {
;     ...
;     bf16_t* H = (bf16_t*)(ws + OFF_H);
;     const int tid = opaque_tid(), wid = tid >> 6, lane = tid & 63;
;     const int step = gridDim.x * 8;
;     for (int t = bid * 8 + wid; t < T; t += 2 * step) {
;         const int t2 = (t + step < T) ? t + step : t;
;         f32x4 v[2][8];
; #pragma unroll
;         for (int q = 0; q < 2; ++q) {
;             const int tt = q ? t2 : t;
; #pragma unroll
;             for (int i = 0; i < 4; ++i) {
;                 const size_t e = (size_t)tt * D + (i * 64 + lane) * 8;
;                 if constexpr (BF) { const u32x4 w = *(const u32x4*)((const bf16_t*)x + e);
;                     v[q][2 * i] = (f32x4){bflo(w[0]), bfhi(w[0]), bflo(w[1]), bfhi(w[1])}; v[q][2 * i + 1] = (f32x4){bflo(w[2]), bfhi(w[2]), bflo(w[3]), bfhi(w[3])}; }
;                 else { v[q][2 * i] = *(const f32x4*)((const float*)x + e); v[q][2 * i + 1] = *(const f32x4*)((const float*)x + e + 4); }
;             }
;         }
;         float ss[2] = {0.f, 0.f};
; #pragma unroll
;         for (int q = 0; q < 2; ++q)
; #pragma unroll
;             for (int i = 0; i < 8; ++i) ss[q] += v[q][i][0] * v[q][i][0] + v[q][i][1] * v[q][i][1] + v[q][i][2] * v[q][i][2] + v[q][i][3] * v[q][i][3];
;     ...
;             for (int i = 0; i < 4; ++i) { const int c = (i * 64 + lane) * 8;
;                 const f32x4 g0 = *(const f32x4*)(gain + c), g1 = *(const f32x4*)(gain + c + 4);
.LBB1_305:
	s_or_b64 exec, exec, s[6:7]
	s_waitcnt lgkmcnt(0)
	s_barrier
	s_load_dwordx2 s[10:11], s[0:1], 0x88
	s_mov_b32 s2, s61
	s_waitcnt vmcnt(0)
	v_mov_b32_e32 v0, v197
	s_lshl_b32 s33, s50, 3
	s_waitcnt lgkmcnt(0)
	s_mov_b32 s9, s11
	s_mov_b32 s8, s10
	s_nop 0
	v_ashrrev_i32_e32 v1, 6, v0
	v_lshl_add_u32 v12, s2, 3, v1
	s_movk_i32 s2, 0x4000
	v_cmp_gt_i32_e32 vcc, s2, v12
	s_and_saveexec_b64 s[6:7], vcc
	s_cbranch_execz .LBB1_308
	v_lshlrev_b32_e32 v0, 3, v0
	v_and_b32_e32 v6, 0x1f8, v0
	v_mbcnt_hi_u32_b32 v0, -1, v228
	v_and_b32_e32 v1, 64, v0
	v_add_u32_e32 v1, 64, v1
	v_xor_b32_e32 v2, 32, v0
	v_cmp_lt_i32_e32 vcc, v2, v1
	s_load_dwordx2 s[4:5], s[0:1], 0x18
	v_lshlrev_b32_e32 v8, 2, v6
	v_cndmask_b32_e32 v2, v0, v2, vcc
	v_lshlrev_b32_e32 v11, 2, v2
	v_xor_b32_e32 v2, 16, v0
	v_cmp_lt_i32_e32 vcc, v2, v1
	v_mov_b32_e32 v9, 0
	v_mov_b32_e32 v3, v9
	v_cndmask_b32_e32 v2, v0, v2, vcc
	v_lshlrev_b32_e32 v80, 2, v2
	v_xor_b32_e32 v2, 8, v0
	v_cmp_lt_i32_e32 vcc, v2, v1
	v_mov_b32_e32 v10, 0x358637bd
	s_mov_b32 s3, 0x800000
	v_cndmask_b32_e32 v2, v0, v2, vcc
	v_lshlrev_b32_e32 v81, 2, v2
	v_xor_b32_e32 v2, 4, v0
	v_cmp_lt_i32_e32 vcc, v2, v1
	s_nop 1
	v_cndmask_b32_e32 v2, v0, v2, vcc
	v_lshlrev_b32_e32 v82, 2, v2
	v_xor_b32_e32 v2, 2, v0
	v_cmp_lt_i32_e32 vcc, v2, v1
	s_nop 1
	v_cndmask_b32_e32 v2, v0, v2, vcc
	v_lshlrev_b32_e32 v83, 2, v2
	v_xor_b32_e32 v2, 1, v0
	v_cmp_lt_i32_e32 vcc, v2, v1
	s_nop 1
	v_cndmask_b32_e32 v0, v0, v2, vcc
	v_lshlrev_b32_e32 v84, 2, v0
	s_waitcnt lgkmcnt(0)
	v_lshl_add_u64 v[0:1], s[4:5], 0, v[8:9]
	v_or_b32_e32 v2, 0x1000, v8
	v_or_b32_e32 v8, 0x1800, v8
	v_lshl_add_u64 v[4:5], s[4:5], 0, v[8:9]
	v_lshlrev_b32_e32 v8, 1, v6
	v_lshl_add_u64 v[2:3], s[4:5], 0, v[2:3]
	v_lshl_add_u64 v[6:7], s[8:9], 0, v[8:9]
	s_mov_b64 s[4:5], 0x4c614000
	v_lshl_add_u64 v[6:7], v[6:7], 0, s[4:5]
	v_lshl_add_u64 v[8:9], s[10:11], 0, v[8:9]
	s_mov_b64 s[4:5], 0x13310000
	v_lshl_add_u64 v[8:9], v[8:9], 0, s[4:5]
	s_mov_b64 s[8:9], 0
	s_mov_b32 s10, 0x3a000000
	s_movk_i32 s4, 0x3fff
	global_load_dwordx4 v[124:127], v[0:1], off offset:16
	global_load_dwordx4 v[128:131], v[0:1], off
	global_load_dwordx4 v[132:135], v[0:1], off offset:2048
	global_load_dwordx4 v[136:139], v[0:1], off offset:2064
	global_load_dwordx4 v[140:143], v[2:3], off
	global_load_dwordx4 v[144:147], v[2:3], off offset:16
	global_load_dwordx4 v[148:151], v[4:5], off
	global_load_dwordx4 v[152:155], v[4:5], off offset:16
.LBB1_307:
	v_add_u32_e32 v85, s33, v12
	v_cmp_gt_i32_e32 vcc, s2, v85
	v_ashrrev_i32_e32 v13, 31, v12
	s_nop 0
	s_nop 0
	v_cndmask_b32_e32 v28, v12, v85, vcc
	v_ashrrev_i32_e32 v29, 31, v28
	v_lshlrev_b64 v[12:13], 12, v[12:13]
	v_lshlrev_b64 v[34:35], 12, v[28:29]
	v_lshl_add_u64 v[24:25], v[6:7], 0, v[12:13]
	v_lshl_add_u64 v[28:29], v[6:7], 0, v[34:35]
	v_lshl_add_u64 v[58:59], v[8:9], 0, v[12:13]
	global_load_dwordx4 v[12:15], v[24:25], off offset:2048
	global_load_dwordx4 v[16:19], v[24:25], off offset:3072
	global_load_dwordx4 v[20:23], v[24:25], off
	s_nop 0
	global_load_dwordx4 v[24:27], v[24:25], off offset:1024
	s_nop 0
	global_load_dwordx4 v[94:97], v[28:29], off offset:2048
	global_load_dwordx4 v[98:101], v[28:29], off
	global_load_dwordx4 v[102:105], v[28:29], off offset:1024
	global_load_dwordx4 v[106:109], v[28:29], off offset:3072
	v_lshl_add_u64 v[34:35], v[8:9], 0, v[34:35]
	s_waitcnt vmcnt(0) lgkmcnt(0)
	s_nop 1
	v_mov_b32_e32 v86, v124
	v_mov_b32_e32 v87, v125
	v_mov_b32_e32 v88, v126
	v_mov_b32_e32 v89, v127
	s_nop 1
	v_mov_b32_e32 v90, v128
	v_mov_b32_e32 v91, v129
	v_mov_b32_e32 v92, v130
	v_mov_b32_e32 v93, v131
	v_and_b32_e32 v77, 0xffff0000, v12
	v_and_b32_e32 v76, 0xffff0000, v14
	v_and_b32_e32 v69, 0xffff0000, v16
	v_and_b32_e32 v68, 0xffff0000, v18
	v_and_b32_e32 v47, 0xffff0000, v20
	v_and_b32_e32 v51, 0xffff0000, v22
	v_and_b32_e32 v46, 0xffff0000, v98
	v_and_b32_e32 v50, 0xffff0000, v100
	v_lshlrev_b32_e32 v73, 16, v12
	v_lshlrev_b32_e32 v72, 16, v14
	v_lshlrev_b32_e32 v75, 16, v13
	v_and_b32_e32 v79, 0xffff0000, v13
	v_lshlrev_b32_e32 v65, 16, v16
	v_lshlrev_b32_e32 v64, 16, v18
	v_lshlrev_b32_e32 v66, 16, v19
	v_and_b32_e32 v70, 0xffff0000, v19
	v_lshlrev_b32_e32 v39, 16, v20
	v_lshlrev_b32_e32 v43, 16, v22
	v_lshlrev_b32_e32 v45, 16, v23
	v_and_b32_e32 v53, 0xffff0000, v23
	v_lshlrev_b32_e32 v13, 16, v24
	v_and_b32_e32 v37, 0xffff0000, v24
	v_pk_mul_f32 v[18:19], v[76:77], v[76:77]
	v_pk_mul_f32 v[22:23], v[68:69], v[68:69]
	v_and_b32_e32 v61, 0xffff0000, v94
	v_and_b32_e32 v60, 0xffff0000, v96
	v_lshlrev_b32_e32 v38, 16, v98
	v_lshlrev_b32_e32 v42, 16, v100
	v_lshlrev_b32_e32 v44, 16, v101
	v_and_b32_e32 v52, 0xffff0000, v101
	v_lshlrev_b32_e32 v12, 16, v102
	v_and_b32_e32 v36, 0xffff0000, v102
	v_lshlrev_b32_e32 v14, 16, v103
	v_and_b32_e32 v24, 0xffff0000, v103
	v_and_b32_e32 v29, 0xffff0000, v106
	v_and_b32_e32 v28, 0xffff0000, v108
	v_pk_mul_f32 v[100:101], v[46:47], v[46:47]
	v_pk_mul_f32 v[102:103], v[50:51], v[50:51]
	v_lshlrev_b32_e32 v67, 16, v17
	v_and_b32_e32 v71, 0xffff0000, v17
	v_lshlrev_b32_e32 v41, 16, v21
	v_lshlrev_b32_e32 v17, 16, v26
	v_and_b32_e32 v31, 0xffff0000, v26
	v_pk_fma_f32 v[118:119], v[72:73], v[72:73], v[18:19]
	v_pk_fma_f32 v[120:121], v[64:65], v[64:65], v[22:23]
	v_lshlrev_b32_e32 v55, 16, v94
	v_lshlrev_b32_e32 v54, 16, v96
	v_lshlrev_b32_e32 v40, 16, v99
	v_and_b32_e32 v48, 0xffff0000, v99
	v_lshlrev_b32_e32 v16, 16, v104
	v_and_b32_e32 v30, 0xffff0000, v104
	v_lshlrev_b32_e32 v20, 16, v105
	v_and_b32_e32 v26, 0xffff0000, v105
	v_lshlrev_b32_e32 v19, 16, v106
	v_lshlrev_b32_e32 v18, 16, v108
	v_lshlrev_b32_e32 v22, 16, v109
	v_and_b32_e32 v32, 0xffff0000, v109
; DI unsigned pack2(float a, float b) { f32x2 v = {a, b}; hwbf16x2 r = __builtin_convertvector(v, hwbf16x2); return __builtin_bit_cast(unsigned, r); }
; DI float wave_sum(float v) { for (int o = 32; o; o >>= 1) v += __shfl_xor(v, o); return v; }
;     DI const char* a(const Unit& u) const { return (const char*)(A + (size_t)u.pm * BM * lda); }
;     DI const char* a(const Unit& u) const { return (const char*)(A + (size_t)u.pm * BM * 2048 + (u.pn >> 1) * 512); }
;     DI const char* a(const Unit& u) const { return (const char*)((u.pn < 12 ? A1 : A2) + (size_t)u.pm * BM * 512); }
; template <bool BF> DI void norm_phase(const Params& p, const void* x, const float* gain) {
;     ...
;         ss[0] = wave_sum(ss[0]); ss[1] = wave_sum(ss[1]);
; #pragma unroll
;         for (int q = 0; q < 2; ++q) {
;             const int tt = q ? t2 : t;
;             const float rs = rsqrtf(ss[q] * (1.0f / D) + EPS);
; #pragma unroll
;             for (int i = 0; i < 4; ++i) { const int c = (i * 64 + lane) * 8;
;                 const f32x4 g0 = *(const f32x4*)(gain + c), g1 = *(const f32x4*)(gain + c + 4);
;                 const f32x4 a = v[q][2 * i] * rs * g0, d = v[q][2 * i + 1] * rs * g1;
;                 u32x4 o; o[0] = pack2(a[0], a[1]); o[1] = pack2(a[2], a[3]); o[2] = pack2(d[0], d[1]); o[3] = pack2(d[2], d[3]);
;                 *(u32x4*)(H + (size_t)tt * D + c) = o; }
	v_pk_mul_f32 v[98:99], v[60:61], v[60:61]
	v_pk_mul_f32 v[104:105], v[36:37], v[36:37]
	v_pk_mul_f32 v[108:109], v[28:29], v[28:29]
	v_pk_fma_f32 v[100:101], v[38:39], v[38:39], v[100:101]
	v_pk_fma_f32 v[102:103], v[42:43], v[42:43], v[102:103]
	v_lshlrev_b32_e32 v74, 16, v15
	v_and_b32_e32 v78, 0xffff0000, v15
	v_and_b32_e32 v49, 0xffff0000, v21
	v_lshlrev_b32_e32 v15, 16, v25
	v_lshlrev_b32_e32 v57, 16, v95
	v_lshlrev_b32_e32 v56, 16, v97
	v_lshlrev_b32_e32 v23, 16, v107
	v_and_b32_e32 v33, 0xffff0000, v107
	v_pk_mul_f32 v[106:107], v[30:31], v[30:31]
	v_pk_fma_f32 v[98:99], v[54:55], v[54:55], v[98:99]
	v_pk_fma_f32 v[104:105], v[12:13], v[12:13], v[104:105]
	v_pk_fma_f32 v[108:109], v[18:19], v[18:19], v[108:109]
	v_pk_fma_f32 v[100:101], v[40:41], v[40:41], v[100:101]
	v_pk_fma_f32 v[102:103], v[44:45], v[44:45], v[102:103]
	v_and_b32_e32 v25, 0xffff0000, v25
	v_lshlrev_b32_e32 v21, 16, v27
	v_and_b32_e32 v63, 0xffff0000, v95
	v_and_b32_e32 v62, 0xffff0000, v97
	v_pk_fma_f32 v[94:95], v[74:75], v[74:75], v[118:119]
	v_pk_fma_f32 v[96:97], v[66:67], v[66:67], v[120:121]
	v_pk_fma_f32 v[106:107], v[16:17], v[16:17], v[106:107]
	v_pk_fma_f32 v[98:99], v[56:57], v[56:57], v[98:99]
	v_pk_fma_f32 v[104:105], v[14:15], v[14:15], v[104:105]
	v_pk_fma_f32 v[108:109], v[22:23], v[22:23], v[108:109]
	v_pk_fma_f32 v[100:101], v[48:49], v[48:49], v[100:101]
	v_pk_fma_f32 v[102:103], v[52:53], v[52:53], v[102:103]
	v_and_b32_e32 v27, 0xffff0000, v27
	v_pk_fma_f32 v[94:95], v[78:79], v[78:79], v[94:95]
	v_pk_fma_f32 v[96:97], v[70:71], v[70:71], v[96:97]
	v_pk_fma_f32 v[106:107], v[20:21], v[20:21], v[106:107]
	v_pk_fma_f32 v[98:99], v[62:63], v[62:63], v[98:99]
	v_pk_fma_f32 v[104:105], v[24:25], v[24:25], v[104:105]
	v_pk_fma_f32 v[108:109], v[32:33], v[32:33], v[108:109]
	v_pk_add_f32 v[100:101], v[100:101], v[102:103]
	v_mov_b32_e32 v119, v95
	v_mov_b32_e32 v95, v97
	v_pk_fma_f32 v[106:107], v[26:27], v[26:27], v[106:107]
	v_mov_b32_e32 v118, v99
	v_mov_b32_e32 v99, v94
	v_mov_b32_e32 v94, v109
	v_mov_b32_e32 v109, v96
	v_pk_add_f32 v[96:97], v[100:101], v[104:105]
	v_mov_b32_e32 v110, v39
	v_pk_add_f32 v[96:97], v[106:107], v[96:97]
	v_mov_b32_e32 v112, v41
	v_pk_add_f32 v[96:97], v[118:119], v[96:97]
	v_mov_b32_e32 v111, v47
	v_pk_add_f32 v[96:97], v[98:99], v[96:97]
	v_mov_b32_e32 v113, v49
	v_pk_add_f32 v[94:95], v[94:95], v[96:97]
	v_mov_b32_e32 v114, v43
	v_pk_add_f32 v[94:95], v[108:109], v[94:95]
	ds_bpermute_b32 v97, v11, v95
	ds_bpermute_b32 v96, v11, v94
	v_mov_b32_e32 v115, v51
	v_mov_b32_e32 v116, v45
	v_mov_b32_e32 v117, v53
	v_mov_b32_e32 v43, v50
	s_waitcnt lgkmcnt(0)
	v_pk_add_f32 v[94:95], v[94:95], v[96:97]
	ds_bpermute_b32 v97, v80, v95
	ds_bpermute_b32 v96, v80, v94
	v_mov_b32_e32 v45, v52
	s_waitcnt lgkmcnt(0)
	v_pk_add_f32 v[94:95], v[94:95], v[96:97]
	ds_bpermute_b32 v97, v81, v95
	ds_bpermute_b32 v96, v81, v94
	s_waitcnt lgkmcnt(0)
	v_pk_add_f32 v[94:95], v[94:95], v[96:97]
	ds_bpermute_b32 v97, v82, v95
	ds_bpermute_b32 v96, v82, v94
	s_waitcnt lgkmcnt(0)
	v_pk_add_f32 v[94:95], v[94:95], v[96:97]
	ds_bpermute_b32 v97, v83, v95
	ds_bpermute_b32 v96, v83, v94
	s_waitcnt lgkmcnt(0)
	v_pk_add_f32 v[94:95], v[94:95], v[96:97]
	ds_bpermute_b32 v97, v84, v95
	ds_bpermute_b32 v96, v84, v94
	s_waitcnt lgkmcnt(0)
	v_pk_add_f32 v[94:95], v[94:95], v[96:97]
	s_nop 0
	v_pk_fma_f32 v[94:95], v[94:95], s[10:11], v[10:11] op_sel_hi:[1,0,0]
	s_nop 0
	v_mul_f32_e32 v39, 0x4b800000, v95
	v_cmp_gt_f32_e32 vcc, s3, v95
	s_nop 1
	v_cndmask_b32_e32 v39, v95, v39, vcc
	v_rsq_f32_e32 v39, v39
	s_nop 0
	v_mul_f32_e32 v41, 0x45800000, v39
	v_cndmask_b32_e32 v96, v39, v41, vcc
	v_pk_mul_f32 v[98:99], v[96:97], v[110:111] op_sel_hi:[0,1]
	v_pk_mul_f32 v[100:101], v[96:97], v[112:113] op_sel_hi:[0,1]
	v_pk_mul_f32 v[102:103], v[96:97], v[114:115] op_sel_hi:[0,1]
	v_pk_mul_f32 v[104:105], v[96:97], v[116:117] op_sel_hi:[0,1]
	v_pk_mul_f32 v[92:93], v[92:93], v[100:101]
	v_pk_mul_f32 v[90:91], v[90:91], v[98:99]
	v_pk_mul_f32 v[98:99], v[88:89], v[104:105]
	v_pk_mul_f32 v[88:89], v[86:87], v[102:103]
	v_cvt_pk_bf16_f32 v86, v90, v91
	v_cvt_pk_bf16_f32 v87, v92, v93
	v_cvt_pk_bf16_f32 v88, v88, v89
	v_cvt_pk_bf16_f32 v89, v98, v99
	global_store_dwordx4 v[58:59], v[86:89], off
	s_nop 1
	v_mov_b32_e32 v86, v132
	v_mov_b32_e32 v87, v133
	v_mov_b32_e32 v88, v134
	v_mov_b32_e32 v89, v135
	s_nop 0
	s_nop 1
	v_mov_b32_e32 v90, v136
	v_mov_b32_e32 v91, v137
	v_mov_b32_e32 v92, v138
	v_mov_b32_e32 v93, v139
	v_mov_b32_e32 v98, v13
	v_mov_b32_e32 v99, v37
	v_mov_b32_e32 v100, v15
	v_mov_b32_e32 v101, v25
	v_mov_b32_e32 v102, v17
	v_mov_b32_e32 v103, v31
	v_mov_b32_e32 v104, v21
	v_mov_b32_e32 v105, v27
	v_pk_mul_f32 v[98:99], v[96:97], v[98:99] op_sel_hi:[0,1]
	v_pk_mul_f32 v[100:101], v[96:97], v[100:101] op_sel_hi:[0,1]
	v_pk_mul_f32 v[102:103], v[96:97], v[102:103] op_sel_hi:[0,1]
	v_pk_mul_f32 v[104:105], v[96:97], v[104:105] op_sel_hi:[0,1]
	v_mul_f32_e32 v13, 0x4b800000, v94
	v_cmp_gt_f32_e32 vcc, s3, v94
	v_mov_b32_e32 v39, v46
	v_mov_b32_e32 v41, v48
	v_cndmask_b32_e32 v13, v94, v13, vcc
	v_rsq_f32_e32 v13, v13
	v_mov_b32_e32 v17, v30
	v_mov_b32_e32 v21, v26
	v_mul_f32_e32 v15, 0x45800000, v13
	v_cndmask_b32_e32 v46, v13, v15, vcc
	v_pk_mul_f32 v[38:39], v[46:47], v[38:39] op_sel_hi:[0,1]
	v_pk_mul_f32 v[40:41], v[46:47], v[40:41] op_sel_hi:[0,1]
	v_pk_mul_f32 v[42:43], v[46:47], v[42:43] op_sel_hi:[0,1]
	v_pk_mul_f32 v[44:45], v[46:47], v[44:45] op_sel_hi:[0,1]
	v_mov_b32_e32 v13, v36
	v_mov_b32_e32 v15, v24
	v_pk_mul_f32 v[12:13], v[46:47], v[12:13] op_sel_hi:[0,1]
	v_pk_mul_f32 v[14:15], v[46:47], v[14:15] op_sel_hi:[0,1]
; DI unsigned pack2(float a, float b) { f32x2 v = {a, b}; hwbf16x2 r = __builtin_convertvector(v, hwbf16x2); return __builtin_bit_cast(unsigned, r); }
;     DI const char* a(const Unit& u) const { return (const char*)(A + (size_t)u.pm * BM * lda); }
;     DI const char* a(const Unit& u) const { return (const char*)(A + (size_t)u.pm * BM * 2048 + (u.pn >> 1) * 512); }
;     DI const char* a(const Unit& u) const { return (const char*)((u.pn < 12 ? A1 : A2) + (size_t)u.pm * BM * 512); }
; template <bool BF> DI void norm_phase(const Params& p, const void* x, const float* gain) {
;     ...
; #pragma unroll
;         for (int q = 0; q < 2; ++q) {
;             const int tt = q ? t2 : t;
;             const float rs = rsqrtf(ss[q] * (1.0f / D) + EPS);
; #pragma unroll
;             for (int i = 0; i < 4; ++i) { const int c = (i * 64 + lane) * 8;
;                 const f32x4 g0 = *(const f32x4*)(gain + c), g1 = *(const f32x4*)(gain + c + 4);
;                 const f32x4 a = v[q][2 * i] * rs * g0, d = v[q][2 * i + 1] * rs * g1;
;                 u32x4 o; o[0] = pack2(a[0], a[1]); o[1] = pack2(a[2], a[3]); o[2] = pack2(d[0], d[1]); o[3] = pack2(d[2], d[3]);
;                 *(u32x4*)(H + (size_t)tt * D + c) = o; }
	v_pk_mul_f32 v[16:17], v[46:47], v[16:17] op_sel_hi:[0,1]
	v_pk_mul_f32 v[20:21], v[46:47], v[20:21] op_sel_hi:[0,1]
	s_nop 0
	v_pk_mul_f32 v[88:89], v[88:89], v[100:101]
	v_pk_mul_f32 v[86:87], v[86:87], v[98:99]
	v_pk_mul_f32 v[92:93], v[92:93], v[104:105]
	v_pk_mul_f32 v[90:91], v[90:91], v[102:103]
	v_cvt_pk_bf16_f32 v86, v86, v87
	v_cvt_pk_bf16_f32 v87, v88, v89
	v_cvt_pk_bf16_f32 v88, v90, v91
	v_cvt_pk_bf16_f32 v89, v92, v93
	global_store_dwordx4 v[58:59], v[86:89], off offset:1024
	s_nop 1
	v_mov_b32_e32 v86, v140
	v_mov_b32_e32 v87, v141
	v_mov_b32_e32 v88, v142
	v_mov_b32_e32 v89, v143
	s_nop 0
	s_nop 1
	v_mov_b32_e32 v90, v144
	v_mov_b32_e32 v91, v145
	v_mov_b32_e32 v92, v146
	v_mov_b32_e32 v93, v147
	v_mov_b32_e32 v98, v73
	v_mov_b32_e32 v99, v77
	v_mov_b32_e32 v100, v75
	v_mov_b32_e32 v101, v79
	v_mov_b32_e32 v73, v76
	v_mov_b32_e32 v75, v78
	v_pk_mul_f32 v[76:77], v[96:97], v[98:99] op_sel_hi:[0,1]
	v_pk_mul_f32 v[78:79], v[96:97], v[100:101] op_sel_hi:[0,1]
	v_pk_mul_f32 v[72:73], v[96:97], v[72:73] op_sel_hi:[0,1]
	v_pk_mul_f32 v[74:75], v[96:97], v[74:75] op_sel_hi:[0,1]
	s_nop 0
	v_pk_mul_f32 v[78:79], v[88:89], v[78:79]
	v_pk_mul_f32 v[76:77], v[86:87], v[76:77]
	v_pk_mul_f32 v[86:87], v[92:93], v[74:75]
	v_pk_mul_f32 v[74:75], v[90:91], v[72:73]
	v_cvt_pk_bf16_f32 v72, v76, v77
	v_cvt_pk_bf16_f32 v73, v78, v79
	v_cvt_pk_bf16_f32 v74, v74, v75
	v_cvt_pk_bf16_f32 v75, v86, v87
	global_store_dwordx4 v[58:59], v[72:75], off offset:2048
	s_nop 1
	v_mov_b32_e32 v72, v148
	v_mov_b32_e32 v73, v149
	v_mov_b32_e32 v74, v150
	v_mov_b32_e32 v75, v151
	s_nop 0
	s_nop 1
	v_mov_b32_e32 v76, v152
	v_mov_b32_e32 v77, v153
	v_mov_b32_e32 v78, v154
	v_mov_b32_e32 v79, v155
	v_mov_b32_e32 v86, v65
	v_mov_b32_e32 v87, v69
	v_mov_b32_e32 v88, v67
	v_mov_b32_e32 v89, v71
	v_mov_b32_e32 v65, v68
	v_mov_b32_e32 v67, v70
	v_pk_mul_f32 v[68:69], v[96:97], v[86:87] op_sel_hi:[0,1]
	v_pk_mul_f32 v[70:71], v[96:97], v[88:89] op_sel_hi:[0,1]
	v_pk_mul_f32 v[64:65], v[96:97], v[64:65] op_sel_hi:[0,1]
	v_pk_mul_f32 v[66:67], v[96:97], v[66:67] op_sel_hi:[0,1]
	s_nop 0
	v_pk_mul_f32 v[70:71], v[74:75], v[70:71]
	v_pk_mul_f32 v[68:69], v[72:73], v[68:69]
	v_pk_mul_f32 v[72:73], v[78:79], v[66:67]
	v_pk_mul_f32 v[66:67], v[76:77], v[64:65]
	v_cvt_pk_bf16_f32 v64, v68, v69
	v_cvt_pk_bf16_f32 v65, v70, v71
	v_cvt_pk_bf16_f32 v66, v66, v67
	v_cvt_pk_bf16_f32 v67, v72, v73
	global_store_dwordx4 v[58:59], v[64:67], off offset:3072
	s_nop 1
	v_mov_b32_e32 v64, v128
	v_mov_b32_e32 v65, v129
	v_mov_b32_e32 v66, v130
	v_mov_b32_e32 v67, v131
	s_nop 0
	s_nop 1
	v_mov_b32_e32 v68, v124
	v_mov_b32_e32 v69, v125
	v_mov_b32_e32 v70, v126
	v_mov_b32_e32 v71, v127
	s_nop 0
	v_pk_mul_f32 v[40:41], v[66:67], v[40:41]
	v_pk_mul_f32 v[38:39], v[64:65], v[38:39]
	v_pk_mul_f32 v[44:45], v[70:71], v[44:45]
	v_pk_mul_f32 v[42:43], v[68:69], v[42:43]
	v_cvt_pk_bf16_f32 v38, v38, v39
	v_cvt_pk_bf16_f32 v39, v40, v41
	v_cvt_pk_bf16_f32 v40, v42, v43
	v_cvt_pk_bf16_f32 v41, v44, v45
	global_store_dwordx4 v[34:35], v[38:41], off
	s_nop 1
	v_mov_b32_e32 v38, v132
	v_mov_b32_e32 v39, v133
	v_mov_b32_e32 v40, v134
	v_mov_b32_e32 v41, v135
	s_nop 0
	s_nop 1
	v_mov_b32_e32 v42, v136
	v_mov_b32_e32 v43, v137
	v_mov_b32_e32 v44, v138
	v_mov_b32_e32 v45, v139
	s_nop 0
	v_pk_mul_f32 v[14:15], v[14:15], v[40:41]
	v_pk_mul_f32 v[12:13], v[12:13], v[38:39]
	v_pk_mul_f32 v[20:21], v[20:21], v[44:45]
	v_pk_mul_f32 v[16:17], v[16:17], v[42:43]
	v_cvt_pk_bf16_f32 v12, v12, v13
	v_cvt_pk_bf16_f32 v13, v14, v15
	v_cvt_pk_bf16_f32 v14, v16, v17
	v_cvt_pk_bf16_f32 v15, v20, v21
	global_store_dwordx4 v[34:35], v[12:15], off offset:1024
	s_nop 1
	v_mov_b32_e32 v12, v140
	v_mov_b32_e32 v13, v141
	v_mov_b32_e32 v14, v142
	v_mov_b32_e32 v15, v143
	s_nop 0
	s_nop 1
	v_mov_b32_e32 v24, v144
	v_mov_b32_e32 v25, v145
	v_mov_b32_e32 v26, v146
	v_mov_b32_e32 v27, v147
	v_mov_b32_e32 v16, v55
	v_mov_b32_e32 v17, v61
	v_mov_b32_e32 v20, v57
	v_mov_b32_e32 v21, v63
	v_mov_b32_e32 v55, v60
	v_mov_b32_e32 v57, v62
	v_pk_mul_f32 v[16:17], v[46:47], v[16:17] op_sel_hi:[0,1]
	v_pk_mul_f32 v[20:21], v[46:47], v[20:21] op_sel_hi:[0,1]
	v_pk_mul_f32 v[30:31], v[46:47], v[54:55] op_sel_hi:[0,1]
	v_pk_mul_f32 v[36:37], v[46:47], v[56:57] op_sel_hi:[0,1]
	s_nop 0
	v_pk_mul_f32 v[14:15], v[20:21], v[14:15]
	v_pk_mul_f32 v[12:13], v[16:17], v[12:13]
	v_pk_mul_f32 v[16:17], v[36:37], v[26:27]
	v_pk_mul_f32 v[20:21], v[30:31], v[24:25]
	v_cvt_pk_bf16_f32 v12, v12, v13
	v_cvt_pk_bf16_f32 v13, v14, v15
	v_cvt_pk_bf16_f32 v14, v20, v21
	v_cvt_pk_bf16_f32 v15, v16, v17
	global_store_dwordx4 v[34:35], v[12:15], off offset:2048
	s_nop 1
	v_mov_b32_e32 v14, v148
	v_mov_b32_e32 v15, v149
	v_mov_b32_e32 v16, v150
	v_mov_b32_e32 v17, v151
	s_nop 0
	s_nop 1
	v_mov_b32_e32 v24, v152
	v_mov_b32_e32 v25, v153
	v_mov_b32_e32 v26, v154
	v_mov_b32_e32 v27, v155
	v_mov_b32_e32 v20, v19
	v_mov_b32_e32 v21, v29
	v_mov_b32_e32 v30, v23
	v_mov_b32_e32 v31, v33
	v_mov_b32_e32 v19, v28
	v_mov_b32_e32 v23, v32
	v_add_u32_e32 v12, s33, v85
	v_pk_mul_f32 v[20:21], v[46:47], v[20:21] op_sel_hi:[0,1]
	v_pk_mul_f32 v[28:29], v[46:47], v[30:31] op_sel_hi:[0,1]
	v_pk_mul_f32 v[18:19], v[46:47], v[18:19] op_sel_hi:[0,1]
	v_pk_mul_f32 v[22:23], v[46:47], v[22:23] op_sel_hi:[0,1]
	v_cmp_lt_i32_e32 vcc, s4, v12
	s_or_b64 s[8:9], vcc, s[8:9]
	s_nop 0
	v_pk_mul_f32 v[16:17], v[28:29], v[16:17]
	v_pk_mul_f32 v[14:15], v[20:21], v[14:15]
	v_pk_mul_f32 v[20:21], v[22:23], v[26:27]
	v_pk_mul_f32 v[18:19], v[18:19], v[24:25]
	v_cvt_pk_bf16_f32 v14, v14, v15
	v_cvt_pk_bf16_f32 v15, v16, v17
	v_cvt_pk_bf16_f32 v16, v18, v19
	v_cvt_pk_bf16_f32 v17, v20, v21
	global_store_dwordx4 v[34:35], v[14:17], off offset:3072
	s_andn2_b64 exec, exec, s[8:9]
	s_cbranch_execnz .LBB1_307

; DI float bflo(unsigned w) { return __uint_as_float(w << 16); }
; DI float bfhi(unsigned w) { return __uint_as_float(w & 0xffff0000u); }
; DI int opaque_tid() { int t = threadIdx.x; asm volatile("" : "+v"(t)); return t; }
; template <bool BF> DI void norm_phase(const Params& p, const void* x, const float* gain) {
;     ...
;     bf16_t* H = (bf16_t*)(ws + OFF_H);
;     const int tid = opaque_tid(), wid = tid >> 6, lane = tid & 63;
;     const int step = gridDim.x * 8;
;     for (int t = bid * 8 + wid; t < T; t += 2 * step) {
;         const int t2 = (t + step < T) ? t + step : t;
;         f32x4 v[2][8];
; #pragma unroll
;         for (int q = 0; q < 2; ++q) {
;             const int tt = q ? t2 : t;
; #pragma unroll
;             for (int i = 0; i < 4; ++i) {
;                 const size_t e = (size_t)tt * D + (i * 64 + lane) * 8;
;                 if constexpr (BF) { const u32x4 w = *(const u32x4*)((const bf16_t*)x + e);
;                     v[q][2 * i] = (f32x4){bflo(w[0]), bfhi(w[0]), bflo(w[1]), bfhi(w[1])}; v[q][2 * i + 1] = (f32x4){bflo(w[2]), bfhi(w[2]), bflo(w[3]), bfhi(w[3])}; }
;                 else { v[q][2 * i] = *(const f32x4*)((const float*)x + e); v[q][2 * i + 1] = *(const f32x4*)((const float*)x + e + 4); }
;             }
;         }
;         float ss[2] = {0.f, 0.f};
; #pragma unroll
;         for (int q = 0; q < 2; ++q)
; #pragma unroll
;             for (int i = 0; i < 8; ++i) ss[q] += v[q][i][0] * v[q][i][0] + v[q][i][1] * v[q][i][1] + v[q][i][2] * v[q][i][2] + v[q][i][3] * v[q][i][3];
;     ...
;             for (int i = 0; i < 4; ++i) { const int c = (i * 64 + lane) * 8;
;                 const f32x4 g0 = *(const f32x4*)(gain + c), g1 = *(const f32x4*)(gain + c + 4);
.LBB1_619:
	s_or_b64 exec, exec, s[6:7]
	s_waitcnt lgkmcnt(0)
	s_barrier
	s_load_dwordx2 s[10:11], s[0:1], 0x88
	v_mov_b32_e32 v0, v197
	s_waitcnt lgkmcnt(0)
	s_mov_b32 s2, s11
	s_mov_b32 s3, s10
	s_mov_b32 s9, s11
	s_mov_b32 s8, s10
	s_mov_b32 s2, s61
	s_nop 0
	v_ashrrev_i32_e32 v1, 6, v0
	v_lshl_add_u32 v22, s2, 3, v1
	s_movk_i32 s2, 0x4000
	v_cmp_gt_i32_e32 vcc, s2, v22
	s_and_saveexec_b64 s[6:7], vcc
	s_cbranch_execz .LBB1_622
	v_lshlrev_b32_e32 v0, 3, v0
	v_mbcnt_hi_u32_b32 v1, -1, v228
	v_and_b32_e32 v4, 0x1f8, v0
	v_and_b32_e32 v0, 64, v1
	v_add_u32_e32 v0, 64, v0
	v_xor_b32_e32 v2, 32, v1
	v_cmp_lt_i32_e32 vcc, v2, v0
	s_load_dwordx2 s[4:5], s[0:1], 0x10
	v_mov_b32_e32 v20, 0x358637bd
	v_cndmask_b32_e32 v2, v1, v2, vcc
	v_lshlrev_b32_e32 v21, 2, v2
	v_xor_b32_e32 v2, 16, v1
	v_cmp_lt_i32_e32 vcc, v2, v0
	s_waitcnt lgkmcnt(0)
	s_add_u32 s4, s4, 0x2000
	s_addc_u32 s5, s5, 0
	v_cndmask_b32_e32 v2, v1, v2, vcc
	v_lshlrev_b32_e32 v74, 2, v2
	v_xor_b32_e32 v2, 8, v1
	v_cmp_lt_i32_e32 vcc, v2, v0
	s_mov_b32 s3, 0x800000
	s_nop 0
	v_cndmask_b32_e32 v2, v1, v2, vcc
	v_lshlrev_b32_e32 v75, 2, v2
	v_xor_b32_e32 v2, 4, v1
	v_cmp_lt_i32_e32 vcc, v2, v0
	s_nop 1
	v_cndmask_b32_e32 v2, v1, v2, vcc
	v_lshlrev_b32_e32 v76, 2, v2
	v_xor_b32_e32 v2, 2, v1
	v_cmp_lt_i32_e32 vcc, v2, v0
	s_nop 1
	v_cndmask_b32_e32 v2, v1, v2, vcc
	v_lshlrev_b32_e32 v77, 2, v2
	v_xor_b32_e32 v2, 1, v1
	v_cmp_lt_i32_e32 vcc, v2, v0
	s_nop 1
	v_cndmask_b32_e32 v0, v1, v2, vcc
	v_lshlrev_b32_e32 v78, 2, v0
	v_lshlrev_b32_e32 v0, 2, v4
	v_mov_b32_e32 v1, 0
	v_or_b32_e32 v2, 0x800, v0
	v_mov_b32_e32 v3, v1
	v_lshl_add_u64 v[8:9], s[4:5], 0, v[0:1]
	v_lshl_add_u64 v[10:11], s[4:5], 0, v[2:3]
	v_or_b32_e32 v2, 0x1000, v0
	v_or_b32_e32 v0, 0x1800, v0
	v_lshl_add_u64 v[14:15], s[4:5], 0, v[0:1]
	v_lshlrev_b32_e32 v0, 1, v4
	v_lshl_add_u64 v[12:13], s[4:5], 0, v[2:3]
	v_lshl_add_u64 v[2:3], s[8:9], 0, v[0:1]
	s_mov_b64 s[4:5], 0x4c614000
	v_lshl_add_u64 v[16:17], v[2:3], 0, s[4:5]
	v_lshl_add_u64 v[0:1], s[10:11], 0, v[0:1]
	s_mov_b64 s[4:5], 0x13310000
	v_lshl_add_u64 v[18:19], v[0:1], 0, s[4:5]
	s_mov_b64 s[8:9], 0
	s_movk_i32 s4, 0x3fff
	s_mov_b32 s10, 0x3a000000
	global_load_dwordx4 v[124:127], v[8:9], off offset:16
	global_load_dwordx4 v[128:131], v[8:9], off
	global_load_dwordx4 v[132:135], v[10:11], off
	global_load_dwordx4 v[136:139], v[10:11], off offset:16
	global_load_dwordx4 v[140:143], v[12:13], off
	global_load_dwordx4 v[144:147], v[12:13], off offset:16
	global_load_dwordx4 v[148:151], v[14:15], off
	global_load_dwordx4 v[152:155], v[14:15], off offset:16
.LBB1_621:
	v_add_u32_e32 v79, s33, v22
	v_cmp_gt_i32_e32 vcc, s2, v79
	v_ashrrev_i32_e32 v23, 31, v22
	s_nop 0
	s_nop 0
	v_cndmask_b32_e32 v38, v22, v79, vcc
	v_ashrrev_i32_e32 v39, 31, v38
	v_lshlrev_b64 v[22:23], 12, v[22:23]
	v_lshlrev_b64 v[52:53], 12, v[38:39]
	v_lshl_add_u64 v[34:35], v[16:17], 0, v[22:23]
	v_lshl_add_u64 v[38:39], v[16:17], 0, v[52:53]
	v_lshl_add_u64 v[72:73], v[18:19], 0, v[22:23]
	global_load_dwordx4 v[22:25], v[34:35], off offset:2048
	global_load_dwordx4 v[26:29], v[34:35], off offset:3072
	global_load_dwordx4 v[30:33], v[34:35], off
	s_nop 0
	global_load_dwordx4 v[34:37], v[34:35], off offset:1024
	s_nop 0
	global_load_dwordx4 v[80:83], v[38:39], off offset:2048
	global_load_dwordx4 v[84:87], v[38:39], off
	global_load_dwordx4 v[88:91], v[38:39], off offset:1024
	global_load_dwordx4 v[92:95], v[38:39], off offset:3072
	v_lshl_add_u64 v[52:53], v[18:19], 0, v[52:53]
	s_waitcnt vmcnt(0) lgkmcnt(0)
	s_nop 1
	v_mov_b32_e32 v0, v124
	v_mov_b32_e32 v1, v125
	v_mov_b32_e32 v2, v126
	v_mov_b32_e32 v3, v127
	s_nop 1
	v_mov_b32_e32 v4, v128
	v_mov_b32_e32 v5, v129
	v_mov_b32_e32 v6, v130
	v_mov_b32_e32 v7, v131
	v_and_b32_e32 v99, 0xffff0000, v22
	v_and_b32_e32 v98, 0xffff0000, v24
	v_and_b32_e32 v107, 0xffff0000, v26
	v_and_b32_e32 v106, 0xffff0000, v28
	v_and_b32_e32 v65, 0xffff0000, v30
	v_and_b32_e32 v69, 0xffff0000, v32
	v_and_b32_e32 v64, 0xffff0000, v84
	v_and_b32_e32 v68, 0xffff0000, v86
	v_lshlrev_b32_e32 v97, 16, v22
	v_lshlrev_b32_e32 v96, 16, v24
	v_lshlrev_b32_e32 v101, 16, v23
	v_lshlrev_b32_e32 v100, 16, v25
	v_and_b32_e32 v103, 0xffff0000, v23
	v_and_b32_e32 v102, 0xffff0000, v25
	v_lshlrev_b32_e32 v105, 16, v26
	v_lshlrev_b32_e32 v104, 16, v28
	v_lshlrev_b32_e32 v108, 16, v29
	v_and_b32_e32 v110, 0xffff0000, v29
	v_lshlrev_b32_e32 v57, 16, v30
	v_lshlrev_b32_e32 v61, 16, v32
	v_lshlrev_b32_e32 v39, 16, v34
	v_and_b32_e32 v55, 0xffff0000, v34
	v_lshlrev_b32_e32 v41, 16, v35
	v_and_b32_e32 v47, 0xffff0000, v35
	v_pk_mul_f32 v[22:23], v[98:99], v[98:99]
	v_pk_mul_f32 v[24:25], v[106:107], v[106:107]
	v_and_b32_e32 v35, 0xffff0000, v80
	v_and_b32_e32 v34, 0xffff0000, v82
	v_lshlrev_b32_e32 v56, 16, v84
	v_lshlrev_b32_e32 v60, 16, v86
	v_lshlrev_b32_e32 v62, 16, v87
	v_and_b32_e32 v70, 0xffff0000, v87
	v_lshlrev_b32_e32 v38, 16, v88
	v_and_b32_e32 v54, 0xffff0000, v88
	v_lshlrev_b32_e32 v40, 16, v89
	v_and_b32_e32 v46, 0xffff0000, v89
	v_and_b32_e32 v29, 0xffff0000, v92
	v_and_b32_e32 v28, 0xffff0000, v94
	v_pk_mul_f32 v[86:87], v[64:65], v[64:65]
	v_pk_mul_f32 v[88:89], v[68:69], v[68:69]
	v_lshlrev_b32_e32 v59, 16, v31
	v_lshlrev_b32_e32 v63, 16, v33
	v_and_b32_e32 v51, 0xffff0000, v36
	v_pk_fma_f32 v[120:121], v[96:97], v[96:97], v[22:23]
	v_pk_fma_f32 v[122:123], v[104:105], v[104:105], v[24:25]
	v_lshlrev_b32_e32 v23, 16, v80
	v_lshlrev_b32_e32 v22, 16, v82
	v_lshlrev_b32_e32 v58, 16, v85
	v_and_b32_e32 v66, 0xffff0000, v85
	v_lshlrev_b32_e32 v42, 16, v90
	v_and_b32_e32 v50, 0xffff0000, v90
	v_lshlrev_b32_e32 v44, 16, v91
	v_and_b32_e32 v48, 0xffff0000, v91
; DI unsigned pack2(float a, float b) { f32x2 v = {a, b}; hwbf16x2 r = __builtin_convertvector(v, hwbf16x2); return __builtin_bit_cast(unsigned, r); }
; DI float wave_sum(float v) { for (int o = 32; o; o >>= 1) v += __shfl_xor(v, o); return v; }
;     DI const char* a(const Unit& u) const { return (const char*)(A + (size_t)u.pm * BM * lda); }
;     DI const char* a(const Unit& u) const { return (const char*)(A + (size_t)u.pm * BM * 2048 + (u.pn >> 1) * 512); }
;     DI const char* a(const Unit& u) const { return (const char*)((u.pn < 12 ? A1 : A2) + (size_t)u.pm * BM * 512); }
; template <bool BF> DI void norm_phase(const Params& p, const void* x, const float* gain) {
;     ...
;         ss[0] = wave_sum(ss[0]); ss[1] = wave_sum(ss[1]);
; #pragma unroll
;         for (int q = 0; q < 2; ++q) {
;             const int tt = q ? t2 : t;
;             const float rs = rsqrtf(ss[q] * (1.0f / D) + EPS);
; #pragma unroll
;             for (int i = 0; i < 4; ++i) { const int c = (i * 64 + lane) * 8;
;                 const f32x4 g0 = *(const f32x4*)(gain + c), g1 = *(const f32x4*)(gain + c + 4);
;                 const f32x4 a = v[q][2 * i] * rs * g0, d = v[q][2 * i + 1] * rs * g1;
;                 u32x4 o; o[0] = pack2(a[0], a[1]); o[1] = pack2(a[2], a[3]); o[2] = pack2(d[0], d[1]); o[3] = pack2(d[2], d[3]);
;                 *(u32x4*)(H + (size_t)tt * D + c) = o; }
	v_lshlrev_b32_e32 v25, 16, v92
	v_lshlrev_b32_e32 v24, 16, v94
	v_lshlrev_b32_e32 v26, 16, v95
	v_and_b32_e32 v30, 0xffff0000, v95
	v_pk_mul_f32 v[84:85], v[34:35], v[34:35]
	v_pk_mul_f32 v[90:91], v[54:55], v[54:55]
	v_pk_mul_f32 v[94:95], v[28:29], v[28:29]
	v_pk_fma_f32 v[86:87], v[56:57], v[56:57], v[86:87]
	v_pk_fma_f32 v[88:89], v[60:61], v[60:61], v[88:89]
	v_lshlrev_b32_e32 v109, 16, v27
	v_and_b32_e32 v111, 0xffff0000, v27
	v_and_b32_e32 v67, 0xffff0000, v31
	v_and_b32_e32 v71, 0xffff0000, v33
	v_lshlrev_b32_e32 v43, 16, v36
	v_lshlrev_b32_e32 v33, 16, v81
	v_lshlrev_b32_e32 v32, 16, v83
	v_lshlrev_b32_e32 v27, 16, v93
	v_and_b32_e32 v31, 0xffff0000, v93
	v_pk_mul_f32 v[92:93], v[50:51], v[50:51]
	v_pk_fma_f32 v[84:85], v[22:23], v[22:23], v[84:85]
	v_pk_fma_f32 v[90:91], v[38:39], v[38:39], v[90:91]
	v_pk_fma_f32 v[94:95], v[24:25], v[24:25], v[94:95]
	v_pk_fma_f32 v[86:87], v[58:59], v[58:59], v[86:87]
	v_pk_fma_f32 v[88:89], v[62:63], v[62:63], v[88:89]
	v_lshlrev_b32_e32 v45, 16, v37
	v_and_b32_e32 v49, 0xffff0000, v37
	v_and_b32_e32 v37, 0xffff0000, v81
	v_and_b32_e32 v36, 0xffff0000, v83
	v_pk_fma_f32 v[80:81], v[100:101], v[100:101], v[120:121]
	v_pk_fma_f32 v[82:83], v[108:109], v[108:109], v[122:123]
	v_pk_fma_f32 v[92:93], v[42:43], v[42:43], v[92:93]
	v_pk_fma_f32 v[84:85], v[32:33], v[32:33], v[84:85]
	v_pk_fma_f32 v[90:91], v[40:41], v[40:41], v[90:91]
	v_pk_fma_f32 v[94:95], v[26:27], v[26:27], v[94:95]
	v_pk_fma_f32 v[86:87], v[66:67], v[66:67], v[86:87]
	v_pk_fma_f32 v[88:89], v[70:71], v[70:71], v[88:89]
	v_pk_fma_f32 v[80:81], v[102:103], v[102:103], v[80:81]
	v_pk_fma_f32 v[82:83], v[110:111], v[110:111], v[82:83]
	v_pk_fma_f32 v[92:93], v[44:45], v[44:45], v[92:93]
	v_pk_fma_f32 v[84:85], v[36:37], v[36:37], v[84:85]
	v_pk_fma_f32 v[90:91], v[46:47], v[46:47], v[90:91]
	v_pk_fma_f32 v[94:95], v[30:31], v[30:31], v[94:95]
	v_pk_add_f32 v[86:87], v[86:87], v[88:89]
	v_mov_b32_e32 v121, v81
	v_mov_b32_e32 v81, v83
	v_pk_fma_f32 v[92:93], v[48:49], v[48:49], v[92:93]
	v_mov_b32_e32 v120, v85
	v_mov_b32_e32 v85, v80
	v_mov_b32_e32 v80, v95
	v_mov_b32_e32 v95, v82
	v_pk_add_f32 v[82:83], v[86:87], v[90:91]
	v_mov_b32_e32 v112, v57
	v_pk_add_f32 v[82:83], v[92:93], v[82:83]
	v_mov_b32_e32 v114, v59
	v_pk_add_f32 v[82:83], v[120:121], v[82:83]
	v_mov_b32_e32 v113, v65
	v_pk_add_f32 v[82:83], v[84:85], v[82:83]
	v_mov_b32_e32 v115, v67
	v_pk_add_f32 v[80:81], v[80:81], v[82:83]
	v_mov_b32_e32 v116, v61
	v_pk_add_f32 v[80:81], v[94:95], v[80:81]
	ds_bpermute_b32 v83, v21, v81
	ds_bpermute_b32 v82, v21, v80
	v_mov_b32_e32 v117, v69
	v_mov_b32_e32 v118, v63
	v_mov_b32_e32 v119, v71
	v_mov_b32_e32 v61, v68
	s_waitcnt lgkmcnt(0)
	v_pk_add_f32 v[80:81], v[80:81], v[82:83]
	ds_bpermute_b32 v83, v74, v81
	ds_bpermute_b32 v82, v74, v80
	v_mov_b32_e32 v63, v70
	s_waitcnt lgkmcnt(0)
	v_pk_add_f32 v[80:81], v[80:81], v[82:83]
	ds_bpermute_b32 v83, v75, v81
	ds_bpermute_b32 v82, v75, v80
	s_waitcnt lgkmcnt(0)
	v_pk_add_f32 v[80:81], v[80:81], v[82:83]
	ds_bpermute_b32 v83, v76, v81
	ds_bpermute_b32 v82, v76, v80
	s_waitcnt lgkmcnt(0)
	v_pk_add_f32 v[80:81], v[80:81], v[82:83]
	ds_bpermute_b32 v83, v77, v81
	ds_bpermute_b32 v82, v77, v80
	s_waitcnt lgkmcnt(0)
	v_pk_add_f32 v[80:81], v[80:81], v[82:83]
	ds_bpermute_b32 v83, v78, v81
	ds_bpermute_b32 v82, v78, v80
	s_waitcnt lgkmcnt(0)
	v_pk_add_f32 v[80:81], v[80:81], v[82:83]
	s_nop 0
	v_pk_fma_f32 v[80:81], v[80:81], s[10:11], v[20:21] op_sel_hi:[1,0,0]
	s_nop 0
	v_mul_f32_e32 v57, 0x4b800000, v81
	v_cmp_gt_f32_e32 vcc, s3, v81
	s_nop 1
	v_cndmask_b32_e32 v57, v81, v57, vcc
	v_rsq_f32_e32 v57, v57
	s_nop 0
	v_mul_f32_e32 v59, 0x45800000, v57
	v_cndmask_b32_e32 v82, v57, v59, vcc
	v_pk_mul_f32 v[84:85], v[82:83], v[112:113] op_sel_hi:[0,1]
	v_pk_mul_f32 v[86:87], v[82:83], v[114:115] op_sel_hi:[0,1]
	v_pk_mul_f32 v[88:89], v[82:83], v[116:117] op_sel_hi:[0,1]
	v_pk_mul_f32 v[90:91], v[82:83], v[118:119] op_sel_hi:[0,1]
	v_pk_mul_f32 v[6:7], v[6:7], v[86:87]
	v_pk_mul_f32 v[4:5], v[4:5], v[84:85]
	v_pk_mul_f32 v[84:85], v[2:3], v[90:91]
	v_pk_mul_f32 v[2:3], v[0:1], v[88:89]
	v_cvt_pk_bf16_f32 v0, v4, v5
	v_cvt_pk_bf16_f32 v1, v6, v7
	v_cvt_pk_bf16_f32 v2, v2, v3
	v_cvt_pk_bf16_f32 v3, v84, v85
	global_store_dwordx4 v[72:73], v[0:3], off
	s_nop 1
	v_mov_b32_e32 v0, v132
	v_mov_b32_e32 v1, v133
	v_mov_b32_e32 v2, v134
	v_mov_b32_e32 v3, v135
	s_nop 0
	s_nop 1
	v_mov_b32_e32 v4, v136
	v_mov_b32_e32 v5, v137
	v_mov_b32_e32 v6, v138
	v_mov_b32_e32 v7, v139
	v_mov_b32_e32 v84, v39
	v_mov_b32_e32 v85, v55
	v_mov_b32_e32 v86, v41
	v_mov_b32_e32 v87, v47
	v_mov_b32_e32 v88, v43
	v_mov_b32_e32 v89, v51
	v_mov_b32_e32 v90, v45
	v_mov_b32_e32 v91, v49
	v_pk_mul_f32 v[84:85], v[82:83], v[84:85] op_sel_hi:[0,1]
	v_pk_mul_f32 v[86:87], v[82:83], v[86:87] op_sel_hi:[0,1]
	v_pk_mul_f32 v[88:89], v[82:83], v[88:89] op_sel_hi:[0,1]
	v_pk_mul_f32 v[90:91], v[82:83], v[90:91] op_sel_hi:[0,1]
	v_mul_f32_e32 v39, 0x4b800000, v80
	v_cmp_gt_f32_e32 vcc, s3, v80
	v_mov_b32_e32 v57, v64
	v_mov_b32_e32 v59, v66
	v_cndmask_b32_e32 v39, v80, v39, vcc
	v_rsq_f32_e32 v39, v39
	v_mov_b32_e32 v43, v50
	v_mov_b32_e32 v45, v48
	v_mul_f32_e32 v41, 0x45800000, v39
	v_cndmask_b32_e32 v64, v39, v41, vcc
	v_pk_mul_f32 v[56:57], v[64:65], v[56:57] op_sel_hi:[0,1]
	v_pk_mul_f32 v[58:59], v[64:65], v[58:59] op_sel_hi:[0,1]
	v_pk_mul_f32 v[60:61], v[64:65], v[60:61] op_sel_hi:[0,1]
	v_pk_mul_f32 v[62:63], v[64:65], v[62:63] op_sel_hi:[0,1]
	v_mov_b32_e32 v39, v54
	v_mov_b32_e32 v41, v46
	v_pk_mul_f32 v[38:39], v[64:65], v[38:39] op_sel_hi:[0,1]
; DI unsigned pack2(float a, float b) { f32x2 v = {a, b}; hwbf16x2 r = __builtin_convertvector(v, hwbf16x2); return __builtin_bit_cast(unsigned, r); }
;     DI const char* a(const Unit& u) const { return (const char*)(A + (size_t)u.pm * BM * lda); }
;     DI const char* a(const Unit& u) const { return (const char*)(A + (size_t)u.pm * BM * 2048 + (u.pn >> 1) * 512); }
;     DI const char* a(const Unit& u) const { return (const char*)((u.pn < 12 ? A1 : A2) + (size_t)u.pm * BM * 512); }
; template <bool BF> DI void norm_phase(const Params& p, const void* x, const float* gain) {
;     ...
;     for (int t = bid * 8 + wid; t < T; t += 2 * step) {
;     ...
; #pragma unroll
;         for (int q = 0; q < 2; ++q) {
;             const int tt = q ? t2 : t;
;             const float rs = rsqrtf(ss[q] * (1.0f / D) + EPS);
; #pragma unroll
;             for (int i = 0; i < 4; ++i) { const int c = (i * 64 + lane) * 8;
;                 const f32x4 g0 = *(const f32x4*)(gain + c), g1 = *(const f32x4*)(gain + c + 4);
;                 const f32x4 a = v[q][2 * i] * rs * g0, d = v[q][2 * i + 1] * rs * g1;
;                 u32x4 o; o[0] = pack2(a[0], a[1]); o[1] = pack2(a[2], a[3]); o[2] = pack2(d[0], d[1]); o[3] = pack2(d[2], d[3]);
;                 *(u32x4*)(H + (size_t)tt * D + c) = o; }
	v_pk_mul_f32 v[40:41], v[64:65], v[40:41] op_sel_hi:[0,1]
	v_pk_mul_f32 v[42:43], v[64:65], v[42:43] op_sel_hi:[0,1]
	v_pk_mul_f32 v[44:45], v[64:65], v[44:45] op_sel_hi:[0,1]
	s_nop 0
	v_pk_mul_f32 v[2:3], v[2:3], v[86:87]
	v_pk_mul_f32 v[0:1], v[0:1], v[84:85]
	v_pk_mul_f32 v[6:7], v[6:7], v[90:91]
	v_pk_mul_f32 v[4:5], v[4:5], v[88:89]
	v_cvt_pk_bf16_f32 v0, v0, v1
	v_cvt_pk_bf16_f32 v1, v2, v3
	v_cvt_pk_bf16_f32 v2, v4, v5
	v_cvt_pk_bf16_f32 v3, v6, v7
	global_store_dwordx4 v[72:73], v[0:3], off offset:1024
	s_nop 1
	v_mov_b32_e32 v0, v140
	v_mov_b32_e32 v1, v141
	v_mov_b32_e32 v2, v142
	v_mov_b32_e32 v3, v143
	s_nop 0
	s_nop 1
	v_mov_b32_e32 v4, v144
	v_mov_b32_e32 v5, v145
	v_mov_b32_e32 v6, v146
	v_mov_b32_e32 v7, v147
	v_mov_b32_e32 v84, v97
	v_mov_b32_e32 v85, v99
	v_mov_b32_e32 v86, v101
	v_mov_b32_e32 v87, v103
	v_mov_b32_e32 v97, v98
	v_mov_b32_e32 v101, v102
	v_pk_mul_f32 v[84:85], v[82:83], v[84:85] op_sel_hi:[0,1]
	v_pk_mul_f32 v[86:87], v[82:83], v[86:87] op_sel_hi:[0,1]
	v_pk_mul_f32 v[88:89], v[82:83], v[96:97] op_sel_hi:[0,1]
	v_pk_mul_f32 v[90:91], v[82:83], v[100:101] op_sel_hi:[0,1]
	s_nop 0
	v_pk_mul_f32 v[2:3], v[2:3], v[86:87]
	v_pk_mul_f32 v[0:1], v[0:1], v[84:85]
	v_pk_mul_f32 v[6:7], v[6:7], v[90:91]
	v_pk_mul_f32 v[4:5], v[4:5], v[88:89]
	v_cvt_pk_bf16_f32 v0, v0, v1
	v_cvt_pk_bf16_f32 v1, v2, v3
	v_cvt_pk_bf16_f32 v2, v4, v5
	v_cvt_pk_bf16_f32 v3, v6, v7
	global_store_dwordx4 v[72:73], v[0:3], off offset:2048
	s_nop 1
	v_mov_b32_e32 v0, v148
	v_mov_b32_e32 v1, v149
	v_mov_b32_e32 v2, v150
	v_mov_b32_e32 v3, v151
	s_nop 0
	s_nop 1
	v_mov_b32_e32 v4, v152
	v_mov_b32_e32 v5, v153
	v_mov_b32_e32 v6, v154
	v_mov_b32_e32 v7, v155
	v_mov_b32_e32 v84, v105
	v_mov_b32_e32 v85, v107
	v_mov_b32_e32 v86, v109
	v_mov_b32_e32 v87, v111
	v_mov_b32_e32 v105, v106
	v_mov_b32_e32 v109, v110
	v_pk_mul_f32 v[84:85], v[82:83], v[84:85] op_sel_hi:[0,1]
	v_pk_mul_f32 v[86:87], v[82:83], v[86:87] op_sel_hi:[0,1]
	v_pk_mul_f32 v[88:89], v[82:83], v[104:105] op_sel_hi:[0,1]
	v_pk_mul_f32 v[82:83], v[82:83], v[108:109] op_sel_hi:[0,1]
	s_nop 0
	v_pk_mul_f32 v[2:3], v[2:3], v[86:87]
	v_pk_mul_f32 v[0:1], v[0:1], v[84:85]
	v_pk_mul_f32 v[6:7], v[6:7], v[82:83]
	v_pk_mul_f32 v[4:5], v[4:5], v[88:89]
	v_cvt_pk_bf16_f32 v0, v0, v1
	v_cvt_pk_bf16_f32 v1, v2, v3
	v_cvt_pk_bf16_f32 v2, v4, v5
	v_cvt_pk_bf16_f32 v3, v6, v7
	global_store_dwordx4 v[72:73], v[0:3], off offset:3072
	s_nop 1
	v_mov_b32_e32 v0, v128
	v_mov_b32_e32 v1, v129
	v_mov_b32_e32 v2, v130
	v_mov_b32_e32 v3, v131
	s_nop 0
	s_nop 1
	v_mov_b32_e32 v4, v124
	v_mov_b32_e32 v5, v125
	v_mov_b32_e32 v6, v126
	v_mov_b32_e32 v7, v127
	s_nop 0
	v_pk_mul_f32 v[2:3], v[2:3], v[58:59]
	v_pk_mul_f32 v[0:1], v[0:1], v[56:57]
	v_pk_mul_f32 v[6:7], v[6:7], v[62:63]
	v_pk_mul_f32 v[4:5], v[4:5], v[60:61]
	v_cvt_pk_bf16_f32 v0, v0, v1
	v_cvt_pk_bf16_f32 v1, v2, v3
	v_cvt_pk_bf16_f32 v2, v4, v5
	v_cvt_pk_bf16_f32 v3, v6, v7
	global_store_dwordx4 v[52:53], v[0:3], off
	s_nop 1
	v_mov_b32_e32 v0, v132
	v_mov_b32_e32 v1, v133
	v_mov_b32_e32 v2, v134
	v_mov_b32_e32 v3, v135
	s_nop 0
	s_nop 1
	v_mov_b32_e32 v4, v136
	v_mov_b32_e32 v5, v137
	v_mov_b32_e32 v6, v138
	v_mov_b32_e32 v7, v139
	s_nop 0
	v_pk_mul_f32 v[2:3], v[40:41], v[2:3]
	v_pk_mul_f32 v[0:1], v[38:39], v[0:1]
	v_pk_mul_f32 v[6:7], v[44:45], v[6:7]
	v_pk_mul_f32 v[4:5], v[42:43], v[4:5]
	v_cvt_pk_bf16_f32 v0, v0, v1
	v_cvt_pk_bf16_f32 v1, v2, v3
	v_cvt_pk_bf16_f32 v2, v4, v5
	v_cvt_pk_bf16_f32 v3, v6, v7
	global_store_dwordx4 v[52:53], v[0:3], off offset:1024
	s_nop 1
	v_mov_b32_e32 v0, v140
	v_mov_b32_e32 v1, v141
	v_mov_b32_e32 v2, v142
	v_mov_b32_e32 v3, v143
	s_nop 0
	s_nop 1
	v_mov_b32_e32 v4, v144
	v_mov_b32_e32 v5, v145
	v_mov_b32_e32 v6, v146
	v_mov_b32_e32 v7, v147
	v_mov_b32_e32 v38, v23
	v_mov_b32_e32 v39, v35
	v_mov_b32_e32 v40, v33
	v_mov_b32_e32 v41, v37
	v_mov_b32_e32 v23, v34
	v_mov_b32_e32 v33, v36
	v_pk_mul_f32 v[34:35], v[64:65], v[38:39] op_sel_hi:[0,1]
	v_pk_mul_f32 v[36:37], v[64:65], v[40:41] op_sel_hi:[0,1]
	v_pk_mul_f32 v[22:23], v[64:65], v[22:23] op_sel_hi:[0,1]
	v_pk_mul_f32 v[32:33], v[64:65], v[32:33] op_sel_hi:[0,1]
	s_nop 0
	v_pk_mul_f32 v[2:3], v[36:37], v[2:3]
	v_pk_mul_f32 v[0:1], v[34:35], v[0:1]
	v_pk_mul_f32 v[6:7], v[32:33], v[6:7]
	v_pk_mul_f32 v[4:5], v[22:23], v[4:5]
	v_cvt_pk_bf16_f32 v0, v0, v1
	v_cvt_pk_bf16_f32 v1, v2, v3
	v_cvt_pk_bf16_f32 v2, v4, v5
	v_cvt_pk_bf16_f32 v3, v6, v7
	global_store_dwordx4 v[52:53], v[0:3], off offset:2048
	s_nop 1
	v_mov_b32_e32 v0, v148
	v_mov_b32_e32 v1, v149
	v_mov_b32_e32 v2, v150
	v_mov_b32_e32 v3, v151
	s_nop 0
	s_nop 1
	v_mov_b32_e32 v4, v152
	v_mov_b32_e32 v5, v153
	v_mov_b32_e32 v6, v154
	v_mov_b32_e32 v7, v155
	v_mov_b32_e32 v32, v25
	v_mov_b32_e32 v33, v29
	v_mov_b32_e32 v34, v27
	v_mov_b32_e32 v35, v31
	v_mov_b32_e32 v25, v28
	v_mov_b32_e32 v27, v30
	v_add_u32_e32 v22, s33, v79
	v_pk_mul_f32 v[28:29], v[64:65], v[32:33] op_sel_hi:[0,1]
	v_pk_mul_f32 v[30:31], v[64:65], v[34:35] op_sel_hi:[0,1]
	v_pk_mul_f32 v[24:25], v[64:65], v[24:25] op_sel_hi:[0,1]
	v_pk_mul_f32 v[26:27], v[64:65], v[26:27] op_sel_hi:[0,1]
	v_cmp_lt_i32_e32 vcc, s4, v22
	s_or_b64 s[8:9], vcc, s[8:9]
	s_nop 0
	v_pk_mul_f32 v[2:3], v[30:31], v[2:3]
	v_pk_mul_f32 v[0:1], v[28:29], v[0:1]
	v_pk_mul_f32 v[6:7], v[26:27], v[6:7]
	v_pk_mul_f32 v[4:5], v[24:25], v[4:5]
	v_cvt_pk_bf16_f32 v0, v0, v1
	v_cvt_pk_bf16_f32 v1, v2, v3
	v_cvt_pk_bf16_f32 v2, v4, v5
	v_cvt_pk_bf16_f32 v3, v6, v7
	global_store_dwordx4 v[52:53], v[0:3], off offset:3072
	s_andn2_b64 exec, exec, s[8:9]
	s_cbranch_execnz .LBB1_621

; DI int opaque_tid() { int t = threadIdx.x; asm volatile("" : "+v"(t)); return t; }
; template <bool BF> DI void norm_phase(const Params& p, const void* x, const float* gain) {
;     ...
;     bf16_t* H = (bf16_t*)(ws + OFF_H);
;     const int tid = opaque_tid(), wid = tid >> 6, lane = tid & 63;
;     const int step = gridDim.x * 8;
;     for (int t = bid * 8 + wid; t < T; t += 2 * step) {
;     ...
;             for (int i = 0; i < 4; ++i) { const int c = (i * 64 + lane) * 8;
;                 const f32x4 g0 = *(const f32x4*)(gain + c), g1 = *(const f32x4*)(gain + c + 4);
.LBB1_994:
	s_or_b64 exec, exec, s[6:7]
	s_waitcnt lgkmcnt(0)
	s_barrier
	s_load_dwordx2 s[8:9], s[0:1], 0x88
	s_mov_b32 s2, s61
	v_mov_b32_e32 v0, v197
	s_waitcnt lgkmcnt(0)
	s_mov_b32 s10, s8
	s_mov_b32 s11, s9
	s_mov_b32 s3, s9
	s_nop 0
	v_ashrrev_i32_e32 v1, 6, v0
	v_lshl_add_u32 v22, s2, 3, v1
	s_movk_i32 s2, 0x4000
	v_cmp_gt_i32_e32 vcc, s2, v22
	s_and_saveexec_b64 s[6:7], vcc
	s_cbranch_execz .LBB1_997
	v_lshlrev_b32_e32 v0, 3, v0
	v_mbcnt_hi_u32_b32 v1, -1, v228
	v_and_b32_e32 v4, 0x1f8, v0
	v_and_b32_e32 v0, 64, v1
	v_add_u32_e32 v0, 64, v0
	v_xor_b32_e32 v2, 32, v1
	v_cmp_lt_i32_e32 vcc, v2, v0
	s_load_dwordx2 s[4:5], s[0:1], 0x18
	s_mov_b32 s9, s3
	v_cndmask_b32_e32 v2, v1, v2, vcc
	v_lshlrev_b32_e32 v21, 2, v2
	v_xor_b32_e32 v2, 16, v1
	v_cmp_lt_i32_e32 vcc, v2, v0
	s_waitcnt lgkmcnt(0)
	s_add_u32 s4, s4, 0x2000
	s_addc_u32 s5, s5, 0
	v_cndmask_b32_e32 v2, v1, v2, vcc
	v_lshlrev_b32_e32 v74, 2, v2
	v_xor_b32_e32 v2, 8, v1
	v_cmp_lt_i32_e32 vcc, v2, v0
	v_mov_b32_e32 v20, 0x358637bd
	s_mov_b32 s3, 0x800000
	v_cndmask_b32_e32 v2, v1, v2, vcc
	v_lshlrev_b32_e32 v75, 2, v2
	v_xor_b32_e32 v2, 4, v1
	v_cmp_lt_i32_e32 vcc, v2, v0
	s_nop 1
	v_cndmask_b32_e32 v2, v1, v2, vcc
	v_lshlrev_b32_e32 v76, 2, v2
	v_xor_b32_e32 v2, 2, v1
	v_cmp_lt_i32_e32 vcc, v2, v0
	s_nop 1
	v_cndmask_b32_e32 v2, v1, v2, vcc
	v_lshlrev_b32_e32 v77, 2, v2
	v_xor_b32_e32 v2, 1, v1
	v_cmp_lt_i32_e32 vcc, v2, v0
	s_nop 1
	v_cndmask_b32_e32 v0, v1, v2, vcc
	v_lshlrev_b32_e32 v78, 2, v0
	v_lshlrev_b32_e32 v0, 2, v4
	v_mov_b32_e32 v1, 0
	v_or_b32_e32 v2, 0x800, v0
	v_mov_b32_e32 v3, v1
	v_lshl_add_u64 v[8:9], s[4:5], 0, v[0:1]
	v_lshl_add_u64 v[10:11], s[4:5], 0, v[2:3]
	v_or_b32_e32 v2, 0x1000, v0
	v_or_b32_e32 v0, 0x1800, v0
	v_lshl_add_u64 v[14:15], s[4:5], 0, v[0:1]
	v_lshlrev_b32_e32 v0, 1, v4
	v_lshl_add_u64 v[12:13], s[4:5], 0, v[2:3]
	v_lshl_add_u64 v[2:3], s[10:11], 0, v[0:1]
	s_mov_b64 s[4:5], 0x4c614000
	v_lshl_add_u64 v[16:17], v[2:3], 0, s[4:5]
	v_lshl_add_u64 v[0:1], s[8:9], 0, v[0:1]
	s_mov_b64 s[4:5], 0x13310000
	v_lshl_add_u64 v[18:19], v[0:1], 0, s[4:5]
	s_mov_b64 s[8:9], 0
	s_movk_i32 s4, 0x3fff
	s_mov_b32 s10, 0x3a000000
	global_load_dwordx4 v[124:127], v[8:9], off offset:16
	global_load_dwordx4 v[128:131], v[8:9], off
	global_load_dwordx4 v[132:135], v[10:11], off
	global_load_dwordx4 v[136:139], v[10:11], off offset:16
	global_load_dwordx4 v[140:143], v[12:13], off
	global_load_dwordx4 v[144:147], v[12:13], off offset:16
	global_load_dwordx4 v[148:151], v[14:15], off
	global_load_dwordx4 v[152:155], v[14:15], off offset:16

; DI unsigned char* wsp(const Params& p) { const unsigned long long a = (unsigned long long)p.ws; unsigned lo = __builtin_amdgcn_readfirstlane((unsigned)a), hi = __builtin_amdgcn_readfirstlane((unsigned)(a >> 32)); asm volatile("" : "+s"(lo), "+s"(hi)); return (unsigned char*)(((unsigned long long)hi << 32) | lo); }
; DI float bflo(unsigned w) { return __uint_as_float(w << 16); }
; DI float bfhi(unsigned w) { return __uint_as_float(w & 0xffff0000u); }
; DI float wave_sum(float v) { for (int o = 32; o; o >>= 1) v += __shfl_xor(v, o); return v; }
; template <bool BF> DI void norm_phase(const Params& p, const void* x, const float* gain) {
;     unsigned char* const ws = wsp(p);
;     const int bid = opaque_bid();
;     bf16_t* H = (bf16_t*)(ws + OFF_H);
;     const int tid = opaque_tid(), wid = tid >> 6, lane = tid & 63;
;     const int step = gridDim.x * 8;
;     for (int t = bid * 8 + wid; t < T; t += 2 * step) {
;         const int t2 = (t + step < T) ? t + step : t;
;         f32x4 v[2][8];
; #pragma unroll
;         for (int q = 0; q < 2; ++q) {
;             const int tt = q ? t2 : t;
; #pragma unroll
;             for (int i = 0; i < 4; ++i) {
;                 const size_t e = (size_t)tt * D + (i * 64 + lane) * 8;
;                 if constexpr (BF) { const u32x4 w = *(const u32x4*)((const bf16_t*)x + e);
;                     v[q][2 * i] = (f32x4){bflo(w[0]), bfhi(w[0]), bflo(w[1]), bfhi(w[1])}; v[q][2 * i + 1] = (f32x4){bflo(w[2]), bfhi(w[2]), bflo(w[3]), bfhi(w[3])}; }
;                 else { v[q][2 * i] = *(const f32x4*)((const float*)x + e); v[q][2 * i + 1] = *(const f32x4*)((const float*)x + e + 4); }
;             }
;         }
;         float ss[2] = {0.f, 0.f};
; #pragma unroll
;         for (int q = 0; q < 2; ++q)
; #pragma unroll
;             for (int i = 0; i < 8; ++i) ss[q] += v[q][i][0] * v[q][i][0] + v[q][i][1] * v[q][i][1] + v[q][i][2] * v[q][i][2] + v[q][i][3] * v[q][i][3];
;         ss[0] = wave_sum(ss[0]); ss[1] = wave_sum(ss[1]);
; #pragma unroll
;         for (int q = 0; q < 2; ++q) {
;             const int tt = q ? t2 : t;
;             const float rs = rsqrtf(ss[q] * (1.0f / D) + EPS);
; #pragma unroll
;             for (int i = 0; i < 4; ++i) { const int c = (i * 64 + lane) * 8;
;                 const f32x4 g0 = *(const f32x4*)(gain + c), g1 = *(const f32x4*)(gain + c + 4);
.LBB1_1308:
	s_or_b64 exec, exec, s[6:7]
	s_waitcnt lgkmcnt(0)
	s_barrier
	s_load_dwordx2 s[8:9], s[0:1], 0x88
	v_mov_b32_e32 v0, v197
	s_waitcnt lgkmcnt(0)
	s_mov_b32 s2, s8
	s_mov_b32 s3, s9
	s_mov_b32 s10, s8
	s_mov_b32 s11, s9
	s_mov_b32 s3, s9
	s_mov_b32 s2, s61
	s_nop 0
	v_ashrrev_i32_e32 v1, 6, v0
	v_lshl_add_u32 v22, s2, 3, v1
	s_movk_i32 s2, 0x4000
	v_cmp_gt_i32_e32 vcc, s2, v22
	s_and_saveexec_b64 s[6:7], vcc
	s_cbranch_execz .LBB1_1311
	v_lshlrev_b32_e32 v0, 3, v0
	v_mbcnt_hi_u32_b32 v1, -1, v228
	v_and_b32_e32 v4, 0x1f8, v0
	v_and_b32_e32 v0, 64, v1
	v_add_u32_e32 v0, 64, v0
	v_xor_b32_e32 v2, 32, v1
	v_cmp_lt_i32_e32 vcc, v2, v0
	s_load_dwordx2 s[4:5], s[0:1], 0x10
	s_mov_b32 s9, s3
	v_cndmask_b32_e32 v2, v1, v2, vcc
	v_lshlrev_b32_e32 v21, 2, v2
	v_xor_b32_e32 v2, 16, v1
	v_cmp_lt_i32_e32 vcc, v2, v0
	s_waitcnt lgkmcnt(0)
	s_add_u32 s4, s4, 0x4000
	s_addc_u32 s5, s5, 0
	v_cndmask_b32_e32 v2, v1, v2, vcc
	v_lshlrev_b32_e32 v74, 2, v2
	v_xor_b32_e32 v2, 8, v1
	v_cmp_lt_i32_e32 vcc, v2, v0
	v_mov_b32_e32 v20, 0x358637bd
	s_mov_b32 s3, 0x800000
	v_cndmask_b32_e32 v2, v1, v2, vcc
	v_lshlrev_b32_e32 v75, 2, v2
	v_xor_b32_e32 v2, 4, v1
	v_cmp_lt_i32_e32 vcc, v2, v0
	s_nop 1
	v_cndmask_b32_e32 v2, v1, v2, vcc
	v_lshlrev_b32_e32 v76, 2, v2
	v_xor_b32_e32 v2, 2, v1
	v_cmp_lt_i32_e32 vcc, v2, v0
	s_nop 1
	v_cndmask_b32_e32 v2, v1, v2, vcc
	v_lshlrev_b32_e32 v77, 2, v2
	v_xor_b32_e32 v2, 1, v1
	v_cmp_lt_i32_e32 vcc, v2, v0
	s_nop 1
	v_cndmask_b32_e32 v0, v1, v2, vcc
	v_lshlrev_b32_e32 v78, 2, v0
	v_lshlrev_b32_e32 v0, 2, v4
	v_mov_b32_e32 v1, 0
	v_or_b32_e32 v2, 0x800, v0
	v_mov_b32_e32 v3, v1
	v_lshl_add_u64 v[8:9], s[4:5], 0, v[0:1]
	v_lshl_add_u64 v[10:11], s[4:5], 0, v[2:3]
	v_or_b32_e32 v2, 0x1000, v0
	v_or_b32_e32 v0, 0x1800, v0
	v_lshl_add_u64 v[14:15], s[4:5], 0, v[0:1]
	v_lshlrev_b32_e32 v0, 1, v4
	v_lshl_add_u64 v[12:13], s[4:5], 0, v[2:3]
	v_lshl_add_u64 v[2:3], s[10:11], 0, v[0:1]
	s_mov_b64 s[4:5], 0x4c614000
	v_lshl_add_u64 v[16:17], v[2:3], 0, s[4:5]
	v_lshl_add_u64 v[0:1], s[8:9], 0, v[0:1]
	s_mov_b64 s[4:5], 0x13310000
	v_lshl_add_u64 v[18:19], v[0:1], 0, s[4:5]
	s_mov_b64 s[8:9], 0
	s_movk_i32 s4, 0x3fff
	s_mov_b32 s10, 0x3a000000
	global_load_dwordx4 v[124:127], v[8:9], off offset:16
	global_load_dwordx4 v[128:131], v[8:9], off
	global_load_dwordx4 v[132:135], v[10:11], off
	global_load_dwordx4 v[136:139], v[10:11], off offset:16
	global_load_dwordx4 v[140:143], v[12:13], off
	global_load_dwordx4 v[144:147], v[12:13], off offset:16
	global_load_dwordx4 v[148:151], v[14:15], off
	global_load_dwordx4 v[152:155], v[14:15], off offset:16

; #define LAS __attribute__((address_space(3)))
; DI float xmax32(float v) { return fmaxf(v, __shfl_xor(v, 32)); }
; #define MLA_LOAD(k0) do { const char* kt_ = Kg + (size_t)(k0) * 384; const char* vt_ = Vg + (size_t)(k0) * 2; \
;                           _Pragma("unroll") for (int i = 0; i < 3; ++i) kreg[i] = *(const u32x4*)(kt_ + kgo + i * 8192); \
;                           _Pragma("unroll") for (int i = 0; i < 2; ++i) vreg[i] = *(const u32x4*)(vt_ + vgo[i]); } while (0)
; template <int NDB>
; DI void softmax_only(f32x16& sacc, float& m, float& l, f32x16 (&oacc)[NDB], bf16x8 (&pf)[2]) {
;     float mx = sacc[0];
; #pragma unroll
;     for (int i = 1; i < 16; ++i) mx = fmaxf(mx, sacc[i]);
;     mx = xmax32(mx);
; DI void mla_attn_phase(const Params& p, LAS unsigned char* lds) {
;     ...
;         for (int t = 0; t < NT; ++t) {
;             if (t + 1 < NT) MLA_LOAD((t + 1) * 64);
;             LAS unsigned char* kb = lds + (t & 1) * BUF;
; #pragma unroll
;             for (int blk = 0; blk < 2; ++blk) {
;                 bf16x8 kf[12];
;                 LAS const unsigned char* kp = kb + (blk * 32 + r) * KSTR + h * 16;
; #pragma unroll
;                 for (int ks = 0; ks < 4; ++ks) kf[ks] = *(LAS const bf16x8*)(kp + ks * 32);
;                 f32x16 sacc;
; #pragma unroll
;                 for (int i = 0; i < 16; ++i) sacc[i] = -m;
; #pragma unroll
;                 for (int kg = 0; kg < 3; ++kg) {
;                     if (kg < 2) {
; #pragma unroll
;                         for (int ks = 0; ks < 4; ++ks) kf[4 * (kg + 1) + ks] = *(LAS const bf16x8*)(kp + (4 * (kg + 1) + ks) * 32);
;                     }
; #pragma unroll
;                     for (int ks = 0; ks < 4; ++ks) sacc = __builtin_amdgcn_mfma_f32_32x32x16_bf16(kf[4 * kg + ks], qf[4 * kg + ks], sacc, 0, 0, 0);
;                 }
;                 bf16x8 vf[2][4], pf[2];
;                 load_vfrags<4, VSTR>(vf, kb + KBUF + r * VSTR + blk * 64 + h * 16);
;                 softmax_only<4>(sacc, m, l, oacc, pf);
.LBB1_1685:
	v_lshl_add_u64 v[64:65], s[40:41], 0, v[226:227]
	v_add_co_u32_e32 v66, vcc, 0x40516000, v64
	s_bitcmp1_b32 s2, 0
	s_nop 0
	v_addc_co_u32_e32 v67, vcc, 0, v65, vcc
	global_load_dwordx4 v[156:159], v[66:67], off
	v_add_co_u32_e32 v66, vcc, 0x40518000, v64
	s_cselect_b32 s3, 0xac00, 0
	s_nop 0
	v_addc_co_u32_e32 v67, vcc, 0, v65, vcc
	v_add_co_u32_e32 v64, vcc, 0x4051a000, v64
	global_load_dwordx4 v[152:155], v[66:67], off
	s_nop 0
	v_addc_co_u32_e32 v65, vcc, 0, v65, vcc
	global_load_dwordx4 v[160:163], v[64:65], off
	v_lshl_add_u64 v[64:65], s[40:41], 0, v[224:225]
	global_load_dwordx4 v[148:151], v[64:65], off
	v_lshl_add_u64 v[64:65], s[40:41], 0, v[222:223]
	s_add_i32 s3, s3, 0
	global_load_dwordx4 v[144:147], v[64:65], off
	v_add_u32_e32 v64, s3, v206
	v_add_u32_e32 v244, v64, v213
	v_xor_b32_e32 v64, 0x80000000, v221
	v_add_u32_e32 v65, s3, v207
	v_mov_b32_e32 v78, v64
	v_mov_b32_e32 v79, v64
	v_add_u32_e32 v243, v65, v206
	ds_read_b128 v[164:167], v244
	ds_read_b128 v[168:171], v244 offset:32
	ds_read_b128 v[172:175], v244 offset:64
	ds_read_b128 v[176:179], v244 offset:96
	v_mov_b32_e32 v65, v64
	v_mov_b32_e32 v66, v64
	v_mov_b32_e32 v67, v64
	v_mov_b32_e32 v68, v64
	v_mov_b32_e32 v69, v64
	v_mov_b32_e32 v70, v64
	v_mov_b32_e32 v71, v64
	v_mov_b32_e32 v72, v64
	v_mov_b32_e32 v73, v64
	v_mov_b32_e32 v74, v64
	v_mov_b32_e32 v75, v64
	v_mov_b32_e32 v76, v64
	v_mov_b32_e32 v77, v64
	v_mov_b64_e32 v[94:95], v[78:79]
	v_mov_b64_e32 v[92:93], v[76:77]
	v_mov_b64_e32 v[90:91], v[74:75]
	v_mov_b64_e32 v[88:89], v[72:73]
	v_mov_b64_e32 v[86:87], v[70:71]
	v_mov_b64_e32 v[84:85], v[68:69]
	v_mov_b64_e32 v[82:83], v[66:67]
	v_mov_b64_e32 v[80:81], v[64:65]
	ds_read_b128 v[180:183], v244 offset:128
	ds_read_b128 v[184:187], v244 offset:160
	ds_read_b128 v[188:191], v244 offset:192
	ds_read_b128 v[192:195], v244 offset:224
	s_waitcnt lgkmcnt(7)
	v_mfma_f32_32x32x16_bf16 v[80:95], v[164:167], v[140:143], v[80:95]
	ds_read_b128 v[66:69], v244 offset:256
	ds_read_b128 v[70:73], v244 offset:288
	ds_read_b128 v[74:77], v244 offset:320
	ds_read_b128 v[164:167], v244 offset:352
	s_waitcnt lgkmcnt(10)
	v_mfma_f32_32x32x16_bf16 v[80:95], v[168:171], v[136:139], v[80:95]
	s_waitcnt lgkmcnt(9)
	v_mfma_f32_32x32x16_bf16 v[80:95], v[172:175], v[132:135], v[80:95]
	s_waitcnt lgkmcnt(8)
	v_mfma_f32_32x32x16_bf16 v[80:95], v[176:179], v[128:131], v[80:95]
	s_waitcnt lgkmcnt(7)
	v_mfma_f32_32x32x16_bf16 v[80:95], v[180:183], v[124:127], v[80:95]
	s_waitcnt lgkmcnt(6)
	v_mfma_f32_32x32x16_bf16 v[80:95], v[184:187], v[120:123], v[80:95]
	s_waitcnt lgkmcnt(5)
	v_mfma_f32_32x32x16_bf16 v[80:95], v[188:191], v[116:119], v[80:95]
	s_waitcnt lgkmcnt(4)
	v_mfma_f32_32x32x16_bf16 v[80:95], v[192:195], v[112:115], v[80:95]
	s_waitcnt lgkmcnt(3)
	v_mfma_f32_32x32x16_bf16 v[80:95], v[66:69], v[108:111], v[80:95]
	s_waitcnt lgkmcnt(2)
	v_mfma_f32_32x32x16_bf16 v[80:95], v[70:73], v[104:107], v[80:95]
	s_waitcnt lgkmcnt(1)
	v_mfma_f32_32x32x16_bf16 v[80:95], v[74:77], v[100:103], v[80:95]
	s_waitcnt lgkmcnt(0)
	v_mfma_f32_32x32x16_bf16 v[80:95], v[164:167], v[96:99], v[80:95]
	ds_read_b128 v[192:195], v243 offset:25600
	ds_read_b128 v[164:167], v243 offset:25632
	ds_read_b128 v[188:191], v243 offset:30208
	ds_read_b128 v[184:187], v243 offset:34816
	ds_read_b128 v[168:171], v243 offset:39424
	ds_read_b128 v[172:175], v243 offset:30240
	ds_read_b128 v[176:179], v243 offset:34848
	ds_read_b128 v[180:183], v243 offset:39456
	s_nop 3
	v_max_f32_e32 v65, v81, v81
	v_max_f32_e32 v66, v80, v80
	v_max_f32_e32 v65, v66, v65
	v_max3_f32 v65, v65, v82, v83
	v_max3_f32 v65, v65, v84, v85
	v_max3_f32 v65, v65, v86, v87
	v_max3_f32 v65, v65, v88, v89
	v_max3_f32 v65, v65, v90, v91
	v_max3_f32 v65, v65, v92, v93
	v_max3_f32 v65, v65, v94, v95
	ds_bpermute_b32 v66, v234, v65
	s_waitcnt lgkmcnt(0)
	v_max_f32_e32 v66, v66, v66
	v_max_f32_e32 v65, v65, v66
	v_cmp_lt_f32_e32 vcc, s10, v65
	s_cbranch_vccz .LBB1_1687
	v_max_f32_e32 v64, v65, v65
	v_max_f32_e32 v64, 0, v64
	v_exp_f32_e64 v66, -v64
	v_add_f32_e32 v221, v221, v64
	v_pk_add_f32 v[80:81], v[80:81], v[64:65] op_sel_hi:[1,0] neg_lo:[0,1] neg_hi:[0,1]
	v_pk_add_f32 v[82:83], v[82:83], v[64:65] op_sel_hi:[1,0] neg_lo:[0,1] neg_hi:[0,1]
	v_mul_f32_e32 v242, v242, v66
	v_pk_add_f32 v[84:85], v[84:85], v[64:65] op_sel_hi:[1,0] neg_lo:[0,1] neg_hi:[0,1]
	v_pk_add_f32 v[86:87], v[86:87], v[64:65] op_sel_hi:[1,0] neg_lo:[0,1] neg_hi:[0,1]
	v_pk_add_f32 v[88:89], v[88:89], v[64:65] op_sel_hi:[1,0] neg_lo:[0,1] neg_hi:[0,1]
	v_pk_add_f32 v[90:91], v[90:91], v[64:65] op_sel_hi:[1,0] neg_lo:[0,1] neg_hi:[0,1]
	v_pk_add_f32 v[92:93], v[92:93], v[64:65] op_sel_hi:[1,0] neg_lo:[0,1] neg_hi:[0,1]
	v_pk_add_f32 v[94:95], v[94:95], v[64:65] op_sel_hi:[1,0] neg_lo:[0,1] neg_hi:[0,1]
	v_pk_mul_f32 v[62:63], v[62:63], v[66:67] op_sel_hi:[1,0]
	v_pk_mul_f32 v[60:61], v[60:61], v[66:67] op_sel_hi:[1,0]
	v_pk_mul_f32 v[58:59], v[58:59], v[66:67] op_sel_hi:[1,0]
	v_pk_mul_f32 v[56:57], v[56:57], v[66:67] op_sel_hi:[1,0]
	v_pk_mul_f32 v[54:55], v[54:55], v[66:67] op_sel_hi:[1,0]
	v_pk_mul_f32 v[52:53], v[52:53], v[66:67] op_sel_hi:[1,0]
	v_pk_mul_f32 v[50:51], v[50:51], v[66:67] op_sel_hi:[1,0]
	v_pk_mul_f32 v[48:49], v[48:49], v[66:67] op_sel_hi:[1,0]
	v_pk_mul_f32 v[46:47], v[46:47], v[66:67] op_sel_hi:[1,0]
	v_pk_mul_f32 v[44:45], v[44:45], v[66:67] op_sel_hi:[1,0]
	v_pk_mul_f32 v[42:43], v[42:43], v[66:67] op_sel_hi:[1,0]
	v_pk_mul_f32 v[40:41], v[40:41], v[66:67] op_sel_hi:[1,0]
	v_pk_mul_f32 v[38:39], v[38:39], v[66:67] op_sel_hi:[1,0]
	v_pk_mul_f32 v[36:37], v[36:37], v[66:67] op_sel_hi:[1,0]
	v_pk_mul_f32 v[34:35], v[34:35], v[66:67] op_sel_hi:[1,0]
	v_pk_mul_f32 v[32:33], v[32:33], v[66:67] op_sel_hi:[1,0]
	v_pk_mul_f32 v[30:31], v[30:31], v[66:67] op_sel_hi:[1,0]
	v_pk_mul_f32 v[28:29], v[28:29], v[66:67] op_sel_hi:[1,0]
	v_pk_mul_f32 v[26:27], v[26:27], v[66:67] op_sel_hi:[1,0]
	v_pk_mul_f32 v[24:25], v[24:25], v[66:67] op_sel_hi:[1,0]
	v_pk_mul_f32 v[22:23], v[22:23], v[66:67] op_sel_hi:[1,0]
	v_pk_mul_f32 v[20:21], v[20:21], v[66:67] op_sel_hi:[1,0]
	v_pk_mul_f32 v[18:19], v[18:19], v[66:67] op_sel_hi:[1,0]
	v_pk_mul_f32 v[16:17], v[16:17], v[66:67] op_sel_hi:[1,0]
	v_pk_mul_f32 v[14:15], v[14:15], v[66:67] op_sel_hi:[1,0]
	v_pk_mul_f32 v[12:13], v[12:13], v[66:67] op_sel_hi:[1,0]
	v_pk_mul_f32 v[10:11], v[10:11], v[66:67] op_sel_hi:[1,0]
	v_pk_mul_f32 v[8:9], v[8:9], v[66:67] op_sel_hi:[1,0]
	v_pk_mul_f32 v[6:7], v[6:7], v[66:67] op_sel_hi:[1,0]
	v_pk_mul_f32 v[4:5], v[4:5], v[66:67] op_sel_hi:[1,0]
	v_pk_mul_f32 v[2:3], v[2:3], v[66:67] op_sel_hi:[1,0]
	v_pk_mul_f32 v[0:1], v[0:1], v[66:67] op_sel_hi:[1,0]
	v_xor_b32_e32 v64, 0x80000000, v221
; #define LAS __attribute__((address_space(3)))
; DI unsigned pack2(float a, float b) { f32x2 v = {a, b}; hwbf16x2 r = __builtin_convertvector(v, hwbf16x2); return __builtin_bit_cast(unsigned, r); }
; DI float fast_exp2(float x) { return __builtin_amdgcn_exp2f(x); }
; template <int NDB>
; DI void softmax_only(f32x16& sacc, float& m, float& l, f32x16 (&oacc)[NDB], bf16x8 (&pf)[2]) {
;     ...
;     float pv[16], ls = 0.f;
; #pragma unroll
;     for (int i = 0; i < 16; ++i) { pv[i] = fast_exp2(sacc[i]); ls += pv[i]; }
;     l += ls;
; #pragma unroll
;     for (int s2 = 0; s2 < 2; ++s2) {
;         u32x4 pw;
; #pragma unroll
;         for (int q = 0; q < 4; ++q) pw[q] = pack2(pv[8 * s2 + 2 * q], pv[8 * s2 + 2 * q + 1]);
;         pf[s2] = __builtin_bit_cast(bf16x8, pw);
;     }
; DI void mla_attn_phase(const Params& p, LAS unsigned char* lds) {
;     ...
; #pragma unroll
;                 for (int ks = 0; ks < 4; ++ks) kf[ks] = *(LAS const bf16x8*)(kp + ks * 32);
;                 f32x16 sacc;
; #pragma unroll
;                 for (int i = 0; i < 16; ++i) sacc[i] = -m;
; #pragma unroll
;                 for (int kg = 0; kg < 3; ++kg) {
;                     if (kg < 2) {
; #pragma unroll
;                         for (int ks = 0; ks < 4; ++ks) kf[4 * (kg + 1) + ks] = *(LAS const bf16x8*)(kp + (4 * (kg + 1) + ks) * 32);
;                     }
; #pragma unroll
;                     for (int ks = 0; ks < 4; ++ks) sacc = __builtin_amdgcn_mfma_f32_32x32x16_bf16(kf[4 * kg + ks], qf[4 * kg + ks], sacc, 0, 0, 0);
;                 }
;                 bf16x8 vf[2][4], pf[2];
;                 load_vfrags<4, VSTR>(vf, kb + KBUF + r * VSTR + blk * 64 + h * 16);
;                 softmax_only<4>(sacc, m, l, oacc, pf);
; #pragma unroll
;                 for (int s2 = 0; s2 < 2; ++s2)
; #pragma unroll
;                     for (int db = 0; db < 4; ++db) oacc[db] = __builtin_amdgcn_mfma_f32_32x32x16_bf16(vf[s2][db], pf[s2], oacc[db], 0, 0, 0);
.LBB1_1687:
	v_exp_f32_e32 v80, v80
	v_exp_f32_e32 v81, v81
	v_exp_f32_e32 v82, v82
	v_exp_f32_e32 v83, v83
	v_add_f32_e32 v245, 0, v80
	v_exp_f32_e32 v84, v84
	v_add_f32_e32 v245, v245, v81
	v_exp_f32_e32 v85, v85
	v_add_f32_e32 v245, v82, v245
	v_exp_f32_e32 v86, v86
	v_exp_f32_e32 v87, v87
	v_add_f32_e32 v245, v83, v245
	v_add_f32_e32 v245, v84, v245
	v_exp_f32_e32 v88, v88
	v_add_f32_e32 v245, v85, v245
	v_exp_f32_e32 v89, v89
	v_add_f32_e32 v245, v86, v245
	v_exp_f32_e32 v90, v90
	v_cvt_pk_bf16_f32 v80, v80, v81
	v_cvt_pk_bf16_f32 v81, v82, v83
	v_cvt_pk_bf16_f32 v82, v84, v85
	v_cvt_pk_bf16_f32 v83, v86, v87
	v_add_f32_e32 v245, v87, v245
	v_exp_f32_e32 v91, v91
	v_mfma_f32_32x32x16_bf16 v[48:63], v[192:195], v[80:83], v[48:63]
	v_add_f32_e32 v245, v88, v245
	v_exp_f32_e32 v92, v92
	v_add_f32_e32 v245, v89, v245
	v_exp_f32_e32 v93, v93
	v_add_f32_e32 v245, v90, v245
	v_exp_f32_e32 v94, v94
	v_exp_f32_e32 v95, v95
	v_mfma_f32_32x32x16_bf16 v[32:47], v[188:191], v[80:83], v[32:47]
	v_add_f32_e32 v245, v91, v245
	v_add_f32_e32 v245, v92, v245
	v_add_f32_e32 v245, v93, v245
	v_mov_b32_e32 v65, v64
	v_mov_b32_e32 v66, v64
	v_mov_b32_e32 v67, v64
	v_mov_b32_e32 v68, v64
	v_mfma_f32_32x32x16_bf16 v[16:31], v[184:187], v[80:83], v[16:31]
	v_mov_b32_e32 v69, v64
	v_mov_b32_e32 v70, v64
	v_mov_b32_e32 v71, v64
	v_mov_b32_e32 v72, v64
	v_mov_b32_e32 v73, v64
	v_mov_b32_e32 v74, v64
	v_mov_b32_e32 v75, v64
	v_mfma_f32_32x32x16_bf16 v[0:15], v[168:171], v[80:83], v[0:15]
	v_mov_b32_e32 v76, v64
	v_mov_b32_e32 v77, v64
	v_mov_b32_e32 v78, v64
	v_mov_b32_e32 v79, v64
	v_add_f32_e32 v245, v94, v245
	v_cvt_pk_bf16_f32 v84, v88, v89
	v_cvt_pk_bf16_f32 v85, v90, v91
	v_cvt_pk_bf16_f32 v86, v92, v93
	v_cvt_pk_bf16_f32 v87, v94, v95
	v_add_f32_e32 v245, v95, v245
	s_nop 0
	v_mfma_f32_32x32x16_bf16 v[48:63], v[164:167], v[84:87], v[48:63]
	v_mfma_f32_32x32x16_bf16 v[32:47], v[172:175], v[84:87], v[32:47]
	v_mfma_f32_32x32x16_bf16 v[16:31], v[176:179], v[84:87], v[16:31]
	v_mfma_f32_32x32x16_bf16 v[0:15], v[180:183], v[84:87], v[0:15]
	ds_read_b128 v[80:83], v244 offset:12800
	ds_read_b128 v[84:87], v244 offset:12832
	ds_read_b128 v[88:91], v244 offset:12864
	ds_read_b128 v[92:95], v244 offset:12896
	ds_read_b128 v[164:167], v244 offset:12928
	ds_read_b128 v[168:171], v244 offset:12960
	ds_read_b128 v[172:175], v244 offset:12992
	ds_read_b128 v[176:179], v244 offset:13024
	v_add_f32_e32 v180, v242, v245
	s_waitcnt lgkmcnt(7)
	v_mfma_f32_32x32x16_bf16 v[64:79], v[80:83], v[140:143], v[64:79]
	s_waitcnt lgkmcnt(6)
	v_mfma_f32_32x32x16_bf16 v[64:79], v[84:87], v[136:139], v[64:79]
	s_waitcnt lgkmcnt(5)
	v_mfma_f32_32x32x16_bf16 v[64:79], v[88:91], v[132:135], v[64:79]
	s_waitcnt lgkmcnt(4)
	v_mfma_f32_32x32x16_bf16 v[64:79], v[92:95], v[128:131], v[64:79]
	ds_read_b128 v[80:83], v244 offset:13056
	ds_read_b128 v[84:87], v244 offset:13088
	ds_read_b128 v[88:91], v244 offset:13120
	ds_read_b128 v[92:95], v244 offset:13152
	s_waitcnt lgkmcnt(7)
	v_mfma_f32_32x32x16_bf16 v[64:79], v[164:167], v[124:127], v[64:79]
	s_waitcnt lgkmcnt(6)
	v_mfma_f32_32x32x16_bf16 v[64:79], v[168:171], v[120:123], v[64:79]
	s_waitcnt lgkmcnt(5)
	v_mfma_f32_32x32x16_bf16 v[64:79], v[172:175], v[116:119], v[64:79]
	s_waitcnt lgkmcnt(4)
	v_mfma_f32_32x32x16_bf16 v[64:79], v[176:179], v[112:115], v[64:79]
	s_waitcnt lgkmcnt(3)
	v_mfma_f32_32x32x16_bf16 v[64:79], v[80:83], v[108:111], v[64:79]
	s_waitcnt lgkmcnt(2)
	v_mfma_f32_32x32x16_bf16 v[64:79], v[84:87], v[104:107], v[64:79]
	s_waitcnt lgkmcnt(1)
	v_mfma_f32_32x32x16_bf16 v[64:79], v[88:91], v[100:103], v[64:79]
	s_waitcnt lgkmcnt(0)
	v_mfma_f32_32x32x16_bf16 v[64:79], v[92:95], v[96:99], v[64:79]
	ds_read_b128 v[176:179], v243 offset:25664
	ds_read_b128 v[92:95], v243 offset:25696
	ds_read_b128 v[172:175], v243 offset:30272
	ds_read_b128 v[168:171], v243 offset:34880
	ds_read_b128 v[164:167], v243 offset:39488
	ds_read_b128 v[80:83], v243 offset:30304
	ds_read_b128 v[84:87], v243 offset:34912
	ds_read_b128 v[88:91], v243 offset:39520
	s_nop 3
	v_max_f32_e32 v181, v65, v65
	v_max_f32_e32 v182, v64, v64
	v_max_f32_e32 v181, v182, v181
	v_max3_f32 v181, v181, v66, v67
	v_max3_f32 v181, v181, v68, v69
	v_max3_f32 v181, v181, v70, v71
	v_max3_f32 v181, v181, v72, v73
	v_max3_f32 v181, v181, v74, v75
	v_max3_f32 v181, v181, v76, v77
	v_max3_f32 v181, v181, v78, v79
	ds_bpermute_b32 v182, v234, v181
	s_waitcnt lgkmcnt(0)
	v_max_f32_e32 v182, v182, v182
	v_max_f32_e32 v181, v181, v182
	v_cmp_lt_f32_e32 vcc, s10, v181
	s_cbranch_vccz .LBB1_1684
; DI float fast_exp2(float x) { return __builtin_amdgcn_exp2f(x); }
; template <int NDB>
; DI void softmax_only(f32x16& sacc, float& m, float& l, f32x16 (&oacc)[NDB], bf16x8 (&pf)[2]) {
;     ...
;     if (__any(mx > 8.0f)) {
;         const float d = fmaxf(mx, 0.f), alpha = fast_exp2(-d);
;         l *= alpha; m += d;
; #pragma unroll
;         for (int i = 0; i < 16; ++i) sacc[i] -= d;
; #pragma unroll
;         for (int db = 0; db < NDB; ++db)
; #pragma unroll
;             for (int i = 0; i < 16; ++i) oacc[db][i] *= alpha;
;     }
	v_max_f32_e32 v181, v181, v181
	v_max_f32_e32 v182, 0, v181
	v_exp_f32_e64 v184, -v182
	v_add_f32_e32 v221, v221, v182
	v_pk_add_f32 v[64:65], v[64:65], v[182:183] op_sel_hi:[1,0] neg_lo:[0,1] neg_hi:[0,1]
	v_pk_add_f32 v[66:67], v[66:67], v[182:183] op_sel_hi:[1,0] neg_lo:[0,1] neg_hi:[0,1]
	v_mul_f32_e32 v180, v180, v184
	v_pk_add_f32 v[68:69], v[68:69], v[182:183] op_sel_hi:[1,0] neg_lo:[0,1] neg_hi:[0,1]
	v_pk_add_f32 v[70:71], v[70:71], v[182:183] op_sel_hi:[1,0] neg_lo:[0,1] neg_hi:[0,1]
	v_pk_add_f32 v[72:73], v[72:73], v[182:183] op_sel_hi:[1,0] neg_lo:[0,1] neg_hi:[0,1]
	v_pk_add_f32 v[74:75], v[74:75], v[182:183] op_sel_hi:[1,0] neg_lo:[0,1] neg_hi:[0,1]
	v_pk_add_f32 v[76:77], v[76:77], v[182:183] op_sel_hi:[1,0] neg_lo:[0,1] neg_hi:[0,1]
	v_pk_add_f32 v[78:79], v[78:79], v[182:183] op_sel_hi:[1,0] neg_lo:[0,1] neg_hi:[0,1]
	v_pk_mul_f32 v[62:63], v[62:63], v[184:185] op_sel_hi:[1,0]
	v_pk_mul_f32 v[60:61], v[60:61], v[184:185] op_sel_hi:[1,0]
	v_pk_mul_f32 v[58:59], v[58:59], v[184:185] op_sel_hi:[1,0]
	v_pk_mul_f32 v[56:57], v[56:57], v[184:185] op_sel_hi:[1,0]
	v_pk_mul_f32 v[54:55], v[54:55], v[184:185] op_sel_hi:[1,0]
	v_pk_mul_f32 v[52:53], v[52:53], v[184:185] op_sel_hi:[1,0]
	v_pk_mul_f32 v[50:51], v[50:51], v[184:185] op_sel_hi:[1,0]
	v_pk_mul_f32 v[48:49], v[48:49], v[184:185] op_sel_hi:[1,0]
	v_pk_mul_f32 v[46:47], v[46:47], v[184:185] op_sel_hi:[1,0]
	v_pk_mul_f32 v[44:45], v[44:45], v[184:185] op_sel_hi:[1,0]
	v_pk_mul_f32 v[42:43], v[42:43], v[184:185] op_sel_hi:[1,0]
	v_pk_mul_f32 v[40:41], v[40:41], v[184:185] op_sel_hi:[1,0]
	v_pk_mul_f32 v[38:39], v[38:39], v[184:185] op_sel_hi:[1,0]
	v_pk_mul_f32 v[36:37], v[36:37], v[184:185] op_sel_hi:[1,0]
	v_pk_mul_f32 v[34:35], v[34:35], v[184:185] op_sel_hi:[1,0]
	v_pk_mul_f32 v[32:33], v[32:33], v[184:185] op_sel_hi:[1,0]
	v_pk_mul_f32 v[30:31], v[30:31], v[184:185] op_sel_hi:[1,0]
	v_pk_mul_f32 v[28:29], v[28:29], v[184:185] op_sel_hi:[1,0]
	v_pk_mul_f32 v[26:27], v[26:27], v[184:185] op_sel_hi:[1,0]
	v_pk_mul_f32 v[24:25], v[24:25], v[184:185] op_sel_hi:[1,0]
	v_pk_mul_f32 v[22:23], v[22:23], v[184:185] op_sel_hi:[1,0]
	v_pk_mul_f32 v[20:21], v[20:21], v[184:185] op_sel_hi:[1,0]
	v_pk_mul_f32 v[18:19], v[18:19], v[184:185] op_sel_hi:[1,0]
	v_pk_mul_f32 v[16:17], v[16:17], v[184:185] op_sel_hi:[1,0]
	v_pk_mul_f32 v[14:15], v[14:15], v[184:185] op_sel_hi:[1,0]
	v_pk_mul_f32 v[12:13], v[12:13], v[184:185] op_sel_hi:[1,0]
	v_pk_mul_f32 v[10:11], v[10:11], v[184:185] op_sel_hi:[1,0]
	v_pk_mul_f32 v[8:9], v[8:9], v[184:185] op_sel_hi:[1,0]
	v_pk_mul_f32 v[6:7], v[6:7], v[184:185] op_sel_hi:[1,0]
	v_pk_mul_f32 v[4:5], v[4:5], v[184:185] op_sel_hi:[1,0]
	v_pk_mul_f32 v[2:3], v[2:3], v[184:185] op_sel_hi:[1,0]
	v_pk_mul_f32 v[0:1], v[0:1], v[184:185] op_sel_hi:[1,0]
	s_branch .LBB1_1684

; DI unsigned char* wsp(const Params& p) { const unsigned long long a = (unsigned long long)p.ws; unsigned lo = __builtin_amdgcn_readfirstlane((unsigned)a), hi = __builtin_amdgcn_readfirstlane((unsigned)(a >> 32)); asm volatile("" : "+s"(lo), "+s"(hi)); return (unsigned char*)(((unsigned long long)hi << 32) | lo); }
; DI float bflo(unsigned w) { return __uint_as_float(w << 16); }
; DI float bfhi(unsigned w) { return __uint_as_float(w & 0xffff0000u); }
; DI int opaque_bid() { int b = blockIdx.x; asm volatile("" : "+s"(b)); return b; }
; DI int opaque_tid() { int t = threadIdx.x; asm volatile("" : "+v"(t)); return t; }
; template <bool BF> DI void norm_phase(const Params& p, const void* x, const float* gain) {
;     unsigned char* const ws = wsp(p);
;     const int bid = opaque_bid();
;     bf16_t* H = (bf16_t*)(ws + OFF_H);
;     const int tid = opaque_tid(), wid = tid >> 6, lane = tid & 63;
;     const int step = gridDim.x * 8;
;     for (int t = bid * 8 + wid; t < T; t += 2 * step) {
;         const int t2 = (t + step < T) ? t + step : t;
;         f32x4 v[2][8];
; #pragma unroll
;         for (int q = 0; q < 2; ++q) {
;             const int tt = q ? t2 : t;
; #pragma unroll
;             for (int i = 0; i < 4; ++i) {
;                 const size_t e = (size_t)tt * D + (i * 64 + lane) * 8;
;                 if constexpr (BF) { const u32x4 w = *(const u32x4*)((const bf16_t*)x + e);
;                     v[q][2 * i] = (f32x4){bflo(w[0]), bfhi(w[0]), bflo(w[1]), bfhi(w[1])}; v[q][2 * i + 1] = (f32x4){bflo(w[2]), bfhi(w[2]), bflo(w[3]), bfhi(w[3])}; }
;                 else { v[q][2 * i] = *(const f32x4*)((const float*)x + e); v[q][2 * i + 1] = *(const f32x4*)((const float*)x + e + 4); }
;             }
;         }
;         float ss[2] = {0.f, 0.f};
; #pragma unroll
;         for (int q = 0; q < 2; ++q)
; #pragma unroll
;             for (int i = 0; i < 8; ++i) ss[q] += v[q][i][0] * v[q][i][0] + v[q][i][1] * v[q][i][1] + v[q][i][2] * v[q][i][2] + v[q][i][3] * v[q][i][3];
.LBB1_1833:
	s_or_b64 exec, exec, s[4:5]
	s_waitcnt lgkmcnt(0)
	s_barrier
	s_load_dwordx2 s[6:7], s[0:1], 0x88
	s_mov_b32 s2, s61
	v_mov_b32_e32 v0, v197
	s_waitcnt lgkmcnt(0)
	s_mov_b32 s8, s6
	s_mov_b32 s9, s7
	s_mov_b32 s3, s7
	s_nop 0
	v_ashrrev_i32_e32 v1, 6, v0
	v_lshl_add_u32 v14, s2, 3, v1
	s_movk_i32 s2, 0x4000
	v_cmp_gt_i32_e32 vcc, s2, v14
	s_and_saveexec_b64 s[4:5], vcc
	s_cbranch_execz .LBB1_1836
	v_lshlrev_b32_e32 v0, 3, v0
	v_mbcnt_hi_u32_b32 v1, -1, v228
	v_and_b32_e32 v8, 0x1f8, v0
	v_and_b32_e32 v0, 64, v1
	v_add_u32_e32 v0, 64, v0
	v_xor_b32_e32 v2, 32, v1
	v_cmp_lt_i32_e32 vcc, v2, v0
	s_load_dwordx2 s[10:11], s[0:1], 0x18
	v_lshlrev_b32_e32 v10, 2, v8
	v_cndmask_b32_e32 v2, v1, v2, vcc
	v_lshlrev_b32_e32 v13, 2, v2
	v_xor_b32_e32 v2, 16, v1
	v_cmp_lt_i32_e32 vcc, v2, v0
	s_waitcnt lgkmcnt(0)
	s_add_u32 s10, s10, 0x4000
	s_addc_u32 s11, s11, 0
	v_cndmask_b32_e32 v2, v1, v2, vcc
	v_lshlrev_b32_e32 v82, 2, v2
	v_xor_b32_e32 v2, 8, v1
	v_cmp_lt_i32_e32 vcc, v2, v0
	v_mov_b32_e32 v11, 0
	v_or_b32_e32 v4, 0x1000, v10
	v_cndmask_b32_e32 v2, v1, v2, vcc
	v_lshlrev_b32_e32 v83, 2, v2
	v_xor_b32_e32 v2, 4, v1
	v_cmp_lt_i32_e32 vcc, v2, v0
	s_mov_b32 s7, s3
	v_mov_b32_e32 v3, v11
	v_cndmask_b32_e32 v2, v1, v2, vcc
	v_lshlrev_b32_e32 v84, 2, v2
	v_xor_b32_e32 v2, 2, v1
	v_cmp_lt_i32_e32 vcc, v2, v0
	v_mov_b32_e32 v5, v11
	v_lshl_add_u64 v[4:5], s[10:11], 0, v[4:5]
	v_cndmask_b32_e32 v2, v1, v2, vcc
	v_lshlrev_b32_e32 v85, 2, v2
	v_xor_b32_e32 v2, 1, v1
	v_cmp_lt_i32_e32 vcc, v2, v0
	v_mov_b32_e32 v12, 0x358637bd
	s_mov_b32 s3, 0x800000
	v_cndmask_b32_e32 v0, v1, v2, vcc
	v_lshlrev_b32_e32 v86, 2, v0
	v_lshl_add_u64 v[0:1], s[10:11], 0, v[10:11]
	v_or_b32_e32 v2, 0x800, v10
	v_or_b32_e32 v10, 0x1800, v10
	v_lshl_add_u64 v[6:7], s[10:11], 0, v[10:11]
	v_lshlrev_b32_e32 v10, 1, v8
	v_lshl_add_u64 v[8:9], s[8:9], 0, v[10:11]
	s_mov_b64 s[8:9], 0x4c614000
	v_lshl_add_u64 v[10:11], s[6:7], 0, v[10:11]
	s_mov_b64 s[6:7], 0x13310000
	v_lshl_add_u64 v[2:3], s[10:11], 0, v[2:3]
	v_lshl_add_u64 v[8:9], v[8:9], 0, s[8:9]
	v_lshl_add_u64 v[10:11], v[10:11], 0, s[6:7]
	s_mov_b64 s[6:7], 0
	s_mov_b32 s8, 0x3a000000
	s_movk_i32 s9, 0x3fff
	global_load_dwordx4 v[124:127], v[0:1], off offset:16
	global_load_dwordx4 v[128:131], v[0:1], off
	global_load_dwordx4 v[132:135], v[2:3], off
	global_load_dwordx4 v[136:139], v[2:3], off offset:16
	global_load_dwordx4 v[140:143], v[4:5], off
	global_load_dwordx4 v[144:147], v[4:5], off offset:16
	global_load_dwordx4 v[148:151], v[6:7], off
	global_load_dwordx4 v[152:155], v[6:7], off offset:16
.LBB1_1835:
	v_add_u32_e32 v87, s33, v14
	v_cmp_gt_i32_e32 vcc, s2, v87
	v_ashrrev_i32_e32 v15, 31, v14
	s_nop 0
	s_nop 0
	v_cndmask_b32_e32 v30, v14, v87, vcc
	v_ashrrev_i32_e32 v31, 31, v30
	v_lshlrev_b64 v[14:15], 12, v[14:15]
	v_lshlrev_b64 v[36:37], 12, v[30:31]
	v_lshl_add_u64 v[26:27], v[8:9], 0, v[14:15]
	v_lshl_add_u64 v[30:31], v[8:9], 0, v[36:37]
	v_lshl_add_u64 v[60:61], v[10:11], 0, v[14:15]
	global_load_dwordx4 v[14:17], v[26:27], off offset:2048
	global_load_dwordx4 v[18:21], v[26:27], off offset:3072
	global_load_dwordx4 v[22:25], v[26:27], off
	s_nop 0
	global_load_dwordx4 v[26:29], v[26:27], off offset:1024
	s_nop 0
	global_load_dwordx4 v[96:99], v[30:31], off offset:2048
	global_load_dwordx4 v[100:103], v[30:31], off
	global_load_dwordx4 v[104:107], v[30:31], off offset:1024
	global_load_dwordx4 v[108:111], v[30:31], off offset:3072
	v_lshl_add_u64 v[36:37], v[10:11], 0, v[36:37]
	s_waitcnt vmcnt(0) lgkmcnt(0)
	s_nop 1
	v_mov_b32_e32 v88, v124
	v_mov_b32_e32 v89, v125
	v_mov_b32_e32 v90, v126
	v_mov_b32_e32 v91, v127
	s_nop 1
	v_mov_b32_e32 v92, v128
	v_mov_b32_e32 v93, v129
	v_mov_b32_e32 v94, v130
	v_mov_b32_e32 v95, v131
	v_and_b32_e32 v79, 0xffff0000, v14
	v_and_b32_e32 v78, 0xffff0000, v16
	v_and_b32_e32 v71, 0xffff0000, v18
	v_and_b32_e32 v70, 0xffff0000, v20
	v_and_b32_e32 v49, 0xffff0000, v22
	v_and_b32_e32 v53, 0xffff0000, v24
	v_and_b32_e32 v48, 0xffff0000, v100
	v_and_b32_e32 v52, 0xffff0000, v102
	v_lshlrev_b32_e32 v75, 16, v14
	v_lshlrev_b32_e32 v74, 16, v16
	v_lshlrev_b32_e32 v77, 16, v15
	v_and_b32_e32 v81, 0xffff0000, v15
	v_lshlrev_b32_e32 v67, 16, v18
	v_lshlrev_b32_e32 v66, 16, v20
	v_lshlrev_b32_e32 v68, 16, v21
	v_and_b32_e32 v72, 0xffff0000, v21
	v_lshlrev_b32_e32 v41, 16, v22
	v_lshlrev_b32_e32 v45, 16, v24
	v_lshlrev_b32_e32 v47, 16, v25
	v_and_b32_e32 v55, 0xffff0000, v25
	v_lshlrev_b32_e32 v15, 16, v26
	v_and_b32_e32 v39, 0xffff0000, v26
	v_pk_mul_f32 v[20:21], v[78:79], v[78:79]
	v_pk_mul_f32 v[24:25], v[70:71], v[70:71]
	v_and_b32_e32 v63, 0xffff0000, v96
	v_and_b32_e32 v62, 0xffff0000, v98
	v_lshlrev_b32_e32 v40, 16, v100
	v_lshlrev_b32_e32 v44, 16, v102
	v_lshlrev_b32_e32 v46, 16, v103
	v_and_b32_e32 v54, 0xffff0000, v103
	v_lshlrev_b32_e32 v14, 16, v104
	v_and_b32_e32 v38, 0xffff0000, v104
	v_lshlrev_b32_e32 v16, 16, v105
	v_and_b32_e32 v26, 0xffff0000, v105
	v_and_b32_e32 v31, 0xffff0000, v108
	v_and_b32_e32 v30, 0xffff0000, v110
	v_pk_mul_f32 v[102:103], v[48:49], v[48:49]
	v_pk_mul_f32 v[104:105], v[52:53], v[52:53]
	v_lshlrev_b32_e32 v69, 16, v19
	v_and_b32_e32 v73, 0xffff0000, v19
	v_lshlrev_b32_e32 v43, 16, v23
	v_lshlrev_b32_e32 v19, 16, v28
	v_and_b32_e32 v33, 0xffff0000, v28
	v_pk_fma_f32 v[120:121], v[74:75], v[74:75], v[20:21]
	v_pk_fma_f32 v[122:123], v[66:67], v[66:67], v[24:25]
	v_lshlrev_b32_e32 v57, 16, v96
	v_lshlrev_b32_e32 v56, 16, v98
	v_lshlrev_b32_e32 v42, 16, v101
	v_and_b32_e32 v50, 0xffff0000, v101
	v_lshlrev_b32_e32 v18, 16, v106
	v_and_b32_e32 v32, 0xffff0000, v106
	v_lshlrev_b32_e32 v22, 16, v107
	v_and_b32_e32 v28, 0xffff0000, v107
; DI unsigned pack2(float a, float b) { f32x2 v = {a, b}; hwbf16x2 r = __builtin_convertvector(v, hwbf16x2); return __builtin_bit_cast(unsigned, r); }
; DI float wave_sum(float v) { for (int o = 32; o; o >>= 1) v += __shfl_xor(v, o); return v; }
;     DI const char* a(const Unit& u) const { return (const char*)(A + (size_t)u.pm * BM * lda); }
;     DI const char* a(const Unit& u) const { return (const char*)(A + (size_t)u.pm * BM * 2048 + (u.pn >> 1) * 512); }
;     DI const char* a(const Unit& u) const { return (const char*)((u.pn < 12 ? A1 : A2) + (size_t)u.pm * BM * 512); }
; template <bool BF> DI void norm_phase(const Params& p, const void* x, const float* gain) {
;     ...
;         float ss[2] = {0.f, 0.f};
; #pragma unroll
;         for (int q = 0; q < 2; ++q)
; #pragma unroll
;             for (int i = 0; i < 8; ++i) ss[q] += v[q][i][0] * v[q][i][0] + v[q][i][1] * v[q][i][1] + v[q][i][2] * v[q][i][2] + v[q][i][3] * v[q][i][3];
;         ss[0] = wave_sum(ss[0]); ss[1] = wave_sum(ss[1]);
; #pragma unroll
;         for (int q = 0; q < 2; ++q) {
;             const int tt = q ? t2 : t;
;             const float rs = rsqrtf(ss[q] * (1.0f / D) + EPS);
; #pragma unroll
;             for (int i = 0; i < 4; ++i) { const int c = (i * 64 + lane) * 8;
;                 const f32x4 g0 = *(const f32x4*)(gain + c), g1 = *(const f32x4*)(gain + c + 4);
;                 const f32x4 a = v[q][2 * i] * rs * g0, d = v[q][2 * i + 1] * rs * g1;
;                 u32x4 o; o[0] = pack2(a[0], a[1]); o[1] = pack2(a[2], a[3]); o[2] = pack2(d[0], d[1]); o[3] = pack2(d[2], d[3]);
;                 *(u32x4*)(H + (size_t)tt * D + c) = o; }
	v_lshlrev_b32_e32 v21, 16, v108
	v_lshlrev_b32_e32 v20, 16, v110
	v_lshlrev_b32_e32 v24, 16, v111
	v_and_b32_e32 v34, 0xffff0000, v111
	v_pk_mul_f32 v[100:101], v[62:63], v[62:63]
	v_pk_mul_f32 v[106:107], v[38:39], v[38:39]
	v_pk_mul_f32 v[110:111], v[30:31], v[30:31]
	v_pk_fma_f32 v[102:103], v[40:41], v[40:41], v[102:103]
	v_pk_fma_f32 v[104:105], v[44:45], v[44:45], v[104:105]
	v_lshlrev_b32_e32 v76, 16, v17
	v_and_b32_e32 v80, 0xffff0000, v17
	v_and_b32_e32 v51, 0xffff0000, v23
	v_lshlrev_b32_e32 v17, 16, v27
	v_lshlrev_b32_e32 v59, 16, v97
	v_lshlrev_b32_e32 v58, 16, v99
	v_lshlrev_b32_e32 v25, 16, v109
	v_and_b32_e32 v35, 0xffff0000, v109
	v_pk_mul_f32 v[108:109], v[32:33], v[32:33]
	v_pk_fma_f32 v[100:101], v[56:57], v[56:57], v[100:101]
	v_pk_fma_f32 v[106:107], v[14:15], v[14:15], v[106:107]
	v_pk_fma_f32 v[110:111], v[20:21], v[20:21], v[110:111]
	v_pk_fma_f32 v[102:103], v[42:43], v[42:43], v[102:103]
	v_pk_fma_f32 v[104:105], v[46:47], v[46:47], v[104:105]
	v_and_b32_e32 v27, 0xffff0000, v27
	v_lshlrev_b32_e32 v23, 16, v29
	v_and_b32_e32 v65, 0xffff0000, v97
	v_and_b32_e32 v64, 0xffff0000, v99
	v_pk_fma_f32 v[96:97], v[76:77], v[76:77], v[120:121]
	v_pk_fma_f32 v[98:99], v[68:69], v[68:69], v[122:123]
	v_pk_fma_f32 v[108:109], v[18:19], v[18:19], v[108:109]
	v_pk_fma_f32 v[100:101], v[58:59], v[58:59], v[100:101]
	v_pk_fma_f32 v[106:107], v[16:17], v[16:17], v[106:107]
	v_pk_fma_f32 v[110:111], v[24:25], v[24:25], v[110:111]
	v_pk_fma_f32 v[102:103], v[50:51], v[50:51], v[102:103]
	v_pk_fma_f32 v[104:105], v[54:55], v[54:55], v[104:105]
	v_and_b32_e32 v29, 0xffff0000, v29
	v_pk_fma_f32 v[96:97], v[80:81], v[80:81], v[96:97]
	v_pk_fma_f32 v[98:99], v[72:73], v[72:73], v[98:99]
	v_pk_fma_f32 v[108:109], v[22:23], v[22:23], v[108:109]
	v_pk_fma_f32 v[100:101], v[64:65], v[64:65], v[100:101]
	v_pk_fma_f32 v[106:107], v[26:27], v[26:27], v[106:107]
	v_pk_fma_f32 v[110:111], v[34:35], v[34:35], v[110:111]
	v_pk_add_f32 v[102:103], v[102:103], v[104:105]
	v_mov_b32_e32 v121, v97
	v_mov_b32_e32 v97, v99
	v_pk_fma_f32 v[108:109], v[28:29], v[28:29], v[108:109]
	v_mov_b32_e32 v120, v101
	v_mov_b32_e32 v101, v96
	v_mov_b32_e32 v96, v111
	v_mov_b32_e32 v111, v98
	v_pk_add_f32 v[98:99], v[102:103], v[106:107]
	v_mov_b32_e32 v112, v41
	v_pk_add_f32 v[98:99], v[108:109], v[98:99]
	v_mov_b32_e32 v114, v43
	v_pk_add_f32 v[98:99], v[120:121], v[98:99]
	v_mov_b32_e32 v113, v49
	v_pk_add_f32 v[98:99], v[100:101], v[98:99]
	v_mov_b32_e32 v115, v51
	v_pk_add_f32 v[96:97], v[96:97], v[98:99]
	v_mov_b32_e32 v116, v45
	v_pk_add_f32 v[96:97], v[110:111], v[96:97]
	ds_bpermute_b32 v99, v13, v97
	ds_bpermute_b32 v98, v13, v96
	v_mov_b32_e32 v117, v53
	v_mov_b32_e32 v118, v47
	v_mov_b32_e32 v119, v55
	v_mov_b32_e32 v45, v52
	s_waitcnt lgkmcnt(0)
	v_pk_add_f32 v[96:97], v[96:97], v[98:99]
	ds_bpermute_b32 v99, v82, v97
	ds_bpermute_b32 v98, v82, v96
	v_mov_b32_e32 v47, v54
	s_waitcnt lgkmcnt(0)
	v_pk_add_f32 v[96:97], v[96:97], v[98:99]
	ds_bpermute_b32 v99, v83, v97
	ds_bpermute_b32 v98, v83, v96
	s_waitcnt lgkmcnt(0)
	v_pk_add_f32 v[96:97], v[96:97], v[98:99]
	ds_bpermute_b32 v99, v84, v97
	ds_bpermute_b32 v98, v84, v96
	s_waitcnt lgkmcnt(0)
	v_pk_add_f32 v[96:97], v[96:97], v[98:99]
	ds_bpermute_b32 v99, v85, v97
	ds_bpermute_b32 v98, v85, v96
	s_waitcnt lgkmcnt(0)
	v_pk_add_f32 v[96:97], v[96:97], v[98:99]
	ds_bpermute_b32 v99, v86, v97
	ds_bpermute_b32 v98, v86, v96
	s_waitcnt lgkmcnt(0)
	v_pk_add_f32 v[96:97], v[96:97], v[98:99]
	s_nop 0
	v_pk_fma_f32 v[96:97], v[96:97], s[8:9], v[12:13] op_sel_hi:[1,0,0]
	s_nop 0
	v_mul_f32_e32 v41, 0x4b800000, v97
	v_cmp_gt_f32_e32 vcc, s3, v97
	s_nop 1
	v_cndmask_b32_e32 v41, v97, v41, vcc
	v_rsq_f32_e32 v41, v41
	s_nop 0
	v_mul_f32_e32 v43, 0x45800000, v41
	v_cndmask_b32_e32 v98, v41, v43, vcc
	v_pk_mul_f32 v[100:101], v[98:99], v[112:113] op_sel_hi:[0,1]
	v_pk_mul_f32 v[102:103], v[98:99], v[114:115] op_sel_hi:[0,1]
	v_pk_mul_f32 v[104:105], v[98:99], v[116:117] op_sel_hi:[0,1]
	v_pk_mul_f32 v[106:107], v[98:99], v[118:119] op_sel_hi:[0,1]
	v_pk_mul_f32 v[94:95], v[94:95], v[102:103]
	v_pk_mul_f32 v[92:93], v[92:93], v[100:101]
	v_pk_mul_f32 v[100:101], v[90:91], v[106:107]
	v_pk_mul_f32 v[90:91], v[88:89], v[104:105]
	v_cvt_pk_bf16_f32 v88, v92, v93
	v_cvt_pk_bf16_f32 v89, v94, v95
	v_cvt_pk_bf16_f32 v90, v90, v91
	v_cvt_pk_bf16_f32 v91, v100, v101
	global_store_dwordx4 v[60:61], v[88:91], off
	s_nop 1
	v_mov_b32_e32 v88, v132
	v_mov_b32_e32 v89, v133
	v_mov_b32_e32 v90, v134
	v_mov_b32_e32 v91, v135
	s_nop 0
	s_nop 1
	v_mov_b32_e32 v92, v136
	v_mov_b32_e32 v93, v137
	v_mov_b32_e32 v94, v138
	v_mov_b32_e32 v95, v139
	v_mov_b32_e32 v100, v15
	v_mov_b32_e32 v101, v39
	v_mov_b32_e32 v102, v17
	v_mov_b32_e32 v103, v27
	v_mov_b32_e32 v104, v19
	v_mov_b32_e32 v105, v33
	v_mov_b32_e32 v106, v23
	v_mov_b32_e32 v107, v29
	v_pk_mul_f32 v[100:101], v[98:99], v[100:101] op_sel_hi:[0,1]
	v_pk_mul_f32 v[102:103], v[98:99], v[102:103] op_sel_hi:[0,1]
	v_pk_mul_f32 v[104:105], v[98:99], v[104:105] op_sel_hi:[0,1]
	v_pk_mul_f32 v[106:107], v[98:99], v[106:107] op_sel_hi:[0,1]
	v_mul_f32_e32 v15, 0x4b800000, v96
	v_cmp_gt_f32_e32 vcc, s3, v96
	v_mov_b32_e32 v41, v48
	v_mov_b32_e32 v43, v50
	v_cndmask_b32_e32 v15, v96, v15, vcc
	v_rsq_f32_e32 v15, v15
	v_mov_b32_e32 v19, v32
	v_mov_b32_e32 v23, v28
	v_mul_f32_e32 v17, 0x45800000, v15
	v_cndmask_b32_e32 v48, v15, v17, vcc
	v_pk_mul_f32 v[40:41], v[48:49], v[40:41] op_sel_hi:[0,1]
	v_pk_mul_f32 v[42:43], v[48:49], v[42:43] op_sel_hi:[0,1]
	v_pk_mul_f32 v[44:45], v[48:49], v[44:45] op_sel_hi:[0,1]
	v_pk_mul_f32 v[46:47], v[48:49], v[46:47] op_sel_hi:[0,1]
	v_mov_b32_e32 v15, v38
; DI unsigned pack2(float a, float b) { f32x2 v = {a, b}; hwbf16x2 r = __builtin_convertvector(v, hwbf16x2); return __builtin_bit_cast(unsigned, r); }
;     DI const char* a(const Unit& u) const { return (const char*)(A + (size_t)u.pm * BM * lda); }
;     DI const char* a(const Unit& u) const { return (const char*)(A + (size_t)u.pm * BM * 2048 + (u.pn >> 1) * 512); }
;     DI const char* a(const Unit& u) const { return (const char*)((u.pn < 12 ? A1 : A2) + (size_t)u.pm * BM * 512); }
; template <bool BF> DI void norm_phase(const Params& p, const void* x, const float* gain) {
;     ...
;         for (int q = 0; q < 2; ++q) {
;             const int tt = q ? t2 : t;
;             const float rs = rsqrtf(ss[q] * (1.0f / D) + EPS);
; #pragma unroll
;             for (int i = 0; i < 4; ++i) { const int c = (i * 64 + lane) * 8;
;                 const f32x4 g0 = *(const f32x4*)(gain + c), g1 = *(const f32x4*)(gain + c + 4);
;                 const f32x4 a = v[q][2 * i] * rs * g0, d = v[q][2 * i + 1] * rs * g1;
;                 u32x4 o; o[0] = pack2(a[0], a[1]); o[1] = pack2(a[2], a[3]); o[2] = pack2(d[0], d[1]); o[3] = pack2(d[2], d[3]);
;                 *(u32x4*)(H + (size_t)tt * D + c) = o; }
	v_mov_b32_e32 v17, v26
	v_pk_mul_f32 v[14:15], v[48:49], v[14:15] op_sel_hi:[0,1]
	v_pk_mul_f32 v[16:17], v[48:49], v[16:17] op_sel_hi:[0,1]
	v_pk_mul_f32 v[18:19], v[48:49], v[18:19] op_sel_hi:[0,1]
	v_pk_mul_f32 v[22:23], v[48:49], v[22:23] op_sel_hi:[0,1]
	s_nop 0
	v_pk_mul_f32 v[90:91], v[90:91], v[102:103]
	v_pk_mul_f32 v[88:89], v[88:89], v[100:101]
	v_pk_mul_f32 v[94:95], v[94:95], v[106:107]
	v_pk_mul_f32 v[92:93], v[92:93], v[104:105]
	v_cvt_pk_bf16_f32 v88, v88, v89
	v_cvt_pk_bf16_f32 v89, v90, v91
	v_cvt_pk_bf16_f32 v90, v92, v93
	v_cvt_pk_bf16_f32 v91, v94, v95
	global_store_dwordx4 v[60:61], v[88:91], off offset:1024
	s_nop 1
	v_mov_b32_e32 v88, v140
	v_mov_b32_e32 v89, v141
	v_mov_b32_e32 v90, v142
	v_mov_b32_e32 v91, v143
	s_nop 0
	s_nop 1
	v_mov_b32_e32 v92, v144
	v_mov_b32_e32 v93, v145
	v_mov_b32_e32 v94, v146
	v_mov_b32_e32 v95, v147
	v_mov_b32_e32 v100, v75
	v_mov_b32_e32 v101, v79
	v_mov_b32_e32 v102, v77
	v_mov_b32_e32 v103, v81
	v_mov_b32_e32 v75, v78
	v_mov_b32_e32 v77, v80
	v_pk_mul_f32 v[78:79], v[98:99], v[100:101] op_sel_hi:[0,1]
	v_pk_mul_f32 v[80:81], v[98:99], v[102:103] op_sel_hi:[0,1]
	v_pk_mul_f32 v[74:75], v[98:99], v[74:75] op_sel_hi:[0,1]
	v_pk_mul_f32 v[76:77], v[98:99], v[76:77] op_sel_hi:[0,1]
	s_nop 0
	v_pk_mul_f32 v[80:81], v[90:91], v[80:81]
	v_pk_mul_f32 v[78:79], v[88:89], v[78:79]
	v_pk_mul_f32 v[88:89], v[94:95], v[76:77]
	v_pk_mul_f32 v[76:77], v[92:93], v[74:75]
	v_cvt_pk_bf16_f32 v74, v78, v79
	v_cvt_pk_bf16_f32 v75, v80, v81
	v_cvt_pk_bf16_f32 v76, v76, v77
	v_cvt_pk_bf16_f32 v77, v88, v89
	global_store_dwordx4 v[60:61], v[74:77], off offset:2048
	s_nop 1
	v_mov_b32_e32 v74, v148
	v_mov_b32_e32 v75, v149
	v_mov_b32_e32 v76, v150
	v_mov_b32_e32 v77, v151
	s_nop 0
	s_nop 1
	v_mov_b32_e32 v78, v152
	v_mov_b32_e32 v79, v153
	v_mov_b32_e32 v80, v154
	v_mov_b32_e32 v81, v155
	v_mov_b32_e32 v88, v67
	v_mov_b32_e32 v89, v71
	v_mov_b32_e32 v90, v69
	v_mov_b32_e32 v91, v73
	v_mov_b32_e32 v67, v70
	v_mov_b32_e32 v69, v72
	v_pk_mul_f32 v[70:71], v[98:99], v[88:89] op_sel_hi:[0,1]
	v_pk_mul_f32 v[72:73], v[98:99], v[90:91] op_sel_hi:[0,1]
	v_pk_mul_f32 v[66:67], v[98:99], v[66:67] op_sel_hi:[0,1]
	v_pk_mul_f32 v[68:69], v[98:99], v[68:69] op_sel_hi:[0,1]
	s_nop 0
	v_pk_mul_f32 v[72:73], v[76:77], v[72:73]
	v_pk_mul_f32 v[70:71], v[74:75], v[70:71]
	v_pk_mul_f32 v[74:75], v[80:81], v[68:69]
	v_pk_mul_f32 v[68:69], v[78:79], v[66:67]
	v_cvt_pk_bf16_f32 v66, v70, v71
	v_cvt_pk_bf16_f32 v67, v72, v73
	v_cvt_pk_bf16_f32 v68, v68, v69
	v_cvt_pk_bf16_f32 v69, v74, v75
	global_store_dwordx4 v[60:61], v[66:69], off offset:3072
	s_nop 1
	v_mov_b32_e32 v66, v128
	v_mov_b32_e32 v67, v129
	v_mov_b32_e32 v68, v130
	v_mov_b32_e32 v69, v131
	s_nop 0
	s_nop 1
	v_mov_b32_e32 v70, v124
	v_mov_b32_e32 v71, v125
	v_mov_b32_e32 v72, v126
	v_mov_b32_e32 v73, v127
	s_nop 0
	v_pk_mul_f32 v[42:43], v[68:69], v[42:43]
	v_pk_mul_f32 v[40:41], v[66:67], v[40:41]
	v_pk_mul_f32 v[46:47], v[72:73], v[46:47]
	v_pk_mul_f32 v[44:45], v[70:71], v[44:45]
	v_cvt_pk_bf16_f32 v40, v40, v41
	v_cvt_pk_bf16_f32 v41, v42, v43
	v_cvt_pk_bf16_f32 v42, v44, v45
	v_cvt_pk_bf16_f32 v43, v46, v47
	global_store_dwordx4 v[36:37], v[40:43], off
	s_nop 1
	v_mov_b32_e32 v40, v132
	v_mov_b32_e32 v41, v133
	v_mov_b32_e32 v42, v134
	v_mov_b32_e32 v43, v135
	s_nop 0
	s_nop 1
	v_mov_b32_e32 v44, v136
	v_mov_b32_e32 v45, v137
	v_mov_b32_e32 v46, v138
	v_mov_b32_e32 v47, v139
	s_nop 0
	v_pk_mul_f32 v[16:17], v[16:17], v[42:43]
	v_pk_mul_f32 v[14:15], v[14:15], v[40:41]
	v_pk_mul_f32 v[22:23], v[22:23], v[46:47]
	v_pk_mul_f32 v[18:19], v[18:19], v[44:45]
	v_cvt_pk_bf16_f32 v14, v14, v15
	v_cvt_pk_bf16_f32 v15, v16, v17
	v_cvt_pk_bf16_f32 v16, v18, v19
	v_cvt_pk_bf16_f32 v17, v22, v23
	global_store_dwordx4 v[36:37], v[14:17], off offset:1024
	s_nop 1
	v_mov_b32_e32 v14, v140
	v_mov_b32_e32 v15, v141
	v_mov_b32_e32 v16, v142
	v_mov_b32_e32 v17, v143
	s_nop 0
	s_nop 1
	v_mov_b32_e32 v26, v144
	v_mov_b32_e32 v27, v145
	v_mov_b32_e32 v28, v146
	v_mov_b32_e32 v29, v147
	v_mov_b32_e32 v18, v57
	v_mov_b32_e32 v19, v63
	v_mov_b32_e32 v22, v59
	v_mov_b32_e32 v23, v65
	v_mov_b32_e32 v57, v62
	v_mov_b32_e32 v59, v64
	v_pk_mul_f32 v[18:19], v[48:49], v[18:19] op_sel_hi:[0,1]
	v_pk_mul_f32 v[22:23], v[48:49], v[22:23] op_sel_hi:[0,1]
	v_pk_mul_f32 v[32:33], v[48:49], v[56:57] op_sel_hi:[0,1]
	v_pk_mul_f32 v[38:39], v[48:49], v[58:59] op_sel_hi:[0,1]
	s_nop 0
	v_pk_mul_f32 v[16:17], v[22:23], v[16:17]
	v_pk_mul_f32 v[14:15], v[18:19], v[14:15]
	v_pk_mul_f32 v[18:19], v[38:39], v[28:29]
	v_pk_mul_f32 v[22:23], v[32:33], v[26:27]
	v_cvt_pk_bf16_f32 v14, v14, v15
	v_cvt_pk_bf16_f32 v15, v16, v17
	v_cvt_pk_bf16_f32 v16, v22, v23
	v_cvt_pk_bf16_f32 v17, v18, v19
	global_store_dwordx4 v[36:37], v[14:17], off offset:2048
	s_nop 1
	v_mov_b32_e32 v16, v148
	v_mov_b32_e32 v17, v149
	v_mov_b32_e32 v18, v150
	v_mov_b32_e32 v19, v151
	s_nop 0
	s_nop 1
	v_mov_b32_e32 v26, v152
	v_mov_b32_e32 v27, v153
	v_mov_b32_e32 v28, v154
	v_mov_b32_e32 v29, v155
	v_mov_b32_e32 v22, v21
	v_mov_b32_e32 v23, v31
	v_mov_b32_e32 v32, v25
	v_mov_b32_e32 v33, v35
	v_mov_b32_e32 v21, v30
	v_mov_b32_e32 v25, v34
	v_add_u32_e32 v14, s33, v87
	v_pk_mul_f32 v[22:23], v[48:49], v[22:23] op_sel_hi:[0,1]
	v_pk_mul_f32 v[30:31], v[48:49], v[32:33] op_sel_hi:[0,1]
	v_pk_mul_f32 v[20:21], v[48:49], v[20:21] op_sel_hi:[0,1]
	v_pk_mul_f32 v[24:25], v[48:49], v[24:25] op_sel_hi:[0,1]
	v_cmp_lt_i32_e32 vcc, s9, v14
	s_or_b64 s[6:7], vcc, s[6:7]
	s_nop 0
	v_pk_mul_f32 v[18:19], v[30:31], v[18:19]
	v_pk_mul_f32 v[16:17], v[22:23], v[16:17]
	v_pk_mul_f32 v[22:23], v[24:25], v[28:29]
	v_pk_mul_f32 v[20:21], v[20:21], v[26:27]
	v_cvt_pk_bf16_f32 v16, v16, v17
	v_cvt_pk_bf16_f32 v17, v18, v19
	v_cvt_pk_bf16_f32 v18, v20, v21
	v_cvt_pk_bf16_f32 v19, v22, v23
	global_store_dwordx4 v[36:37], v[16:19], off offset:3072
	s_andn2_b64 exec, exec, s[6:7]
	s_cbranch_execnz .LBB1_1835

; #define PG8_STAGE(bufoff, gbase, voff) do { _Pragma("unroll") for (int _i = 0; _i < 2; ++_i) \
;         __builtin_amdgcn_global_load_lds((const unsigned*)((const char*)(gbase) + (voff)[_i]), (LAS unsigned*)(lds + (bufoff) + ldsw + _i * 8192), 16, 0, 0); } while (0)
; #define PG8_LDA(dst, b, h) do { _Pragma("unroll") for (int m = 0; m < 4; ++m) _Pragma("unroll") for (int k = 0; k < 2; ++k) dst[m][k] = *(const LAS bf16x8*)(lds + PG8_SA(b, h) + aoff + m * 2048 + k * 1024); } while (0)
; #define PG8_LDB(dst, b, h) do { _Pragma("unroll") for (int n = 0; n < 2; ++n) _Pragma("unroll") for (int k = 0; k < 2; ++k) dst[n][k] = *(const LAS bf16x8*)(lds + PG8_SB(b, h) + boff + n * 2048 + k * 1024); } while (0)
; #define PG8_MMA(ai, bj, At, Bt) do { __builtin_amdgcn_s_setprio(1); _Pragma("unroll") for (int m = 0; m < 4; ++m) _Pragma("unroll") for (int n = 0; n < 2; ++n) _Pragma("unroll") for (int k = 0; k < 2; ++k) \
;         acc[ai][bj][m][n] = __builtin_amdgcn_mfma_f32_16x16x32_bf16(Bt[n][k], At[m][k], acc[ai][bj][m][n], 0, 0, 0); __builtin_amdgcn_s_setprio(0); } while (0)
; #define PG8_WAIT_L(n) asm volatile("s_waitcnt lgkmcnt(" #n ")" ::: "memory")
; #define PG8_BAR __builtin_amdgcn_s_barrier()
; #define PG8_SCHED __builtin_amdgcn_sched_barrier(0)
; template <class Map, class Epi>
; DI void gemm_phase(LAS unsigned char* lds, const Map& MP, const Epi& E, const int nM, const int nN, const int K, const int lda, const int ldb) {
;     ...
;         for (int t = 0; t < nt; t += 2) {
;             const bool last = (t == nt - 2);
;             const char* a1 = cA + (size_t)(t + 1) * kstep;
;             const char* a2 = last ? nA : cA + (size_t)(t + 2) * kstep; const char* b2 = last ? nB : cB + (size_t)(t + 2) * kstep;
;             const char* a3 = a2 + kstep; const char* b3 = b2 + kstep;
;             PG8_LDB(B0, 0, 0); PG8_SCHED; PG8_LDA(At, 0, 0); PG8_STAGE(PG8_SA(1, 1), a1 + hstepA, voffA);
;             PG8_WAIT_L(8); PG8_BAR; PG8_WAIT_L(0); PG8_MMA(0, 0, At, B0); PG8_BAR; PG8_SCHED;
;             PG8_LDB(B1, 0, 1); PG8_STAGE(PG8_SB(0, 0), b2, voffB);
;             PG8_BAR; PG8_WAIT_L(0); PG8_MMA(0, 1, At, B1); PG8_BAR;
;             PG8_LDA(At, 0, 1); PG8_STAGE(PG8_SA(0, 0), a2, voffA);
;             PG8_BAR; PG8_WAIT_L(0); PG8_MMA(1, 0, At, B0); PG8_BAR; PG8_SCHED;
.LBB1_2339:
	ds_read_b128 v[40:43], v165
	ds_read_b128 v[44:47], v165 offset:1024
	ds_read_b128 v[56:59], v165 offset:2048
	ds_read_b128 v[60:63], v165 offset:3072
	s_add_u32 s12, s10, 0xfff80080
	s_addc_u32 s13, s11, -1
	s_cmp_eq_u32 s3, 4
	s_cselect_b32 s15, s38, s13
	s_cselect_b32 s14, s39, s12
	s_cselect_b32 s13, s48, s56
	s_cselect_b32 s12, s49, s53
	v_lshl_add_u64 v[160:161], s[10:11], 0, v[154:155]
	s_add_i32 m0, s9, 0xc000
	ds_read_b128 v[168:171], v166
	ds_read_b128 v[172:175], v166 offset:1024
	ds_read_b128 v[176:179], v166 offset:2048
	ds_read_b128 v[180:183], v166 offset:3072
	ds_read_b128 v[184:187], v166 offset:4096
	ds_read_b128 v[188:191], v166 offset:5120
	ds_read_b128 v[192:195], v166 offset:6144
	ds_read_b128 v[198:201], v166 offset:7168
	global_load_lds_dwordx4 v[160:161], off
	v_lshl_add_u64 v[160:161], s[10:11], 0, v[152:153]
	s_add_i32 m0, s9, 0xe000
	s_nop 0
	global_load_lds_dwordx4 v[160:161], off
	s_waitcnt lgkmcnt(8)
	s_barrier
	s_setprio 1
	s_waitcnt lgkmcnt(7)
	v_mfma_f32_16x16x32_bf16 v[140:143], v[40:43], v[168:171], v[140:143]
	v_mfma_f32_16x16x32_bf16 v[136:139], v[56:59], v[168:171], v[136:139]
	s_waitcnt lgkmcnt(5)
	v_mfma_f32_16x16x32_bf16 v[124:127], v[40:43], v[176:179], v[124:127]
	v_mfma_f32_16x16x32_bf16 v[120:123], v[56:59], v[176:179], v[120:123]
	s_waitcnt lgkmcnt(3)
	v_mfma_f32_16x16x32_bf16 v[108:111], v[40:43], v[184:187], v[108:111]
	v_mfma_f32_16x16x32_bf16 v[104:107], v[56:59], v[184:187], v[104:107]
	s_waitcnt lgkmcnt(1)
	v_mfma_f32_16x16x32_bf16 v[92:95], v[40:43], v[192:195], v[92:95]
	v_mfma_f32_16x16x32_bf16 v[88:91], v[56:59], v[192:195], v[88:91]
	v_mfma_f32_16x16x32_bf16 v[140:143], v[44:47], v[172:175], v[140:143]
	v_mfma_f32_16x16x32_bf16 v[136:139], v[60:63], v[172:175], v[136:139]
	v_mfma_f32_16x16x32_bf16 v[124:127], v[44:47], v[180:183], v[124:127]
	v_mfma_f32_16x16x32_bf16 v[120:123], v[60:63], v[180:183], v[120:123]
	v_mfma_f32_16x16x32_bf16 v[108:111], v[44:47], v[188:191], v[108:111]
	v_mfma_f32_16x16x32_bf16 v[104:107], v[60:63], v[188:191], v[104:107]
	s_waitcnt lgkmcnt(0)
	v_mfma_f32_16x16x32_bf16 v[92:95], v[44:47], v[198:201], v[92:95]
	v_mfma_f32_16x16x32_bf16 v[88:91], v[60:63], v[198:201], v[88:91]
	s_setprio 0
	s_barrier
	s_add_i32 s57, s35, s22
	v_lshl_add_u64 v[160:161], s[12:13], 0, v[148:149]
	s_mov_b32 m0, s57
	ds_read_b128 v[202:205], v167
	ds_read_b128 v[206:209], v167 offset:1024
	ds_read_b128 v[210:213], v167 offset:2048
	ds_read_b128 v[214:217], v167 offset:3072
	global_load_lds_dwordx4 v[160:161], off
	v_lshl_add_u64 v[218:219], s[12:13], 0, v[144:145]
	s_add_i32 m0, s57, 0x2000
	s_nop 0
	global_load_lds_dwordx4 v[218:219], off
	s_barrier
	s_setprio 1
	s_waitcnt lgkmcnt(3)
	v_mfma_f32_16x16x32_bf16 v[132:135], v[202:205], v[168:171], v[132:135]
	s_waitcnt lgkmcnt(1)
	v_mfma_f32_16x16x32_bf16 v[128:131], v[210:213], v[168:171], v[128:131]
	v_mfma_f32_16x16x32_bf16 v[116:119], v[202:205], v[176:179], v[116:119]
	v_mfma_f32_16x16x32_bf16 v[112:115], v[210:213], v[176:179], v[112:115]
	v_mfma_f32_16x16x32_bf16 v[100:103], v[202:205], v[184:187], v[100:103]
	v_mfma_f32_16x16x32_bf16 v[96:99], v[210:213], v[184:187], v[96:99]
	v_mfma_f32_16x16x32_bf16 v[84:87], v[202:205], v[192:195], v[84:87]
	v_mfma_f32_16x16x32_bf16 v[80:83], v[210:213], v[192:195], v[80:83]
	v_mfma_f32_16x16x32_bf16 v[132:135], v[206:209], v[172:175], v[132:135]
	s_waitcnt lgkmcnt(0)
	v_mfma_f32_16x16x32_bf16 v[128:131], v[214:217], v[172:175], v[128:131]
	v_mfma_f32_16x16x32_bf16 v[116:119], v[206:209], v[180:183], v[116:119]
	v_mfma_f32_16x16x32_bf16 v[112:115], v[214:217], v[180:183], v[112:115]
	v_mfma_f32_16x16x32_bf16 v[100:103], v[206:209], v[188:191], v[100:103]
	v_mfma_f32_16x16x32_bf16 v[96:99], v[214:217], v[188:191], v[96:99]
	v_mfma_f32_16x16x32_bf16 v[84:87], v[206:209], v[198:201], v[84:87]
	v_mfma_f32_16x16x32_bf16 v[80:83], v[214:217], v[198:201], v[80:83]
	s_setprio 0
	s_mov_b32 m0, s9
	v_lshl_add_u64 v[220:221], s[14:15], 0, v[150:151]
	s_barrier
	ds_read_b128 v[168:171], v166 offset:16384
	ds_read_b128 v[172:175], v166 offset:17408
	ds_read_b128 v[176:179], v166 offset:18432
	ds_read_b128 v[180:183], v166 offset:19456
	ds_read_b128 v[184:187], v166 offset:20480
	ds_read_b128 v[188:191], v166 offset:21504
	ds_read_b128 v[192:195], v166 offset:22528
	ds_read_b128 v[198:201], v166 offset:23552
	global_load_lds_dwordx4 v[220:221], off
	v_lshl_add_u64 v[222:223], s[14:15], 0, v[146:147]
	s_mov_b32 m0, s24
	s_nop 0
	global_load_lds_dwordx4 v[222:223], off
	s_barrier
	s_setprio 1
	s_waitcnt lgkmcnt(7)
	v_mfma_f32_16x16x32_bf16 v[76:79], v[40:43], v[168:171], v[76:79]
	v_mfma_f32_16x16x32_bf16 v[72:75], v[56:59], v[168:171], v[72:75]
	s_waitcnt lgkmcnt(5)
	v_mfma_f32_16x16x32_bf16 v[52:55], v[40:43], v[176:179], v[52:55]
	v_mfma_f32_16x16x32_bf16 v[48:51], v[56:59], v[176:179], v[48:51]
	s_waitcnt lgkmcnt(3)
	v_mfma_f32_16x16x32_bf16 v[28:31], v[40:43], v[184:187], v[28:31]
	v_mfma_f32_16x16x32_bf16 v[24:27], v[56:59], v[184:187], v[24:27]
	s_waitcnt lgkmcnt(1)
	v_mfma_f32_16x16x32_bf16 v[12:15], v[40:43], v[192:195], v[12:15]
	v_mfma_f32_16x16x32_bf16 v[8:11], v[56:59], v[192:195], v[8:11]
	v_mfma_f32_16x16x32_bf16 v[76:79], v[44:47], v[172:175], v[76:79]
	v_mfma_f32_16x16x32_bf16 v[72:75], v[60:63], v[172:175], v[72:75]
	v_mfma_f32_16x16x32_bf16 v[52:55], v[44:47], v[180:183], v[52:55]
	v_mfma_f32_16x16x32_bf16 v[48:51], v[60:63], v[180:183], v[48:51]
	v_mfma_f32_16x16x32_bf16 v[28:31], v[44:47], v[188:191], v[28:31]
	v_mfma_f32_16x16x32_bf16 v[24:27], v[60:63], v[188:191], v[24:27]
	s_waitcnt lgkmcnt(0)
	v_mfma_f32_16x16x32_bf16 v[12:15], v[44:47], v[198:201], v[12:15]
	v_mfma_f32_16x16x32_bf16 v[8:11], v[60:63], v[198:201], v[8:11]
	s_setprio 0
	s_barrier
; #define PG8_STAGE(bufoff, gbase, voff) do { _Pragma("unroll") for (int _i = 0; _i < 2; ++_i) \
;         __builtin_amdgcn_global_load_lds((const unsigned*)((const char*)(gbase) + (voff)[_i]), (LAS unsigned*)(lds + (bufoff) + ldsw + _i * 8192), 16, 0, 0); } while (0)
; #define PG8_LDA(dst, b, h) do { _Pragma("unroll") for (int m = 0; m < 4; ++m) _Pragma("unroll") for (int k = 0; k < 2; ++k) dst[m][k] = *(const LAS bf16x8*)(lds + PG8_SA(b, h) + aoff + m * 2048 + k * 1024); } while (0)
; #define PG8_LDB(dst, b, h) do { _Pragma("unroll") for (int n = 0; n < 2; ++n) _Pragma("unroll") for (int k = 0; k < 2; ++k) dst[n][k] = *(const LAS bf16x8*)(lds + PG8_SB(b, h) + boff + n * 2048 + k * 1024); } while (0)
; #define PG8_MMA(ai, bj, At, Bt) do { __builtin_amdgcn_s_setprio(1); _Pragma("unroll") for (int m = 0; m < 4; ++m) _Pragma("unroll") for (int n = 0; n < 2; ++n) _Pragma("unroll") for (int k = 0; k < 2; ++k) \
;         acc[ai][bj][m][n] = __builtin_amdgcn_mfma_f32_16x16x32_bf16(Bt[n][k], At[m][k], acc[ai][bj][m][n], 0, 0, 0); __builtin_amdgcn_s_setprio(0); } while (0)
; #define PG8_WAIT_V(n) asm volatile("s_waitcnt vmcnt(" #n ")" ::: "memory")
; #define PG8_WAIT_L(n) asm volatile("s_waitcnt lgkmcnt(" #n ")" ::: "memory")
; #define PG8_BAR __builtin_amdgcn_s_barrier()
; #define PG8_SCHED __builtin_amdgcn_sched_barrier(0)
; template <class Map, class Epi>
; DI void gemm_phase(LAS unsigned char* lds, const Map& MP, const Epi& E, const int nM, const int nN, const int K, const int lda, const int ldb) {
;     ...
;             PG8_BAR; PG8_WAIT_L(0); PG8_MMA(1, 0, At, B0); PG8_BAR; PG8_SCHED;
;             PG8_STAGE(PG8_SB(0, 1), b2 + hstepB, voffB);
;             PG8_WAIT_V(6); PG8_BAR; PG8_MMA(1, 1, At, B1); PG8_BAR;
;             PG8_LDB(B0, 1, 0); PG8_SCHED; PG8_LDA(At, 1, 0); PG8_STAGE(PG8_SA(0, 1), a2 + hstepA, voffA);
;             PG8_WAIT_L(8); PG8_BAR; PG8_WAIT_L(0); PG8_MMA(0, 0, At, B0); PG8_BAR; PG8_SCHED;
;             PG8_LDB(B1, 1, 1); PG8_STAGE(PG8_SB(1, 0), b3, voffB);
;             PG8_BAR; PG8_WAIT_L(0); PG8_MMA(0, 1, At, B1); PG8_BAR;
;             PG8_LDA(At, 1, 1); PG8_STAGE(PG8_SA(1, 0), a3, voffA);
;             PG8_BAR; PG8_WAIT_L(0); PG8_MMA(1, 0, At, B0); PG8_BAR; PG8_SCHED;
	s_add_u32 s58, s12, 0x20000
	s_addc_u32 s59, s13, 0
	s_add_i32 s57, s36, s22
	v_lshl_add_u64 v[40:41], s[58:59], 0, v[148:149]
	s_mov_b32 m0, s57
	s_nop 0
	global_load_lds_dwordx4 v[40:41], off
	v_lshl_add_u64 v[40:41], s[58:59], 0, v[144:145]
	s_add_i32 m0, s57, 0x2000
	s_nop 0
	global_load_lds_dwordx4 v[40:41], off
	s_waitcnt vmcnt(6)
	s_barrier
	s_setprio 1
	v_mfma_f32_16x16x32_bf16 v[36:39], v[202:205], v[176:179], v[36:39]
	v_mfma_f32_16x16x32_bf16 v[32:35], v[210:213], v[176:179], v[32:35]
	v_mfma_f32_16x16x32_bf16 v[20:23], v[202:205], v[184:187], v[20:23]
	v_mfma_f32_16x16x32_bf16 v[16:19], v[210:213], v[184:187], v[16:19]
	v_mfma_f32_16x16x32_bf16 v[4:7], v[202:205], v[192:195], v[4:7]
	v_mfma_f32_16x16x32_bf16 v[0:3], v[210:213], v[192:195], v[0:3]
	v_mfma_f32_16x16x32_bf16 v[40:43], v[202:205], v[168:171], v[68:71]
	v_mfma_f32_16x16x32_bf16 v[44:47], v[210:213], v[168:171], v[64:67]
	v_mfma_f32_16x16x32_bf16 v[36:39], v[206:209], v[180:183], v[36:39]
	v_mfma_f32_16x16x32_bf16 v[32:35], v[214:217], v[180:183], v[32:35]
	v_mfma_f32_16x16x32_bf16 v[20:23], v[206:209], v[188:191], v[20:23]
	v_mfma_f32_16x16x32_bf16 v[16:19], v[214:217], v[188:191], v[16:19]
	v_mfma_f32_16x16x32_bf16 v[4:7], v[206:209], v[198:201], v[4:7]
	v_mfma_f32_16x16x32_bf16 v[0:3], v[214:217], v[198:201], v[0:3]
	v_mfma_f32_16x16x32_bf16 v[40:43], v[206:209], v[172:175], v[40:43]
	v_mfma_f32_16x16x32_bf16 v[44:47], v[214:217], v[172:175], v[44:47]
	s_setprio 0
	s_add_i32 s57, 0, 0x18000
	v_add_u32_e32 v68, s57, v164
	s_barrier
	ds_read_b128 v[56:59], v68
	ds_read_b128 v[60:63], v68 offset:1024
	ds_read_b128 v[64:67], v68 offset:2048
	ds_read_b128 v[68:71], v68 offset:3072
	s_add_u32 s14, s14, 0x80000
	s_addc_u32 s15, s15, 0
	s_mov_b32 m0, s25
	v_lshl_add_u64 v[202:203], s[14:15], 0, v[150:151]
	ds_read_b128 v[168:171], v166 offset:32768
	ds_read_b128 v[172:175], v166 offset:33792
	ds_read_b128 v[176:179], v166 offset:34816
	ds_read_b128 v[180:183], v166 offset:35840
	ds_read_b128 v[184:187], v166 offset:36864
	ds_read_b128 v[188:191], v166 offset:37888
	ds_read_b128 v[192:195], v166 offset:38912
	ds_read_b128 v[198:201], v166 offset:39936
	global_load_lds_dwordx4 v[202:203], off
	v_lshl_add_u64 v[202:203], s[14:15], 0, v[146:147]
	s_mov_b32 m0, s26
	s_nop 0
	global_load_lds_dwordx4 v[202:203], off
	s_waitcnt lgkmcnt(8)
	s_barrier
	s_setprio 1
	s_waitcnt lgkmcnt(7)
	v_mfma_f32_16x16x32_bf16 v[140:143], v[56:59], v[168:171], v[140:143]
	v_mfma_f32_16x16x32_bf16 v[136:139], v[64:67], v[168:171], v[136:139]
	s_waitcnt lgkmcnt(5)
	v_mfma_f32_16x16x32_bf16 v[124:127], v[56:59], v[176:179], v[124:127]
	v_mfma_f32_16x16x32_bf16 v[120:123], v[64:67], v[176:179], v[120:123]
	s_waitcnt lgkmcnt(3)
	v_mfma_f32_16x16x32_bf16 v[108:111], v[56:59], v[184:187], v[108:111]
	v_mfma_f32_16x16x32_bf16 v[104:107], v[64:67], v[184:187], v[104:107]
	s_waitcnt lgkmcnt(1)
	v_mfma_f32_16x16x32_bf16 v[92:95], v[56:59], v[192:195], v[92:95]
	v_mfma_f32_16x16x32_bf16 v[88:91], v[64:67], v[192:195], v[88:91]
	v_mfma_f32_16x16x32_bf16 v[140:143], v[60:63], v[172:175], v[140:143]
	v_mfma_f32_16x16x32_bf16 v[136:139], v[68:71], v[172:175], v[136:139]
	v_mfma_f32_16x16x32_bf16 v[124:127], v[60:63], v[180:183], v[124:127]
	v_mfma_f32_16x16x32_bf16 v[120:123], v[68:71], v[180:183], v[120:123]
	v_mfma_f32_16x16x32_bf16 v[108:111], v[60:63], v[188:191], v[108:111]
	v_mfma_f32_16x16x32_bf16 v[104:107], v[68:71], v[188:191], v[104:107]
	s_waitcnt lgkmcnt(0)
	v_mfma_f32_16x16x32_bf16 v[92:95], v[60:63], v[198:201], v[92:95]
	v_mfma_f32_16x16x32_bf16 v[88:91], v[68:71], v[198:201], v[88:91]
	s_setprio 0
	s_barrier
	s_add_i32 s14, 0, 0x1c000
	s_add_i32 s15, s57, s22
	v_add_u32_e32 v196, s14, v164
	v_lshl_add_u64 v[160:161], v[160:161], 0, s[46:47]
	s_mov_b32 m0, s15
	ds_read_b128 v[202:205], v196
	ds_read_b128 v[206:209], v196 offset:1024
	ds_read_b128 v[210:213], v196 offset:2048
	ds_read_b128 v[214:217], v196 offset:3072
	global_load_lds_dwordx4 v[160:161], off
	v_lshl_add_u64 v[160:161], v[218:219], 0, s[46:47]
	s_add_i32 m0, s15, 0x2000
	s_nop 0
	global_load_lds_dwordx4 v[160:161], off
	s_barrier
	s_setprio 1
	s_waitcnt lgkmcnt(3)
	v_mfma_f32_16x16x32_bf16 v[132:135], v[202:205], v[168:171], v[132:135]
	s_waitcnt lgkmcnt(1)
	v_mfma_f32_16x16x32_bf16 v[128:131], v[210:213], v[168:171], v[128:131]
	v_mfma_f32_16x16x32_bf16 v[116:119], v[202:205], v[176:179], v[116:119]
	v_mfma_f32_16x16x32_bf16 v[112:115], v[210:213], v[176:179], v[112:115]
	v_mfma_f32_16x16x32_bf16 v[100:103], v[202:205], v[184:187], v[100:103]
	v_mfma_f32_16x16x32_bf16 v[96:99], v[210:213], v[184:187], v[96:99]
	v_mfma_f32_16x16x32_bf16 v[84:87], v[202:205], v[192:195], v[84:87]
	v_mfma_f32_16x16x32_bf16 v[80:83], v[210:213], v[192:195], v[80:83]
	v_mfma_f32_16x16x32_bf16 v[132:135], v[206:209], v[172:175], v[132:135]
	s_waitcnt lgkmcnt(0)
	v_mfma_f32_16x16x32_bf16 v[128:131], v[214:217], v[172:175], v[128:131]
	v_mfma_f32_16x16x32_bf16 v[116:119], v[206:209], v[180:183], v[116:119]
	v_mfma_f32_16x16x32_bf16 v[112:115], v[214:217], v[180:183], v[112:115]
	v_mfma_f32_16x16x32_bf16 v[100:103], v[206:209], v[188:191], v[100:103]
	v_mfma_f32_16x16x32_bf16 v[96:99], v[214:217], v[188:191], v[96:99]
	v_mfma_f32_16x16x32_bf16 v[84:87], v[206:209], v[198:201], v[84:87]
	v_mfma_f32_16x16x32_bf16 v[80:83], v[214:217], v[198:201], v[80:83]
	s_setprio 0
	s_mov_b32 m0, s30
	v_lshl_add_u64 v[160:161], v[220:221], 0, s[46:47]
	s_barrier
; DI float bflo(unsigned w) { return __uint_as_float(w << 16); }
; DI float bfhi(unsigned w) { return __uint_as_float(w & 0xffff0000u); }
; #define PG8_STAGE(bufoff, gbase, voff) do { _Pragma("unroll") for (int _i = 0; _i < 2; ++_i) \
;         __builtin_amdgcn_global_load_lds((const unsigned*)((const char*)(gbase) + (voff)[_i]), (LAS unsigned*)(lds + (bufoff) + ldsw + _i * 8192), 16, 0, 0); } while (0)
; #define PG8_WAIT_V(n) asm volatile("s_waitcnt vmcnt(" #n ")" ::: "memory")
; #define PG8_WAIT_L(n) asm volatile("s_waitcnt lgkmcnt(" #n ")" ::: "memory")
; #define PG8_BAR __builtin_amdgcn_s_barrier()
;     DI void operator()(const f32x4 (&acc)[2][2][4][2], const Unit& u, int wr, int wc, int fr, int fq) const {
;         const int row0 = u.pm * BM + wr * 64 + fr, col0 = u.pn * BM + wc * 32 + 8 * fq;
;         f32x4 sc[2][2];
; #pragma unroll
;         for (int bj = 0; bj < 2; ++bj)
; #pragma unroll
;             for (int n = 0; n < 2; ++n) sc[bj][n] = scale ? *(const f32x4*)(scale + col0 + bj * HALF + 4 * n) : (f32x4){1.f, 1.f, 1.f, 1.f};
; #pragma unroll
;         for (int ai = 0; ai < 2; ++ai)
; #pragma unroll
;             for (int m = 0; m < 4; ++m) { const size_t ro = (size_t)(row0 + ai * HALF + m * 16) * D + col0;
; #pragma unroll
;                 for (int bj = 0; bj < 2; ++bj) {
;                     f32x4 x0, x1;
;                     if constexpr (IB) { const u32x4 w = *(const u32x4*)((const bf16_t*)Xin + ro + bj * HALF);
;                         x0 = (f32x4){bflo(w[0]), bfhi(w[0]), bflo(w[1]), bfhi(w[1])}; x1 = (f32x4){bflo(w[2]), bfhi(w[2]), bflo(w[3]), bfhi(w[3])}; }
;                     else { x0 = *(const f32x4*)((const float*)Xin + ro + bj * HALF); x1 = *(const f32x4*)((const float*)Xin + ro + bj * HALF + 4); }
;                     x0 += acc[ai][bj][m][0] * sc[bj][0]; x1 += acc[ai][bj][m][1] * sc[bj][1];
; template <class Map, class Epi>
; DI void gemm_phase(LAS unsigned char* lds, const Map& MP, const Epi& E, const int nM, const int nN, const int K, const int lda, const int ldb) {
;     ...
;             PG8_BAR; PG8_WAIT_L(0); PG8_MMA(1, 0, At, B0); PG8_BAR; PG8_SCHED;
;             PG8_STAGE(PG8_SB(1, 1), b3 + hstepB, voffB);
;             PG8_WAIT_V(6); PG8_BAR; PG8_MMA(1, 1, At, B1); PG8_BAR;
;         }
;         { int frr = fr, fqq = fq; asm volatile("" : "+v"(frr), "+v"(fqq)); E(acc, cur, wr, wc, frr, fqq); }
	ds_read_b128 v[168:171], v166 offset:49152
	ds_read_b128 v[172:175], v166 offset:50176
	ds_read_b128 v[176:179], v166 offset:51200
	ds_read_b128 v[180:183], v166 offset:52224
	ds_read_b128 v[184:187], v166 offset:53248
	ds_read_b128 v[188:191], v166 offset:54272
	ds_read_b128 v[192:195], v166 offset:55296
	ds_read_b128 v[198:201], v166 offset:56320
	global_load_lds_dwordx4 v[160:161], off
	v_lshl_add_u64 v[160:161], v[222:223], 0, s[46:47]
	s_mov_b32 m0, s31
	s_nop 0
	global_load_lds_dwordx4 v[160:161], off
	s_barrier
	s_setprio 1
	s_waitcnt lgkmcnt(7)
	v_mfma_f32_16x16x32_bf16 v[76:79], v[56:59], v[168:171], v[76:79]
	v_mfma_f32_16x16x32_bf16 v[72:75], v[64:67], v[168:171], v[72:75]
	s_waitcnt lgkmcnt(5)
	v_mfma_f32_16x16x32_bf16 v[52:55], v[56:59], v[176:179], v[52:55]
	v_mfma_f32_16x16x32_bf16 v[48:51], v[64:67], v[176:179], v[48:51]
	s_waitcnt lgkmcnt(3)
	v_mfma_f32_16x16x32_bf16 v[28:31], v[56:59], v[184:187], v[28:31]
	v_mfma_f32_16x16x32_bf16 v[24:27], v[64:67], v[184:187], v[24:27]
	s_waitcnt lgkmcnt(1)
	v_mfma_f32_16x16x32_bf16 v[12:15], v[56:59], v[192:195], v[12:15]
	v_mfma_f32_16x16x32_bf16 v[8:11], v[64:67], v[192:195], v[8:11]
	v_mfma_f32_16x16x32_bf16 v[76:79], v[60:63], v[172:175], v[76:79]
	v_mfma_f32_16x16x32_bf16 v[72:75], v[68:71], v[172:175], v[72:75]
	v_mfma_f32_16x16x32_bf16 v[52:55], v[60:63], v[180:183], v[52:55]
	v_mfma_f32_16x16x32_bf16 v[48:51], v[68:71], v[180:183], v[48:51]
	v_mfma_f32_16x16x32_bf16 v[28:31], v[60:63], v[188:191], v[28:31]
	v_mfma_f32_16x16x32_bf16 v[24:27], v[68:71], v[188:191], v[24:27]
	s_waitcnt lgkmcnt(0)
	v_mfma_f32_16x16x32_bf16 v[12:15], v[60:63], v[198:201], v[12:15]
	v_mfma_f32_16x16x32_bf16 v[8:11], v[68:71], v[198:201], v[8:11]
	s_setprio 0
	s_barrier
	s_add_u32 s12, s12, 0x20080
	s_addc_u32 s13, s13, 0
	s_add_i32 s14, s14, s22
	v_lshl_add_u64 v[56:57], s[12:13], 0, v[148:149]
	s_mov_b32 m0, s14
	s_nop 0
	global_load_lds_dwordx4 v[56:57], off
	v_lshl_add_u64 v[56:57], s[12:13], 0, v[144:145]
	s_add_i32 m0, s14, 0x2000
	s_nop 0
	global_load_lds_dwordx4 v[56:57], off
	s_waitcnt vmcnt(6)
	s_barrier
	s_setprio 1
	v_mfma_f32_16x16x32_bf16 v[40:43], v[202:205], v[168:171], v[40:43]
	v_mfma_f32_16x16x32_bf16 v[68:71], v[206:209], v[172:175], v[40:43]
	v_mfma_f32_16x16x32_bf16 v[40:43], v[210:213], v[168:171], v[44:47]
	v_mfma_f32_16x16x32_bf16 v[36:39], v[202:205], v[176:179], v[36:39]
	v_mfma_f32_16x16x32_bf16 v[32:35], v[210:213], v[176:179], v[32:35]
	v_mfma_f32_16x16x32_bf16 v[20:23], v[202:205], v[184:187], v[20:23]
	v_mfma_f32_16x16x32_bf16 v[16:19], v[210:213], v[184:187], v[16:19]
	v_mfma_f32_16x16x32_bf16 v[4:7], v[202:205], v[192:195], v[4:7]
	v_mfma_f32_16x16x32_bf16 v[0:3], v[210:213], v[192:195], v[0:3]
	v_mfma_f32_16x16x32_bf16 v[64:67], v[214:217], v[172:175], v[40:43]
	v_mfma_f32_16x16x32_bf16 v[36:39], v[206:209], v[180:183], v[36:39]
	v_mfma_f32_16x16x32_bf16 v[32:35], v[214:217], v[180:183], v[32:35]
	v_mfma_f32_16x16x32_bf16 v[20:23], v[206:209], v[188:191], v[20:23]
	v_mfma_f32_16x16x32_bf16 v[16:19], v[214:217], v[188:191], v[16:19]
	v_mfma_f32_16x16x32_bf16 v[4:7], v[206:209], v[198:201], v[4:7]
	v_mfma_f32_16x16x32_bf16 v[0:3], v[214:217], v[198:201], v[0:3]
	s_setprio 0
	s_add_i32 s3, s3, 2
	s_add_u32 s53, s53, 0x100
	s_addc_u32 s56, s56, 0
	s_add_u32 s10, s10, 0x100
	s_addc_u32 s11, s11, 0
	s_cmp_gt_u32 s3, 5
	s_barrier
	s_cbranch_scc0 .LBB1_2339
	s_lshl_b32 s2, s2, 8
	v_mov_b32_e32 v40, v163
	v_mov_b32_e32 v168, v162
	s_or_b32 s2, s2, s29
	s_and_b64 vcc, exec, s[40:41]
	v_lshl_add_u32 v160, v40, 3, s2
	s_lshl_b32 s2, s8, 8
	s_add_i32 s2, s2, s28
	v_add_u32_e32 v168, s2, v168
	v_ashrrev_i32_e32 v169, 31, v168
	v_ashrrev_i32_e32 v161, 31, v160
	v_lshlrev_b64 v[168:169], 11, v[168:169]
	v_lshl_add_u64 v[44:45], v[160:161], 2, s[44:45]
	v_lshl_add_u64 v[160:161], v[168:169], 0, v[160:161]
	v_lshlrev_b64 v[160:161], 1, v[160:161]
	v_lshl_add_u64 v[172:173], s[4:5], 0, v[160:161]
	global_load_dwordx4 v[56:59], v[44:45], off offset:16
	global_load_dwordx4 v[60:63], v[44:45], off
	global_load_dwordx4 v[40:43], v[44:45], off offset:528
	s_nop 0
	global_load_dwordx4 v[44:47], v[44:45], off offset:512
	s_mov_b64 s[2:3], 0x10000
	global_load_dwordx4 v[178:181], v[172:173], off
	global_load_dwordx4 v[182:185], v[172:173], off offset:256
	s_mov_b64 s[98:99], 0x10000
	v_lshl_add_u64 v[170:171], v[172:173], 0, s[98:99]
	global_load_dwordx4 v[186:189], v[170:171], off
	global_load_dwordx4 v[190:193], v[170:171], off offset:256
	s_mov_b64 s[98:99], 0x20000
	v_lshl_add_u64 v[170:171], v[172:173], 0, s[98:99]
	global_load_dwordx4 v[198:201], v[170:171], off
	global_load_dwordx4 v[202:205], v[170:171], off offset:256
	s_mov_b64 s[98:99], 0x30000
	v_lshl_add_u64 v[170:171], v[172:173], 0, s[98:99]
	global_load_dwordx4 v[206:209], v[170:171], off
	global_load_dwordx4 v[210:213], v[170:171], off offset:256
	s_mov_b64 s[98:99], 0x80000
	v_lshl_add_u64 v[170:171], v[172:173], 0, s[98:99]
	global_load_dwordx4 v[214:217], v[170:171], off
	global_load_dwordx4 v[248:251], v[170:171], off offset:256
	s_mov_b64 s[98:99], 0x90000
	v_lshl_add_u64 v[170:171], v[172:173], 0, s[98:99]
	global_load_dwordx4 v[252:255], v[170:171], off
	s_waitcnt vmcnt(10)
	s_nop 1
	v_mov_b32_e32 v168, v178
	v_mov_b32_e32 v169, v179
	v_mov_b32_e32 v170, v180
	v_mov_b32_e32 v171, v181
	s_mov_b32 s8, s52
	s_mov_b64 s[10:11], s[54:55]
	s_mov_b64 s[12:13], s[6:7]
	s_waitcnt lgkmcnt(0)
; DI unsigned pack2(float a, float b) { f32x2 v = {a, b}; hwbf16x2 r = __builtin_convertvector(v, hwbf16x2); return __builtin_bit_cast(unsigned, r); }
; DI float bflo(unsigned w) { return __uint_as_float(w << 16); }
; DI float bfhi(unsigned w) { return __uint_as_float(w & 0xffff0000u); }
;     DI void operator()(const f32x4 (&acc)[2][2][4][2], const Unit& u, int wr, int wc, int fr, int fq) const {
;     ...
;         for (int ai = 0; ai < 2; ++ai)
; #pragma unroll
;             for (int m = 0; m < 4; ++m) { const size_t ro = (size_t)(row0 + ai * HALF + m * 16) * D + col0;
; #pragma unroll
;                 for (int bj = 0; bj < 2; ++bj) {
;                     f32x4 x0, x1;
;                     if constexpr (IB) { const u32x4 w = *(const u32x4*)((const bf16_t*)Xin + ro + bj * HALF);
;                         x0 = (f32x4){bflo(w[0]), bfhi(w[0]), bflo(w[1]), bfhi(w[1])}; x1 = (f32x4){bflo(w[2]), bfhi(w[2]), bflo(w[3]), bfhi(w[3])}; }
;                     else { x0 = *(const f32x4*)((const float*)Xin + ro + bj * HALF); x1 = *(const f32x4*)((const float*)Xin + ro + bj * HALF + 4); }
;                     x0 += acc[ai][bj][m][0] * sc[bj][0]; x1 += acc[ai][bj][m][1] * sc[bj][1];
;                     if constexpr (OB) { u32x4 o; o[0] = pack2(x0[0], x0[1]); o[1] = pack2(x0[2], x0[3]); o[2] = pack2(x1[0], x1[1]); o[3] = pack2(x1[2], x1[3]);
;                         *(u32x4*)((bf16_t*)Xout + ro + bj * HALF) = o; }
;                     else { *(f32x4*)((float*)Xout + ro + bj * HALF) = x0; *(f32x4*)((float*)Xout + ro + bj * HALF + 4) = x1; } } }
	v_lshlrev_b32_e32 v174, 16, v168
	v_and_b32_e32 v175, 0xffff0000, v168
	v_lshlrev_b32_e32 v168, 16, v169
	v_and_b32_e32 v169, 0xffff0000, v169
	v_lshlrev_b32_e32 v176, 16, v170
	v_and_b32_e32 v177, 0xffff0000, v170
	v_lshlrev_b32_e32 v170, 16, v171
	v_and_b32_e32 v171, 0xffff0000, v171
	v_pk_fma_f32 v[142:143], v[142:143], v[62:63], v[168:169]
	v_pk_fma_f32 v[140:141], v[140:141], v[60:61], v[174:175]
	v_pk_fma_f32 v[168:169], v[138:139], v[58:59], v[170:171]
	v_pk_fma_f32 v[138:139], v[136:137], v[56:57], v[176:177]
	v_cvt_pk_bf16_f32 v136, v140, v141
	v_cvt_pk_bf16_f32 v137, v142, v143
	v_cvt_pk_bf16_f32 v138, v138, v139
	v_cvt_pk_bf16_f32 v139, v168, v169
	v_lshl_add_u64 v[140:141], s[42:43], 0, v[160:161]
	global_store_dwordx4 v[140:141], v[136:139], off
	s_waitcnt vmcnt(10)
	s_nop 1
	v_mov_b32_e32 v136, v182
	v_mov_b32_e32 v137, v183
	v_mov_b32_e32 v138, v184
	v_mov_b32_e32 v139, v185
	s_waitcnt lgkmcnt(0)
	v_lshlrev_b32_e32 v142, 16, v136
	v_and_b32_e32 v143, 0xffff0000, v136
	v_lshlrev_b32_e32 v136, 16, v137
	v_and_b32_e32 v137, 0xffff0000, v137
	v_lshlrev_b32_e32 v168, 16, v138
	v_and_b32_e32 v169, 0xffff0000, v138
	v_lshlrev_b32_e32 v138, 16, v139
	v_and_b32_e32 v139, 0xffff0000, v139
	v_pk_fma_f32 v[134:135], v[134:135], v[46:47], v[136:137]
	v_pk_fma_f32 v[132:133], v[132:133], v[44:45], v[142:143]
	v_pk_fma_f32 v[136:137], v[130:131], v[42:43], v[138:139]
	v_pk_fma_f32 v[130:131], v[128:129], v[40:41], v[168:169]
	v_cvt_pk_bf16_f32 v128, v132, v133
	v_cvt_pk_bf16_f32 v129, v134, v135
	v_cvt_pk_bf16_f32 v130, v130, v131
	v_cvt_pk_bf16_f32 v131, v136, v137
	v_lshl_add_u64 v[132:133], v[160:161], 0, s[2:3]
	global_store_dwordx4 v[140:141], v[128:131], off offset:256
	v_lshl_add_u64 v[134:135], s[4:5], 0, v[132:133]
	s_waitcnt vmcnt(10)
	s_nop 1
	v_mov_b32_e32 v128, v186
	v_mov_b32_e32 v129, v187
	v_mov_b32_e32 v130, v188
	v_mov_b32_e32 v131, v189
	s_mov_b64 s[2:3], 0x20000
	s_waitcnt lgkmcnt(0)
	v_lshlrev_b32_e32 v136, 16, v128
	v_and_b32_e32 v137, 0xffff0000, v128
	v_lshlrev_b32_e32 v128, 16, v129
	v_and_b32_e32 v129, 0xffff0000, v129
	v_lshlrev_b32_e32 v138, 16, v130
	v_and_b32_e32 v139, 0xffff0000, v130
	v_lshlrev_b32_e32 v130, 16, v131
	v_and_b32_e32 v131, 0xffff0000, v131
	v_pk_fma_f32 v[126:127], v[126:127], v[62:63], v[128:129]
	v_pk_fma_f32 v[124:125], v[124:125], v[60:61], v[136:137]
	v_pk_fma_f32 v[128:129], v[122:123], v[58:59], v[130:131]
	v_pk_fma_f32 v[122:123], v[120:121], v[56:57], v[138:139]
	v_cvt_pk_bf16_f32 v120, v124, v125
	v_cvt_pk_bf16_f32 v121, v126, v127
	v_cvt_pk_bf16_f32 v122, v122, v123
	v_cvt_pk_bf16_f32 v123, v128, v129
	v_lshl_add_u64 v[124:125], s[42:43], 0, v[132:133]
	global_store_dwordx4 v[124:125], v[120:123], off
	s_waitcnt vmcnt(10)
	s_nop 1
	v_mov_b32_e32 v120, v190
	v_mov_b32_e32 v121, v191
	v_mov_b32_e32 v122, v192
	v_mov_b32_e32 v123, v193
	s_waitcnt lgkmcnt(0)
	v_lshlrev_b32_e32 v126, 16, v120
	v_and_b32_e32 v127, 0xffff0000, v120
	v_lshlrev_b32_e32 v120, 16, v121
	v_and_b32_e32 v121, 0xffff0000, v121
	v_lshlrev_b32_e32 v128, 16, v122
	v_and_b32_e32 v129, 0xffff0000, v122
	v_lshlrev_b32_e32 v122, 16, v123
	v_and_b32_e32 v123, 0xffff0000, v123
	v_pk_fma_f32 v[118:119], v[118:119], v[46:47], v[120:121]
	v_pk_fma_f32 v[116:117], v[116:117], v[44:45], v[126:127]
	v_pk_fma_f32 v[120:121], v[114:115], v[42:43], v[122:123]
	v_pk_fma_f32 v[114:115], v[112:113], v[40:41], v[128:129]
	v_cvt_pk_bf16_f32 v112, v116, v117
	v_cvt_pk_bf16_f32 v113, v118, v119
	v_cvt_pk_bf16_f32 v114, v114, v115
	v_cvt_pk_bf16_f32 v115, v120, v121
	v_lshl_add_u64 v[116:117], v[160:161], 0, s[2:3]
	global_store_dwordx4 v[124:125], v[112:115], off offset:256
	v_lshl_add_u64 v[118:119], s[4:5], 0, v[116:117]
	s_waitcnt vmcnt(10)
	s_nop 1
	v_mov_b32_e32 v112, v198
	v_mov_b32_e32 v113, v199
	v_mov_b32_e32 v114, v200
	v_mov_b32_e32 v115, v201
	s_mov_b64 s[2:3], 0x30000
	s_waitcnt lgkmcnt(0)
	v_lshlrev_b32_e32 v120, 16, v112
	v_and_b32_e32 v121, 0xffff0000, v112
	v_lshlrev_b32_e32 v112, 16, v113
	v_and_b32_e32 v113, 0xffff0000, v113
	v_lshlrev_b32_e32 v122, 16, v114
	v_and_b32_e32 v123, 0xffff0000, v114
	v_lshlrev_b32_e32 v114, 16, v115
	v_and_b32_e32 v115, 0xffff0000, v115
	v_pk_fma_f32 v[110:111], v[110:111], v[62:63], v[112:113]
	v_pk_fma_f32 v[108:109], v[108:109], v[60:61], v[120:121]
	v_pk_fma_f32 v[112:113], v[106:107], v[58:59], v[114:115]
	v_pk_fma_f32 v[106:107], v[104:105], v[56:57], v[122:123]
	v_cvt_pk_bf16_f32 v104, v108, v109
	v_cvt_pk_bf16_f32 v105, v110, v111
	v_cvt_pk_bf16_f32 v106, v106, v107
	v_cvt_pk_bf16_f32 v107, v112, v113
	v_lshl_add_u64 v[108:109], s[42:43], 0, v[116:117]
	global_store_dwordx4 v[108:109], v[104:107], off
	s_waitcnt vmcnt(10)
	s_nop 1
	v_mov_b32_e32 v104, v202
	v_mov_b32_e32 v105, v203
	v_mov_b32_e32 v106, v204
	v_mov_b32_e32 v107, v205
	s_waitcnt lgkmcnt(0)
	v_lshlrev_b32_e32 v110, 16, v104
	v_and_b32_e32 v111, 0xffff0000, v104
	v_lshlrev_b32_e32 v104, 16, v105
	v_and_b32_e32 v105, 0xffff0000, v105
	v_lshlrev_b32_e32 v112, 16, v106
	v_and_b32_e32 v113, 0xffff0000, v106
	v_lshlrev_b32_e32 v106, 16, v107
	v_and_b32_e32 v107, 0xffff0000, v107
	v_pk_fma_f32 v[102:103], v[102:103], v[46:47], v[104:105]
	v_pk_fma_f32 v[100:101], v[100:101], v[44:45], v[110:111]
	v_pk_fma_f32 v[104:105], v[98:99], v[42:43], v[106:107]
	v_pk_fma_f32 v[98:99], v[96:97], v[40:41], v[112:113]
	v_cvt_pk_bf16_f32 v96, v100, v101
	v_cvt_pk_bf16_f32 v97, v102, v103
	v_cvt_pk_bf16_f32 v98, v98, v99
	v_cvt_pk_bf16_f32 v99, v104, v105
	v_lshl_add_u64 v[100:101], v[160:161], 0, s[2:3]
	global_store_dwordx4 v[108:109], v[96:99], off offset:256
	v_lshl_add_u64 v[102:103], s[4:5], 0, v[100:101]
	s_waitcnt vmcnt(10)
; DI unsigned pack2(float a, float b) { f32x2 v = {a, b}; hwbf16x2 r = __builtin_convertvector(v, hwbf16x2); return __builtin_bit_cast(unsigned, r); }
; DI float bflo(unsigned w) { return __uint_as_float(w << 16); }
; DI float bfhi(unsigned w) { return __uint_as_float(w & 0xffff0000u); }
;     DI void operator()(const f32x4 (&acc)[2][2][4][2], const Unit& u, int wr, int wc, int fr, int fq) const {
;     ...
;         for (int ai = 0; ai < 2; ++ai)
; #pragma unroll
;             for (int m = 0; m < 4; ++m) { const size_t ro = (size_t)(row0 + ai * HALF + m * 16) * D + col0;
; #pragma unroll
;                 for (int bj = 0; bj < 2; ++bj) {
;                     f32x4 x0, x1;
;                     if constexpr (IB) { const u32x4 w = *(const u32x4*)((const bf16_t*)Xin + ro + bj * HALF);
;                         x0 = (f32x4){bflo(w[0]), bfhi(w[0]), bflo(w[1]), bfhi(w[1])}; x1 = (f32x4){bflo(w[2]), bfhi(w[2]), bflo(w[3]), bfhi(w[3])}; }
;                     else { x0 = *(const f32x4*)((const float*)Xin + ro + bj * HALF); x1 = *(const f32x4*)((const float*)Xin + ro + bj * HALF + 4); }
;                     x0 += acc[ai][bj][m][0] * sc[bj][0]; x1 += acc[ai][bj][m][1] * sc[bj][1];
;                     if constexpr (OB) { u32x4 o; o[0] = pack2(x0[0], x0[1]); o[1] = pack2(x0[2], x0[3]); o[2] = pack2(x1[0], x1[1]); o[3] = pack2(x1[2], x1[3]);
;                         *(u32x4*)((bf16_t*)Xout + ro + bj * HALF) = o; }
;                     else { *(f32x4*)((float*)Xout + ro + bj * HALF) = x0; *(f32x4*)((float*)Xout + ro + bj * HALF + 4) = x1; } } }
	s_nop 1
	v_mov_b32_e32 v96, v206
	v_mov_b32_e32 v97, v207
	v_mov_b32_e32 v98, v208
	v_mov_b32_e32 v99, v209
	s_mov_b64 s[2:3], 0x80000
	s_waitcnt lgkmcnt(0)
	v_lshlrev_b32_e32 v104, 16, v96
	v_and_b32_e32 v105, 0xffff0000, v96
	v_lshlrev_b32_e32 v96, 16, v97
	v_and_b32_e32 v97, 0xffff0000, v97
	v_lshlrev_b32_e32 v106, 16, v98
	v_and_b32_e32 v107, 0xffff0000, v98
	v_lshlrev_b32_e32 v98, 16, v99
	v_and_b32_e32 v99, 0xffff0000, v99
	v_pk_fma_f32 v[94:95], v[94:95], v[62:63], v[96:97]
	v_pk_fma_f32 v[92:93], v[92:93], v[60:61], v[104:105]
	v_pk_fma_f32 v[96:97], v[90:91], v[58:59], v[98:99]
	v_pk_fma_f32 v[90:91], v[88:89], v[56:57], v[106:107]
	v_cvt_pk_bf16_f32 v88, v92, v93
	v_cvt_pk_bf16_f32 v89, v94, v95
	v_cvt_pk_bf16_f32 v90, v90, v91
	v_cvt_pk_bf16_f32 v91, v96, v97
	v_lshl_add_u64 v[92:93], s[42:43], 0, v[100:101]
	global_store_dwordx4 v[92:93], v[88:91], off
	s_waitcnt vmcnt(10)
	s_nop 1
	v_mov_b32_e32 v88, v210
	v_mov_b32_e32 v89, v211
	v_mov_b32_e32 v90, v212
	v_mov_b32_e32 v91, v213
	s_waitcnt lgkmcnt(0)
	v_lshlrev_b32_e32 v94, 16, v88
	v_and_b32_e32 v95, 0xffff0000, v88
	v_lshlrev_b32_e32 v88, 16, v89
	v_and_b32_e32 v89, 0xffff0000, v89
	v_lshlrev_b32_e32 v96, 16, v90
	v_and_b32_e32 v97, 0xffff0000, v90
	v_lshlrev_b32_e32 v90, 16, v91
	v_and_b32_e32 v91, 0xffff0000, v91
	v_pk_fma_f32 v[86:87], v[86:87], v[46:47], v[88:89]
	v_pk_fma_f32 v[84:85], v[84:85], v[44:45], v[94:95]
	v_pk_fma_f32 v[88:89], v[82:83], v[42:43], v[90:91]
	v_pk_fma_f32 v[82:83], v[80:81], v[40:41], v[96:97]
	v_cvt_pk_bf16_f32 v80, v84, v85
	v_cvt_pk_bf16_f32 v81, v86, v87
	v_cvt_pk_bf16_f32 v82, v82, v83
	v_cvt_pk_bf16_f32 v83, v88, v89
	v_lshl_add_u64 v[84:85], v[160:161], 0, s[2:3]
	global_store_dwordx4 v[92:93], v[80:83], off offset:256
	v_lshl_add_u64 v[86:87], s[4:5], 0, v[84:85]
	s_waitcnt vmcnt(10)
	s_nop 1
	v_mov_b32_e32 v80, v214
	v_mov_b32_e32 v81, v215
	v_mov_b32_e32 v82, v216
	v_mov_b32_e32 v83, v217
	s_mov_b64 s[2:3], 0x90000
	s_waitcnt lgkmcnt(0)
	v_lshlrev_b32_e32 v88, 16, v80
	v_and_b32_e32 v89, 0xffff0000, v80
	v_lshlrev_b32_e32 v80, 16, v81
	v_and_b32_e32 v81, 0xffff0000, v81
	v_lshlrev_b32_e32 v90, 16, v82
	v_and_b32_e32 v91, 0xffff0000, v82
	v_lshlrev_b32_e32 v82, 16, v83
	v_and_b32_e32 v83, 0xffff0000, v83
	v_pk_fma_f32 v[78:79], v[78:79], v[62:63], v[80:81]
	v_pk_fma_f32 v[76:77], v[76:77], v[60:61], v[88:89]
	v_pk_fma_f32 v[80:81], v[74:75], v[58:59], v[82:83]
	v_pk_fma_f32 v[74:75], v[72:73], v[56:57], v[90:91]
	v_cvt_pk_bf16_f32 v72, v76, v77
	v_cvt_pk_bf16_f32 v73, v78, v79
	v_cvt_pk_bf16_f32 v74, v74, v75
	v_cvt_pk_bf16_f32 v75, v80, v81
	v_lshl_add_u64 v[76:77], s[42:43], 0, v[84:85]
	global_store_dwordx4 v[76:77], v[72:75], off
	s_waitcnt vmcnt(10)
	s_nop 1
	v_mov_b32_e32 v72, v248
	v_mov_b32_e32 v73, v249
	v_mov_b32_e32 v74, v250
	v_mov_b32_e32 v75, v251
	s_waitcnt lgkmcnt(0)
	v_lshlrev_b32_e32 v78, 16, v72
	v_and_b32_e32 v79, 0xffff0000, v72
	v_lshlrev_b32_e32 v72, 16, v73
	v_and_b32_e32 v73, 0xffff0000, v73
	v_lshlrev_b32_e32 v80, 16, v74
	v_and_b32_e32 v81, 0xffff0000, v74
	v_lshlrev_b32_e32 v74, 16, v75
	v_and_b32_e32 v75, 0xffff0000, v75
	v_pk_fma_f32 v[70:71], v[70:71], v[46:47], v[72:73]
	v_pk_fma_f32 v[68:69], v[68:69], v[44:45], v[78:79]
	v_pk_fma_f32 v[72:73], v[66:67], v[42:43], v[74:75]
	v_pk_fma_f32 v[66:67], v[64:65], v[40:41], v[80:81]
	v_cvt_pk_bf16_f32 v64, v68, v69
	v_cvt_pk_bf16_f32 v65, v70, v71
	v_cvt_pk_bf16_f32 v66, v66, v67
	v_cvt_pk_bf16_f32 v67, v72, v73
	v_lshl_add_u64 v[68:69], v[160:161], 0, s[2:3]
	global_store_dwordx4 v[76:77], v[64:67], off offset:256
	v_lshl_add_u64 v[70:71], s[4:5], 0, v[68:69]
	s_waitcnt vmcnt(10)
	s_nop 1
	v_mov_b32_e32 v64, v252
	v_mov_b32_e32 v65, v253
	v_mov_b32_e32 v66, v254
	v_mov_b32_e32 v67, v255
	s_mov_b64 s[2:3], 0xa0000
	s_waitcnt lgkmcnt(0)
	v_lshlrev_b32_e32 v72, 16, v64
	v_and_b32_e32 v73, 0xffff0000, v64
	v_lshlrev_b32_e32 v64, 16, v65
	v_and_b32_e32 v65, 0xffff0000, v65
	v_lshlrev_b32_e32 v74, 16, v66
	v_and_b32_e32 v75, 0xffff0000, v66
	v_lshlrev_b32_e32 v66, 16, v67
	v_and_b32_e32 v67, 0xffff0000, v67
	v_pk_fma_f32 v[54:55], v[54:55], v[62:63], v[64:65]
	v_pk_fma_f32 v[52:53], v[52:53], v[60:61], v[72:73]
	v_pk_fma_f32 v[64:65], v[50:51], v[58:59], v[66:67]
	v_pk_fma_f32 v[50:51], v[48:49], v[56:57], v[74:75]
	v_cvt_pk_bf16_f32 v48, v52, v53
	v_cvt_pk_bf16_f32 v49, v54, v55
	v_cvt_pk_bf16_f32 v50, v50, v51
	v_cvt_pk_bf16_f32 v51, v64, v65
	v_lshl_add_u64 v[52:53], s[42:43], 0, v[68:69]
	global_store_dwordx4 v[52:53], v[48:51], off
	global_load_dwordx4 v[48:51], v[70:71], off offset:256
	s_waitcnt vmcnt(0) lgkmcnt(0)
; DI unsigned pack2(float a, float b) { f32x2 v = {a, b}; hwbf16x2 r = __builtin_convertvector(v, hwbf16x2); return __builtin_bit_cast(unsigned, r); }
; DI float bflo(unsigned w) { return __uint_as_float(w << 16); }
; DI float bfhi(unsigned w) { return __uint_as_float(w & 0xffff0000u); }
;     DI const char* a(const Unit& u) const { return (const char*)(A + (size_t)u.pm * BM * lda); }
;     DI const char* a(const Unit& u) const { return (const char*)(A + (size_t)u.pm * BM * 2048 + (u.pn >> 1) * 512); }
;     DI void operator()(const f32x4 (&acc)[2][2][4][2], const Unit& u, int wr, int wc, int fr, int fq) const {
;     ...
;         for (int ai = 0; ai < 2; ++ai)
; #pragma unroll
;             for (int m = 0; m < 4; ++m) { const size_t ro = (size_t)(row0 + ai * HALF + m * 16) * D + col0;
; #pragma unroll
;                 for (int bj = 0; bj < 2; ++bj) {
;                     f32x4 x0, x1;
;                     if constexpr (IB) { const u32x4 w = *(const u32x4*)((const bf16_t*)Xin + ro + bj * HALF);
;                         x0 = (f32x4){bflo(w[0]), bfhi(w[0]), bflo(w[1]), bfhi(w[1])}; x1 = (f32x4){bflo(w[2]), bfhi(w[2]), bflo(w[3]), bfhi(w[3])}; }
;                     else { x0 = *(const f32x4*)((const float*)Xin + ro + bj * HALF); x1 = *(const f32x4*)((const float*)Xin + ro + bj * HALF + 4); }
;                     x0 += acc[ai][bj][m][0] * sc[bj][0]; x1 += acc[ai][bj][m][1] * sc[bj][1];
;                     if constexpr (OB) { u32x4 o; o[0] = pack2(x0[0], x0[1]); o[1] = pack2(x0[2], x0[3]); o[2] = pack2(x1[0], x1[1]); o[3] = pack2(x1[2], x1[3]);
;                         *(u32x4*)((bf16_t*)Xout + ro + bj * HALF) = o; }
;                     else { *(f32x4*)((float*)Xout + ro + bj * HALF) = x0; *(f32x4*)((float*)Xout + ro + bj * HALF + 4) = x1; } } }
; template <class Map, class Epi>
; DI void gemm_phase(LAS unsigned char* lds, const Map& MP, const Epi& E, const int nM, const int nN, const int K, const int lda, const int ldb) {
;     ...
;         if (!has_next) break;
; #pragma unroll
;         for (int a = 0; a < 2; ++a)
; #pragma unroll
;             for (int b = 0; b < 2; ++b)
; #pragma unroll
;                 for (int m = 0; m < 4; ++m)
; #pragma unroll
;                     for (int n = 0; n < 2; ++n) acc[a][b][m][n] = (f32x4){0.f, 0.f, 0.f, 0.f};
;         cur = nxt; cA = nA; cB = nB; ++ui;
;     }
;     PG8_WAIT_V(0);
;     if (wr == 0) PG8_BAR;
;     PG8_BAR;
	v_lshlrev_b32_e32 v54, 16, v48
	v_and_b32_e32 v55, 0xffff0000, v48
	v_lshlrev_b32_e32 v48, 16, v49
	v_and_b32_e32 v49, 0xffff0000, v49
	v_lshlrev_b32_e32 v64, 16, v50
	v_and_b32_e32 v65, 0xffff0000, v50
	v_lshlrev_b32_e32 v50, 16, v51
	v_and_b32_e32 v51, 0xffff0000, v51
	v_pk_fma_f32 v[38:39], v[38:39], v[46:47], v[48:49]
	v_pk_fma_f32 v[36:37], v[36:37], v[44:45], v[54:55]
	v_pk_fma_f32 v[48:49], v[34:35], v[42:43], v[50:51]
	v_pk_fma_f32 v[34:35], v[32:33], v[40:41], v[64:65]
	v_cvt_pk_bf16_f32 v32, v36, v37
	v_cvt_pk_bf16_f32 v33, v38, v39
	v_cvt_pk_bf16_f32 v34, v34, v35
	v_cvt_pk_bf16_f32 v35, v48, v49
	v_lshl_add_u64 v[36:37], v[160:161], 0, s[2:3]
	global_store_dwordx4 v[52:53], v[32:35], off offset:256
	v_lshl_add_u64 v[38:39], s[4:5], 0, v[36:37]
	global_load_dwordx4 v[32:35], v[38:39], off
	s_mov_b64 s[2:3], 0xb0000
	s_waitcnt vmcnt(0) lgkmcnt(0)
	v_lshlrev_b32_e32 v48, 16, v32
	v_and_b32_e32 v49, 0xffff0000, v32
	v_lshlrev_b32_e32 v32, 16, v33
	v_and_b32_e32 v33, 0xffff0000, v33
	v_lshlrev_b32_e32 v50, 16, v34
	v_and_b32_e32 v51, 0xffff0000, v34
	v_lshlrev_b32_e32 v34, 16, v35
	v_and_b32_e32 v35, 0xffff0000, v35
	v_pk_fma_f32 v[30:31], v[30:31], v[62:63], v[32:33]
	v_pk_fma_f32 v[28:29], v[28:29], v[60:61], v[48:49]
	v_pk_fma_f32 v[32:33], v[26:27], v[58:59], v[34:35]
	v_pk_fma_f32 v[26:27], v[24:25], v[56:57], v[50:51]
	v_cvt_pk_bf16_f32 v24, v28, v29
	v_cvt_pk_bf16_f32 v25, v30, v31
	v_cvt_pk_bf16_f32 v26, v26, v27
	v_cvt_pk_bf16_f32 v27, v32, v33
	v_lshl_add_u64 v[28:29], s[42:43], 0, v[36:37]
	global_store_dwordx4 v[28:29], v[24:27], off
	global_load_dwordx4 v[24:27], v[38:39], off offset:256
	s_waitcnt vmcnt(0) lgkmcnt(0)
	v_lshlrev_b32_e32 v30, 16, v24
	v_and_b32_e32 v31, 0xffff0000, v24
	v_lshlrev_b32_e32 v24, 16, v25
	v_and_b32_e32 v25, 0xffff0000, v25
	v_lshlrev_b32_e32 v32, 16, v26
	v_and_b32_e32 v33, 0xffff0000, v26
	v_lshlrev_b32_e32 v26, 16, v27
	v_and_b32_e32 v27, 0xffff0000, v27
	v_pk_fma_f32 v[22:23], v[22:23], v[46:47], v[24:25]
	v_pk_fma_f32 v[20:21], v[20:21], v[44:45], v[30:31]
	v_pk_fma_f32 v[24:25], v[18:19], v[42:43], v[26:27]
	v_pk_fma_f32 v[18:19], v[16:17], v[40:41], v[32:33]
	v_cvt_pk_bf16_f32 v16, v20, v21
	v_cvt_pk_bf16_f32 v17, v22, v23
	v_cvt_pk_bf16_f32 v18, v18, v19
	v_cvt_pk_bf16_f32 v19, v24, v25
	v_lshl_add_u64 v[20:21], v[160:161], 0, s[2:3]
	global_store_dwordx4 v[28:29], v[16:19], off offset:256
	v_lshl_add_u64 v[22:23], s[4:5], 0, v[20:21]
	global_load_dwordx4 v[16:19], v[22:23], off
	s_mov_b32 s2, s37
	s_waitcnt vmcnt(0) lgkmcnt(0)
	v_lshlrev_b32_e32 v24, 16, v16
	v_and_b32_e32 v25, 0xffff0000, v16
	v_lshlrev_b32_e32 v16, 16, v17
	v_and_b32_e32 v17, 0xffff0000, v17
	v_lshlrev_b32_e32 v26, 16, v18
	v_and_b32_e32 v27, 0xffff0000, v18
	v_lshlrev_b32_e32 v18, 16, v19
	v_and_b32_e32 v19, 0xffff0000, v19
	v_pk_fma_f32 v[14:15], v[14:15], v[62:63], v[16:17]
	v_pk_fma_f32 v[12:13], v[12:13], v[60:61], v[24:25]
	v_pk_fma_f32 v[16:17], v[10:11], v[58:59], v[18:19]
	v_pk_fma_f32 v[10:11], v[8:9], v[56:57], v[26:27]
	v_cvt_pk_bf16_f32 v8, v12, v13
	v_cvt_pk_bf16_f32 v9, v14, v15
	v_cvt_pk_bf16_f32 v10, v10, v11
	v_cvt_pk_bf16_f32 v11, v16, v17
	v_lshl_add_u64 v[12:13], s[42:43], 0, v[20:21]
	global_store_dwordx4 v[12:13], v[8:11], off
	global_load_dwordx4 v[8:11], v[22:23], off offset:256
	s_waitcnt vmcnt(0) lgkmcnt(0)
	v_lshlrev_b32_e32 v14, 16, v8
	v_and_b32_e32 v15, 0xffff0000, v8
	v_lshlrev_b32_e32 v8, 16, v9
	v_and_b32_e32 v9, 0xffff0000, v9
	v_lshlrev_b32_e32 v16, 16, v10
	v_and_b32_e32 v17, 0xffff0000, v10
	v_lshlrev_b32_e32 v10, 16, v11
	v_and_b32_e32 v11, 0xffff0000, v11
	v_pk_fma_f32 v[6:7], v[6:7], v[46:47], v[8:9]
	v_pk_fma_f32 v[4:5], v[4:5], v[44:45], v[14:15]
	v_pk_fma_f32 v[8:9], v[2:3], v[42:43], v[10:11]
	v_pk_fma_f32 v[2:3], v[0:1], v[40:41], v[16:17]
	v_cvt_pk_bf16_f32 v0, v4, v5
	v_cvt_pk_bf16_f32 v1, v6, v7
	v_cvt_pk_bf16_f32 v2, v2, v3
	v_cvt_pk_bf16_f32 v3, v8, v9
	global_store_dwordx4 v[12:13], v[0:3], off offset:256
	s_cbranch_vccz .LBB1_2336
	s_waitcnt vmcnt(0)
	s_cmpk_gt_u32 s17, 0xff
	s_cbranch_scc1 .LBB1_2343
	s_barrier

; DI unsigned char* wsp(const Params& p) { const unsigned long long a = (unsigned long long)p.ws; unsigned lo = __builtin_amdgcn_readfirstlane((unsigned)a), hi = __builtin_amdgcn_readfirstlane((unsigned)(a >> 32)); asm volatile("" : "+s"(lo), "+s"(hi)); return (unsigned char*)(((unsigned long long)hi << 32) | lo); }
; DI float bflo(unsigned w) { return __uint_as_float(w << 16); }
; DI float bfhi(unsigned w) { return __uint_as_float(w & 0xffff0000u); }
; DI float wave_sum(float v) { for (int o = 32; o; o >>= 1) v += __shfl_xor(v, o); return v; }
; template <bool BF> DI void norm_phase(const Params& p, const void* x, const float* gain) {
;     unsigned char* const ws = wsp(p);
;     const int bid = opaque_bid();
;     bf16_t* H = (bf16_t*)(ws + OFF_H);
;     const int tid = opaque_tid(), wid = tid >> 6, lane = tid & 63;
;     const int step = gridDim.x * 8;
;     for (int t = bid * 8 + wid; t < T; t += 2 * step) {
;         const int t2 = (t + step < T) ? t + step : t;
;         f32x4 v[2][8];
; #pragma unroll
;         for (int q = 0; q < 2; ++q) {
;             const int tt = q ? t2 : t;
; #pragma unroll
;             for (int i = 0; i < 4; ++i) {
;                 const size_t e = (size_t)tt * D + (i * 64 + lane) * 8;
;                 if constexpr (BF) { const u32x4 w = *(const u32x4*)((const bf16_t*)x + e);
;                     v[q][2 * i] = (f32x4){bflo(w[0]), bfhi(w[0]), bflo(w[1]), bfhi(w[1])}; v[q][2 * i + 1] = (f32x4){bflo(w[2]), bfhi(w[2]), bflo(w[3]), bfhi(w[3])}; }
;                 else { v[q][2 * i] = *(const f32x4*)((const float*)x + e); v[q][2 * i + 1] = *(const f32x4*)((const float*)x + e + 4); }
;             }
;         }
;         float ss[2] = {0.f, 0.f};
; #pragma unroll
;         for (int q = 0; q < 2; ++q)
; #pragma unroll
;             for (int i = 0; i < 8; ++i) ss[q] += v[q][i][0] * v[q][i][0] + v[q][i][1] * v[q][i][1] + v[q][i][2] * v[q][i][2] + v[q][i][3] * v[q][i][3];
;         ss[0] = wave_sum(ss[0]); ss[1] = wave_sum(ss[1]);
; #pragma unroll
;         for (int q = 0; q < 2; ++q) {
;             const int tt = q ? t2 : t;
;             const float rs = rsqrtf(ss[q] * (1.0f / D) + EPS);
; #pragma unroll
;             for (int i = 0; i < 4; ++i) { const int c = (i * 64 + lane) * 8;
;                 const f32x4 g0 = *(const f32x4*)(gain + c), g1 = *(const f32x4*)(gain + c + 4);
.LBB1_2408:
	s_or_b64 exec, exec, s[4:5]
	s_waitcnt lgkmcnt(0)
	s_barrier
	s_load_dwordx2 s[6:7], s[0:1], 0x88
	s_mov_b32 s2, s61
	s_waitcnt vmcnt(0)
	v_mov_b32_e32 v0, v197
	s_waitcnt lgkmcnt(0)
	s_mov_b32 s8, s6
	s_mov_b32 s9, s7
	s_mov_b32 s3, s7
	s_nop 0
	v_ashrrev_i32_e32 v1, 6, v0
	v_lshl_add_u32 v14, s2, 3, v1
	s_movk_i32 s2, 0x4000
	v_cmp_gt_i32_e32 vcc, s2, v14
	s_and_saveexec_b64 s[4:5], vcc
	s_cbranch_execz .LBB1_2411
	v_lshlrev_b32_e32 v0, 3, v0
	v_mbcnt_hi_u32_b32 v1, -1, v228
	v_and_b32_e32 v8, 0x1f8, v0
	v_and_b32_e32 v0, 64, v1
	v_add_u32_e32 v0, 64, v0
	v_xor_b32_e32 v2, 32, v1
	v_cmp_lt_i32_e32 vcc, v2, v0
	s_load_dwordx2 s[10:11], s[0:1], 0x18
	v_lshlrev_b32_e32 v10, 2, v8
	v_cndmask_b32_e32 v2, v1, v2, vcc
	v_lshlrev_b32_e32 v13, 2, v2
	v_xor_b32_e32 v2, 16, v1
	v_cmp_lt_i32_e32 vcc, v2, v0
	s_waitcnt lgkmcnt(0)
	s_add_u32 s10, s10, 0x6000
	s_addc_u32 s11, s11, 0
	v_cndmask_b32_e32 v2, v1, v2, vcc
	v_lshlrev_b32_e32 v82, 2, v2
	v_xor_b32_e32 v2, 8, v1
	v_cmp_lt_i32_e32 vcc, v2, v0
	v_mov_b32_e32 v11, 0
	v_or_b32_e32 v4, 0x1000, v10
	v_cndmask_b32_e32 v2, v1, v2, vcc
	v_lshlrev_b32_e32 v83, 2, v2
	v_xor_b32_e32 v2, 4, v1
	v_cmp_lt_i32_e32 vcc, v2, v0
	s_mov_b32 s7, s3
	v_mov_b32_e32 v3, v11
	v_cndmask_b32_e32 v2, v1, v2, vcc
	v_lshlrev_b32_e32 v84, 2, v2
	v_xor_b32_e32 v2, 2, v1
	v_cmp_lt_i32_e32 vcc, v2, v0
	v_mov_b32_e32 v5, v11
	v_lshl_add_u64 v[4:5], s[10:11], 0, v[4:5]
	v_cndmask_b32_e32 v2, v1, v2, vcc
	v_lshlrev_b32_e32 v85, 2, v2
	v_xor_b32_e32 v2, 1, v1
	v_cmp_lt_i32_e32 vcc, v2, v0
	v_mov_b32_e32 v12, 0x358637bd
	s_mov_b32 s3, 0x800000
	v_cndmask_b32_e32 v0, v1, v2, vcc
	v_lshlrev_b32_e32 v86, 2, v0
	v_lshl_add_u64 v[0:1], s[10:11], 0, v[10:11]
	v_or_b32_e32 v2, 0x800, v10
	v_or_b32_e32 v10, 0x1800, v10
	v_lshl_add_u64 v[6:7], s[10:11], 0, v[10:11]
	v_lshlrev_b32_e32 v10, 1, v8
	v_lshl_add_u64 v[8:9], s[8:9], 0, v[10:11]
	s_mov_b64 s[8:9], 0x4c614000
	v_lshl_add_u64 v[10:11], s[6:7], 0, v[10:11]
	s_mov_b64 s[6:7], 0x13310000
	v_lshl_add_u64 v[2:3], s[10:11], 0, v[2:3]
	v_lshl_add_u64 v[8:9], v[8:9], 0, s[8:9]
	v_lshl_add_u64 v[10:11], v[10:11], 0, s[6:7]
	s_mov_b64 s[6:7], 0
	s_mov_b32 s8, 0x3a000000
	s_movk_i32 s9, 0x3fff
	global_load_dwordx4 v[124:127], v[0:1], off offset:16
	global_load_dwordx4 v[128:131], v[0:1], off
	global_load_dwordx4 v[132:135], v[2:3], off
	global_load_dwordx4 v[136:139], v[2:3], off offset:16
	global_load_dwordx4 v[140:143], v[4:5], off
	global_load_dwordx4 v[144:147], v[4:5], off offset:16
	global_load_dwordx4 v[148:151], v[6:7], off
	global_load_dwordx4 v[152:155], v[6:7], off offset:16
